# loop-edge rotation: K-loop induction/pointer updates and exit compare moved ahead of the closing s_barrier in 10 GEMM K-loops
# baseline (speedup 1.0000x reference)
.LBB0_258:
	s_add_u32 s46, s44, 0xfff80080
	s_addc_u32 s47, s45, -1
	s_add_i32 s59, 0, 0x10000
	s_cmp_eq_u32 s58, 28
	s_cselect_b32 s49, s19, s47
	s_cselect_b32 s48, s20, s46
	s_cselect_b32 s47, s21, s57
	s_cselect_b32 s46, s23, s29
	s_add_i32 s62, 0, 0x14000
	v_add_u32_e32 v46, s59, v163
	v_add_u32_e32 v160, s62, v163
	ds_read_b128 v[26:29], v46
	ds_read_b128 v[30:33], v46 offset:1024
	ds_read_b128 v[42:45], v46 offset:2048
	ds_read_b128 v[46:49], v46 offset:3072
	ds_read_b128 v[166:169], v160
	ds_read_b128 v[178:181], v160 offset:1024
	ds_read_b128 v[182:185], v160 offset:2048
	ds_read_b128 v[186:189], v160 offset:3072
	v_lshl_add_u64 v[160:161], s[44:45], 0, v[156:157]
	s_add_i32 m0, s43, 0xc000
	ds_read_b128 v[190:193], v165
	ds_read_b128 v[194:197], v165 offset:1024
	ds_read_b128 v[204:207], v165 offset:2048
	ds_read_b128 v[208:211], v165 offset:3072
	ds_read_b128 v[212:215], v165 offset:4096
	ds_read_b128 v[216:219], v165 offset:5120
	ds_read_b128 v[220:223], v165 offset:6144
	ds_read_b128 v[224:227], v165 offset:7168
	global_load_lds_dwordx4 v[160:161], off
	v_lshl_add_u64 v[160:161], s[44:45], 0, v[158:159]
	s_add_i32 m0, s43, 0xe000
	s_nop 0
	global_load_lds_dwordx4 v[160:161], off
	s_waitcnt vmcnt(8)
	s_waitcnt lgkmcnt(0)
	s_barrier
	s_setprio 1
	s_waitcnt lgkmcnt(0)
	v_mfma_f32_16x16x32_bf16 v[146:149], v[26:29], v[190:193], v[146:149]
	v_mfma_f32_16x16x32_bf16 v[142:145], v[42:45], v[190:193], v[142:145]
	v_mfma_f32_16x16x32_bf16 v[130:133], v[26:29], v[204:207], v[130:133]
	v_mfma_f32_16x16x32_bf16 v[126:129], v[42:45], v[204:207], v[126:129]
	v_mfma_f32_16x16x32_bf16 v[114:117], v[26:29], v[212:215], v[114:117]
	v_mfma_f32_16x16x32_bf16 v[110:113], v[42:45], v[212:215], v[110:113]
	v_mfma_f32_16x16x32_bf16 v[94:97], v[26:29], v[220:223], v[94:97]
	v_mfma_f32_16x16x32_bf16 v[90:93], v[42:45], v[220:223], v[90:93]
	v_mfma_f32_16x16x32_bf16 v[146:149], v[30:33], v[194:197], v[146:149]
	v_mfma_f32_16x16x32_bf16 v[142:145], v[46:49], v[194:197], v[142:145]
	v_mfma_f32_16x16x32_bf16 v[130:133], v[30:33], v[208:211], v[130:133]
	v_mfma_f32_16x16x32_bf16 v[126:129], v[46:49], v[208:211], v[126:129]
	v_mfma_f32_16x16x32_bf16 v[114:117], v[30:33], v[216:219], v[114:117]
	v_mfma_f32_16x16x32_bf16 v[110:113], v[46:49], v[216:219], v[110:113]
	v_mfma_f32_16x16x32_bf16 v[94:97], v[30:33], v[224:227], v[94:97]
	v_mfma_f32_16x16x32_bf16 v[90:93], v[46:49], v[224:227], v[90:93]
	s_setprio 0
	s_setprio 1
	v_mfma_f32_16x16x32_bf16 v[138:141], v[166:169], v[190:193], v[138:141]
	v_mfma_f32_16x16x32_bf16 v[134:137], v[182:185], v[190:193], v[134:137]
	v_mfma_f32_16x16x32_bf16 v[122:125], v[166:169], v[204:207], v[122:125]
	v_mfma_f32_16x16x32_bf16 v[118:121], v[182:185], v[204:207], v[118:121]
	v_mfma_f32_16x16x32_bf16 v[106:109], v[166:169], v[212:215], v[106:109]
	v_mfma_f32_16x16x32_bf16 v[102:105], v[182:185], v[212:215], v[102:105]
	v_mfma_f32_16x16x32_bf16 v[86:89], v[166:169], v[220:223], v[86:89]
	v_mfma_f32_16x16x32_bf16 v[82:85], v[182:185], v[220:223], v[82:85]
	v_mfma_f32_16x16x32_bf16 v[138:141], v[178:181], v[194:197], v[138:141]
	v_mfma_f32_16x16x32_bf16 v[134:137], v[186:189], v[194:197], v[134:137]
	v_mfma_f32_16x16x32_bf16 v[122:125], v[178:181], v[208:211], v[122:125]
	v_mfma_f32_16x16x32_bf16 v[118:121], v[186:189], v[208:211], v[118:121]
	v_mfma_f32_16x16x32_bf16 v[106:109], v[178:181], v[216:219], v[106:109]
	v_mfma_f32_16x16x32_bf16 v[102:105], v[186:189], v[216:219], v[102:105]
	v_mfma_f32_16x16x32_bf16 v[86:89], v[178:181], v[224:227], v[86:89]
	v_mfma_f32_16x16x32_bf16 v[82:85], v[186:189], v[224:227], v[82:85]
	s_setprio 0
	s_barrier
	s_add_i32 s59, s59, s50
	v_lshl_add_u64 v[160:161], s[46:47], 0, v[172:173]
	s_mov_b32 m0, s59
	ds_read_b128 v[190:193], v165 offset:16384
	ds_read_b128 v[194:197], v165 offset:17408
	ds_read_b128 v[204:207], v165 offset:18432
	ds_read_b128 v[208:211], v165 offset:19456
	ds_read_b128 v[212:215], v165 offset:20480
	ds_read_b128 v[216:219], v165 offset:21504
	ds_read_b128 v[220:223], v165 offset:22528
	ds_read_b128 v[224:227], v165 offset:23552
	global_load_lds_dwordx4 v[160:161], off
	s_add_i32 m0, s59, 0x2000
	s_add_u32 s60, s46, 0x80000
	v_lshl_add_u64 v[198:199], s[46:47], 0, v[154:155]
	s_addc_u32 s61, s47, 0
	s_add_i32 s59, s62, s50
	global_load_lds_dwordx4 v[198:199], off
	v_lshl_add_u64 v[228:229], s[60:61], 0, v[172:173]
	s_mov_b32 m0, s59
	v_lshl_add_u64 v[230:231], s[48:49], 0, v[152:153]
	global_load_lds_dwordx4 v[228:229], off
	v_lshl_add_u64 v[228:229], s[60:61], 0, v[154:155]
	s_add_i32 m0, s59, 0x2000
	s_nop 0
	global_load_lds_dwordx4 v[228:229], off
	v_lshl_add_u64 v[228:229], s[48:49], 0, v[150:151]
	s_mov_b32 m0, s43
	s_nop 0
	global_load_lds_dwordx4 v[228:229], off
	s_mov_b32 m0, s51
	s_nop 0
	global_load_lds_dwordx4 v[230:231], off
	s_waitcnt vmcnt(8)
	s_waitcnt lgkmcnt(0)
	s_barrier
	s_setprio 1
	s_waitcnt lgkmcnt(0)
	v_mfma_f32_16x16x32_bf16 v[78:81], v[26:29], v[190:193], v[78:81]
	v_mfma_f32_16x16x32_bf16 v[74:77], v[42:45], v[190:193], v[74:77]
	v_mfma_f32_16x16x32_bf16 v[62:65], v[26:29], v[204:207], v[62:65]
	v_mfma_f32_16x16x32_bf16 v[58:61], v[42:45], v[204:207], v[58:61]
	v_mfma_f32_16x16x32_bf16 v[38:41], v[26:29], v[212:215], v[38:41]
	v_mfma_f32_16x16x32_bf16 v[34:37], v[42:45], v[212:215], v[34:37]
	v_mfma_f32_16x16x32_bf16 v[14:17], v[26:29], v[220:223], v[14:17]
	v_mfma_f32_16x16x32_bf16 v[10:13], v[42:45], v[220:223], v[10:13]
	v_mfma_f32_16x16x32_bf16 v[78:81], v[30:33], v[194:197], v[78:81]
	v_mfma_f32_16x16x32_bf16 v[74:77], v[46:49], v[194:197], v[74:77]
	v_mfma_f32_16x16x32_bf16 v[62:65], v[30:33], v[208:211], v[62:65]
	v_mfma_f32_16x16x32_bf16 v[58:61], v[46:49], v[208:211], v[58:61]
	v_mfma_f32_16x16x32_bf16 v[38:41], v[30:33], v[216:219], v[38:41]
	v_mfma_f32_16x16x32_bf16 v[34:37], v[46:49], v[216:219], v[34:37]
	v_mfma_f32_16x16x32_bf16 v[14:17], v[30:33], v[224:227], v[14:17]
	v_mfma_f32_16x16x32_bf16 v[10:13], v[46:49], v[224:227], v[10:13]
	s_setprio 0
	s_setprio 1
	v_mfma_f32_16x16x32_bf16 v[22:25], v[166:169], v[212:215], v[22:25]
	v_mfma_f32_16x16x32_bf16 v[18:21], v[182:185], v[212:215], v[18:21]
	v_mfma_f32_16x16x32_bf16 v[6:9], v[166:169], v[220:223], v[6:9]
	v_mfma_f32_16x16x32_bf16 v[2:5], v[182:185], v[220:223], v[2:5]
	v_mfma_f32_16x16x32_bf16 v[26:29], v[166:169], v[190:193], v[70:73]
	v_mfma_f32_16x16x32_bf16 v[30:33], v[182:185], v[190:193], v[66:69]
	v_mfma_f32_16x16x32_bf16 v[42:45], v[166:169], v[204:207], v[54:57]
	v_mfma_f32_16x16x32_bf16 v[46:49], v[182:185], v[204:207], v[50:53]
	v_mfma_f32_16x16x32_bf16 v[22:25], v[178:181], v[216:219], v[22:25]
	v_mfma_f32_16x16x32_bf16 v[18:21], v[186:189], v[216:219], v[18:21]
	v_mfma_f32_16x16x32_bf16 v[6:9], v[178:181], v[224:227], v[6:9]
	v_mfma_f32_16x16x32_bf16 v[2:5], v[186:189], v[224:227], v[2:5]
	v_mfma_f32_16x16x32_bf16 v[26:29], v[178:181], v[194:197], v[26:29]
	v_mfma_f32_16x16x32_bf16 v[30:33], v[186:189], v[194:197], v[30:33]
	v_mfma_f32_16x16x32_bf16 v[42:45], v[178:181], v[208:211], v[42:45]
	v_mfma_f32_16x16x32_bf16 v[46:49], v[186:189], v[208:211], v[46:49]
	s_setprio 0
	s_barrier
	s_add_i32 s59, 0, 0x18000
	s_add_i32 s60, 0, 0x1c000
	v_add_u32_e32 v70, s59, v163
	v_add_u32_e32 v186, s60, v163
	ds_read_b128 v[50:53], v70
	ds_read_b128 v[54:57], v70 offset:1024
	ds_read_b128 v[66:69], v70 offset:2048
	ds_read_b128 v[70:73], v70 offset:3072
	ds_read_b128 v[166:169], v186
	ds_read_b128 v[178:181], v186 offset:1024
	ds_read_b128 v[182:185], v186 offset:2048
	ds_read_b128 v[186:189], v186 offset:3072
	s_add_u32 s48, s48, 0x80000
	s_addc_u32 s49, s49, 0
	s_mov_b32 m0, s52
	v_lshl_add_u64 v[232:233], s[48:49], 0, v[150:151]
	ds_read_b128 v[190:193], v165 offset:32768
	ds_read_b128 v[194:197], v165 offset:33792
	ds_read_b128 v[204:207], v165 offset:34816
	ds_read_b128 v[208:211], v165 offset:35840
	ds_read_b128 v[212:215], v165 offset:36864
	ds_read_b128 v[216:219], v165 offset:37888
	ds_read_b128 v[220:223], v165 offset:38912
	ds_read_b128 v[224:227], v165 offset:39936
	global_load_lds_dwordx4 v[232:233], off
	v_lshl_add_u64 v[232:233], s[48:49], 0, v[152:153]
	s_mov_b32 m0, s53
	s_nop 0
	global_load_lds_dwordx4 v[232:233], off
	s_waitcnt vmcnt(8)
	s_waitcnt lgkmcnt(0)
	s_barrier
	s_setprio 1
	s_waitcnt lgkmcnt(0)
	v_mfma_f32_16x16x32_bf16 v[146:149], v[50:53], v[190:193], v[146:149]
	v_mfma_f32_16x16x32_bf16 v[142:145], v[66:69], v[190:193], v[142:145]
	v_mfma_f32_16x16x32_bf16 v[130:133], v[50:53], v[204:207], v[130:133]
	v_mfma_f32_16x16x32_bf16 v[126:129], v[66:69], v[204:207], v[126:129]
	v_mfma_f32_16x16x32_bf16 v[114:117], v[50:53], v[212:215], v[114:117]
	v_mfma_f32_16x16x32_bf16 v[110:113], v[66:69], v[212:215], v[110:113]
	v_mfma_f32_16x16x32_bf16 v[94:97], v[50:53], v[220:223], v[94:97]
	v_mfma_f32_16x16x32_bf16 v[90:93], v[66:69], v[220:223], v[90:93]
	v_mfma_f32_16x16x32_bf16 v[146:149], v[54:57], v[194:197], v[146:149]
	v_mfma_f32_16x16x32_bf16 v[142:145], v[70:73], v[194:197], v[142:145]
	v_mfma_f32_16x16x32_bf16 v[130:133], v[54:57], v[208:211], v[130:133]
	v_mfma_f32_16x16x32_bf16 v[126:129], v[70:73], v[208:211], v[126:129]
	v_mfma_f32_16x16x32_bf16 v[114:117], v[54:57], v[216:219], v[114:117]
	v_mfma_f32_16x16x32_bf16 v[110:113], v[70:73], v[216:219], v[110:113]
	v_mfma_f32_16x16x32_bf16 v[94:97], v[54:57], v[224:227], v[94:97]
	v_mfma_f32_16x16x32_bf16 v[90:93], v[70:73], v[224:227], v[90:93]
	s_setprio 0
	s_setprio 1
	v_mfma_f32_16x16x32_bf16 v[138:141], v[166:169], v[190:193], v[138:141]
	v_mfma_f32_16x16x32_bf16 v[134:137], v[182:185], v[190:193], v[134:137]
	v_mfma_f32_16x16x32_bf16 v[122:125], v[166:169], v[204:207], v[122:125]
	v_mfma_f32_16x16x32_bf16 v[118:121], v[182:185], v[204:207], v[118:121]
	v_mfma_f32_16x16x32_bf16 v[106:109], v[166:169], v[212:215], v[106:109]
	v_mfma_f32_16x16x32_bf16 v[102:105], v[182:185], v[212:215], v[102:105]
	v_mfma_f32_16x16x32_bf16 v[86:89], v[166:169], v[220:223], v[86:89]
	v_mfma_f32_16x16x32_bf16 v[82:85], v[182:185], v[220:223], v[82:85]
	v_mfma_f32_16x16x32_bf16 v[138:141], v[178:181], v[194:197], v[138:141]
	v_mfma_f32_16x16x32_bf16 v[134:137], v[186:189], v[194:197], v[134:137]
	v_mfma_f32_16x16x32_bf16 v[122:125], v[178:181], v[208:211], v[122:125]
	v_mfma_f32_16x16x32_bf16 v[118:121], v[186:189], v[208:211], v[118:121]
	v_mfma_f32_16x16x32_bf16 v[106:109], v[178:181], v[216:219], v[106:109]
	v_mfma_f32_16x16x32_bf16 v[102:105], v[186:189], v[216:219], v[102:105]
	v_mfma_f32_16x16x32_bf16 v[86:89], v[178:181], v[224:227], v[86:89]
	v_mfma_f32_16x16x32_bf16 v[82:85], v[186:189], v[224:227], v[82:85]
	s_setprio 0
	s_barrier
	s_add_i32 s48, s59, s50
	v_lshl_add_u64 v[160:161], v[160:161], 0, s[84:85]
	s_mov_b32 m0, s48
	ds_read_b128 v[190:193], v165 offset:49152
	ds_read_b128 v[194:197], v165 offset:50176
	ds_read_b128 v[204:207], v165 offset:51200
	ds_read_b128 v[208:211], v165 offset:52224
	ds_read_b128 v[212:215], v165 offset:53248
	ds_read_b128 v[216:219], v165 offset:54272
	ds_read_b128 v[220:223], v165 offset:55296
	ds_read_b128 v[224:227], v165 offset:56320
	global_load_lds_dwordx4 v[160:161], off
	s_add_i32 m0, s48, 0x2000
	s_add_u32 s46, s46, 0x80080
	v_lshl_add_u64 v[160:161], v[198:199], 0, s[84:85]
	s_addc_u32 s47, s47, 0
	s_add_i32 s48, s60, s50
	global_load_lds_dwordx4 v[160:161], off
	v_lshl_add_u64 v[160:161], s[46:47], 0, v[172:173]
	s_mov_b32 m0, s48
	s_nop 0
	global_load_lds_dwordx4 v[160:161], off
	v_lshl_add_u64 v[160:161], s[46:47], 0, v[154:155]
	s_add_i32 m0, s48, 0x2000
	s_nop 0
	global_load_lds_dwordx4 v[160:161], off
	v_lshl_add_u64 v[160:161], v[228:229], 0, s[84:85]
	s_mov_b32 m0, s54
	s_nop 0
	global_load_lds_dwordx4 v[160:161], off
	v_lshl_add_u64 v[160:161], v[230:231], 0, s[84:85]
	s_mov_b32 m0, s55
	s_nop 0
	global_load_lds_dwordx4 v[160:161], off
	s_waitcnt vmcnt(8)
	s_waitcnt lgkmcnt(0)
	s_barrier
	s_setprio 1
	s_waitcnt lgkmcnt(0)
	v_mfma_f32_16x16x32_bf16 v[78:81], v[50:53], v[190:193], v[78:81]
	v_mfma_f32_16x16x32_bf16 v[74:77], v[66:69], v[190:193], v[74:77]
	v_mfma_f32_16x16x32_bf16 v[62:65], v[50:53], v[204:207], v[62:65]
	v_mfma_f32_16x16x32_bf16 v[58:61], v[66:69], v[204:207], v[58:61]
	v_mfma_f32_16x16x32_bf16 v[38:41], v[50:53], v[212:215], v[38:41]
	v_mfma_f32_16x16x32_bf16 v[34:37], v[66:69], v[212:215], v[34:37]
	v_mfma_f32_16x16x32_bf16 v[14:17], v[50:53], v[220:223], v[14:17]
	v_mfma_f32_16x16x32_bf16 v[10:13], v[66:69], v[220:223], v[10:13]
	v_mfma_f32_16x16x32_bf16 v[78:81], v[54:57], v[194:197], v[78:81]
	v_mfma_f32_16x16x32_bf16 v[74:77], v[70:73], v[194:197], v[74:77]
	v_mfma_f32_16x16x32_bf16 v[62:65], v[54:57], v[208:211], v[62:65]
	v_mfma_f32_16x16x32_bf16 v[58:61], v[70:73], v[208:211], v[58:61]
	v_mfma_f32_16x16x32_bf16 v[38:41], v[54:57], v[216:219], v[38:41]
	v_mfma_f32_16x16x32_bf16 v[34:37], v[70:73], v[216:219], v[34:37]
	v_mfma_f32_16x16x32_bf16 v[14:17], v[54:57], v[224:227], v[14:17]
	v_mfma_f32_16x16x32_bf16 v[10:13], v[70:73], v[224:227], v[10:13]
	s_setprio 0
	s_setprio 1
	v_mfma_f32_16x16x32_bf16 v[26:29], v[166:169], v[190:193], v[26:29]
	v_mfma_f32_16x16x32_bf16 v[70:73], v[178:181], v[194:197], v[26:29]
	v_mfma_f32_16x16x32_bf16 v[26:29], v[182:185], v[190:193], v[30:33]
	v_mfma_f32_16x16x32_bf16 v[66:69], v[186:189], v[194:197], v[26:29]
	v_mfma_f32_16x16x32_bf16 v[26:29], v[166:169], v[204:207], v[42:45]
	v_mfma_f32_16x16x32_bf16 v[54:57], v[178:181], v[208:211], v[26:29]
	v_mfma_f32_16x16x32_bf16 v[26:29], v[182:185], v[204:207], v[46:49]
	v_mfma_f32_16x16x32_bf16 v[22:25], v[166:169], v[212:215], v[22:25]
	v_mfma_f32_16x16x32_bf16 v[18:21], v[182:185], v[212:215], v[18:21]
	v_mfma_f32_16x16x32_bf16 v[6:9], v[166:169], v[220:223], v[6:9]
	v_mfma_f32_16x16x32_bf16 v[2:5], v[182:185], v[220:223], v[2:5]
	v_mfma_f32_16x16x32_bf16 v[50:53], v[186:189], v[208:211], v[26:29]
	v_mfma_f32_16x16x32_bf16 v[22:25], v[178:181], v[216:219], v[22:25]
	v_mfma_f32_16x16x32_bf16 v[18:21], v[186:189], v[216:219], v[18:21]
	v_mfma_f32_16x16x32_bf16 v[6:9], v[178:181], v[224:227], v[6:9]
	v_mfma_f32_16x16x32_bf16 v[2:5], v[186:189], v[224:227], v[2:5]
	s_add_i32 s58, s58, 2
	s_add_u32 s44, s44, 0x100
	s_addc_u32 s45, s45, 0
	s_add_u32 s29, s29, 0x100
	s_addc_u32 s57, s57, 0
	s_cmp_gt_u32 s58, 29
	s_setprio 0
	s_barrier
	s_cbranch_scc0 .LBB0_258
	s_and_b64 vcc, exec, s[14:15]
	s_cbranch_vccz .LBB0_261
	s_barrier

.LBB0_893:
	s_add_u32 s14, s48, s10
	s_addc_u32 s15, s49, s11
	s_add_u32 s14, s14, 0x29800100
	s_addc_u32 s15, s15, 0
	s_add_u32 s42, s50, s10
	s_addc_u32 s43, s63, s11
	s_add_i32 s44, 0, 0x10000
	s_cmpk_eq_i32 s10, 0x700
	s_cselect_b32 s19, s47, s15
	s_cselect_b32 s18, s46, s14
	s_cselect_b32 s15, s1, s43
	s_cselect_b32 s14, s0, s42
	s_add_i32 s45, 0, 0x14000
	v_add_u32_e32 v160, s44, v146
	v_add_u32_e32 v168, s45, v146
	ds_read_b128 v[148:151], v160
	ds_read_b128 v[152:155], v160 offset:1024
	ds_read_b128 v[156:159], v160 offset:2048
	ds_read_b128 v[160:163], v160 offset:3072
	ds_read_b128 v[164:167], v168
	ds_read_b128 v[178:181], v168 offset:1024
	ds_read_b128 v[182:185], v168 offset:2048
	ds_read_b128 v[186:189], v168 offset:3072
	v_lshl_add_u64 v[168:169], v[140:141], 0, s[10:11]
	s_add_i32 m0, s28, 0xc000
	ds_read_b128 v[190:193], v147
	ds_read_b128 v[194:197], v147 offset:1024
	ds_read_b128 v[204:207], v147 offset:2048
	ds_read_b128 v[208:211], v147 offset:3072
	ds_read_b128 v[212:215], v147 offset:4096
	ds_read_b128 v[216:219], v147 offset:5120
	ds_read_b128 v[220:223], v147 offset:6144
	ds_read_b128 v[224:227], v147 offset:7168
	global_load_lds_dwordx4 v[168:169], off
	v_lshl_add_u64 v[168:169], v[142:143], 0, s[10:11]
	s_add_i32 m0, s28, 0xe000
	s_nop 0
	global_load_lds_dwordx4 v[168:169], off
	s_waitcnt vmcnt(8)
	s_waitcnt lgkmcnt(0)
	s_barrier
	s_setprio 1
	s_waitcnt lgkmcnt(0)
	v_mfma_f32_16x16x32_bf16 v[130:133], v[148:151], v[190:193], v[130:133]
	v_mfma_f32_16x16x32_bf16 v[126:129], v[156:159], v[190:193], v[126:129]
	v_mfma_f32_16x16x32_bf16 v[114:117], v[148:151], v[204:207], v[114:117]
	v_mfma_f32_16x16x32_bf16 v[110:113], v[156:159], v[204:207], v[110:113]
	v_mfma_f32_16x16x32_bf16 v[94:97], v[148:151], v[212:215], v[94:97]
	v_mfma_f32_16x16x32_bf16 v[90:93], v[156:159], v[212:215], v[90:93]
	v_mfma_f32_16x16x32_bf16 v[78:81], v[148:151], v[220:223], v[78:81]
	v_mfma_f32_16x16x32_bf16 v[74:77], v[156:159], v[220:223], v[74:77]
	v_mfma_f32_16x16x32_bf16 v[130:133], v[152:155], v[194:197], v[130:133]
	v_mfma_f32_16x16x32_bf16 v[126:129], v[160:163], v[194:197], v[126:129]
	v_mfma_f32_16x16x32_bf16 v[114:117], v[152:155], v[208:211], v[114:117]
	v_mfma_f32_16x16x32_bf16 v[110:113], v[160:163], v[208:211], v[110:113]
	v_mfma_f32_16x16x32_bf16 v[94:97], v[152:155], v[216:219], v[94:97]
	v_mfma_f32_16x16x32_bf16 v[90:93], v[160:163], v[216:219], v[90:93]
	v_mfma_f32_16x16x32_bf16 v[78:81], v[152:155], v[224:227], v[78:81]
	v_mfma_f32_16x16x32_bf16 v[74:77], v[160:163], v[224:227], v[74:77]
	s_setprio 0
	s_setprio 1
	v_mfma_f32_16x16x32_bf16 v[122:125], v[164:167], v[190:193], v[122:125]
	v_mfma_f32_16x16x32_bf16 v[118:121], v[182:185], v[190:193], v[118:121]
	v_mfma_f32_16x16x32_bf16 v[106:109], v[164:167], v[204:207], v[106:109]
	v_mfma_f32_16x16x32_bf16 v[102:105], v[182:185], v[204:207], v[102:105]
	v_mfma_f32_16x16x32_bf16 v[86:89], v[164:167], v[212:215], v[86:89]
	v_mfma_f32_16x16x32_bf16 v[82:85], v[182:185], v[212:215], v[82:85]
	v_mfma_f32_16x16x32_bf16 v[70:73], v[164:167], v[220:223], v[70:73]
	v_mfma_f32_16x16x32_bf16 v[66:69], v[182:185], v[220:223], v[66:69]
	v_mfma_f32_16x16x32_bf16 v[122:125], v[178:181], v[194:197], v[122:125]
	v_mfma_f32_16x16x32_bf16 v[118:121], v[186:189], v[194:197], v[118:121]
	v_mfma_f32_16x16x32_bf16 v[106:109], v[178:181], v[208:211], v[106:109]
	v_mfma_f32_16x16x32_bf16 v[102:105], v[186:189], v[208:211], v[102:105]
	v_mfma_f32_16x16x32_bf16 v[86:89], v[178:181], v[216:219], v[86:89]
	v_mfma_f32_16x16x32_bf16 v[82:85], v[186:189], v[216:219], v[82:85]
	v_mfma_f32_16x16x32_bf16 v[70:73], v[178:181], v[224:227], v[70:73]
	v_mfma_f32_16x16x32_bf16 v[66:69], v[186:189], v[224:227], v[66:69]
	s_setprio 0
	s_barrier
	s_add_i32 s42, s44, s23
	v_lshl_add_u64 v[168:169], s[14:15], 0, v[172:173]
	s_mov_b32 m0, s42
	ds_read_b128 v[190:193], v147 offset:16384
	ds_read_b128 v[194:197], v147 offset:17408
	ds_read_b128 v[204:207], v147 offset:18432
	ds_read_b128 v[208:211], v147 offset:19456
	ds_read_b128 v[212:215], v147 offset:20480
	ds_read_b128 v[216:219], v147 offset:21504
	ds_read_b128 v[220:223], v147 offset:22528
	ds_read_b128 v[224:227], v147 offset:23552
	global_load_lds_dwordx4 v[168:169], off
	s_add_i32 m0, s42, 0x2000
	s_add_u32 s42, s14, 0x40000
	v_lshl_add_u64 v[198:199], s[14:15], 0, v[134:135]
	s_addc_u32 s43, s15, 0
	s_add_i32 s44, s45, s23
	global_load_lds_dwordx4 v[198:199], off
	v_lshl_add_u64 v[228:229], s[42:43], 0, v[172:173]
	s_mov_b32 m0, s44
	v_lshl_add_u64 v[230:231], s[18:19], 0, v[136:137]
	global_load_lds_dwordx4 v[228:229], off
	v_lshl_add_u64 v[228:229], s[42:43], 0, v[134:135]
	s_add_i32 m0, s44, 0x2000
	s_nop 0
	global_load_lds_dwordx4 v[228:229], off
	v_lshl_add_u64 v[228:229], s[18:19], 0, v[138:139]
	s_mov_b32 m0, s28
	s_nop 0
	global_load_lds_dwordx4 v[228:229], off
	s_mov_b32 m0, s29
	s_nop 0
	global_load_lds_dwordx4 v[230:231], off
	s_waitcnt vmcnt(8)
	s_waitcnt lgkmcnt(0)
	s_barrier
	s_setprio 1
	s_waitcnt lgkmcnt(0)
	v_mfma_f32_16x16x32_bf16 v[62:65], v[148:151], v[190:193], v[62:65]
	v_mfma_f32_16x16x32_bf16 v[58:61], v[156:159], v[190:193], v[58:61]
	v_mfma_f32_16x16x32_bf16 v[46:49], v[148:151], v[204:207], v[46:49]
	v_mfma_f32_16x16x32_bf16 v[42:45], v[156:159], v[204:207], v[42:45]
	v_mfma_f32_16x16x32_bf16 v[30:33], v[148:151], v[212:215], v[30:33]
	v_mfma_f32_16x16x32_bf16 v[26:29], v[156:159], v[212:215], v[26:29]
	v_mfma_f32_16x16x32_bf16 v[14:17], v[148:151], v[220:223], v[14:17]
	v_mfma_f32_16x16x32_bf16 v[10:13], v[156:159], v[220:223], v[10:13]
	v_mfma_f32_16x16x32_bf16 v[62:65], v[152:155], v[194:197], v[62:65]
	v_mfma_f32_16x16x32_bf16 v[58:61], v[160:163], v[194:197], v[58:61]
	v_mfma_f32_16x16x32_bf16 v[46:49], v[152:155], v[208:211], v[46:49]
	v_mfma_f32_16x16x32_bf16 v[42:45], v[160:163], v[208:211], v[42:45]
	v_mfma_f32_16x16x32_bf16 v[30:33], v[152:155], v[216:219], v[30:33]
	v_mfma_f32_16x16x32_bf16 v[26:29], v[160:163], v[216:219], v[26:29]
	v_mfma_f32_16x16x32_bf16 v[14:17], v[152:155], v[224:227], v[14:17]
	v_mfma_f32_16x16x32_bf16 v[10:13], v[160:163], v[224:227], v[10:13]
	s_setprio 0
	s_setprio 1
	v_mfma_f32_16x16x32_bf16 v[54:57], v[164:167], v[190:193], v[54:57]
	v_mfma_f32_16x16x32_bf16 v[50:53], v[182:185], v[190:193], v[50:53]
	v_mfma_f32_16x16x32_bf16 v[38:41], v[164:167], v[204:207], v[38:41]
	v_mfma_f32_16x16x32_bf16 v[34:37], v[182:185], v[204:207], v[34:37]
	v_mfma_f32_16x16x32_bf16 v[22:25], v[164:167], v[212:215], v[22:25]
	v_mfma_f32_16x16x32_bf16 v[18:21], v[182:185], v[212:215], v[18:21]
	v_mfma_f32_16x16x32_bf16 v[6:9], v[164:167], v[220:223], v[6:9]
	v_mfma_f32_16x16x32_bf16 v[2:5], v[182:185], v[220:223], v[2:5]
	v_mfma_f32_16x16x32_bf16 v[54:57], v[178:181], v[194:197], v[54:57]
	v_mfma_f32_16x16x32_bf16 v[50:53], v[186:189], v[194:197], v[50:53]
	v_mfma_f32_16x16x32_bf16 v[38:41], v[178:181], v[208:211], v[38:41]
	v_mfma_f32_16x16x32_bf16 v[34:37], v[186:189], v[208:211], v[34:37]
	v_mfma_f32_16x16x32_bf16 v[22:25], v[178:181], v[216:219], v[22:25]
	v_mfma_f32_16x16x32_bf16 v[18:21], v[186:189], v[216:219], v[18:21]
	v_mfma_f32_16x16x32_bf16 v[6:9], v[178:181], v[224:227], v[6:9]
	v_mfma_f32_16x16x32_bf16 v[2:5], v[186:189], v[224:227], v[2:5]
	s_setprio 0
	s_barrier
	s_add_i32 s42, 0, 0x18000
	s_add_i32 s43, 0, 0x1c000
	v_add_u32_e32 v160, s42, v146
	v_add_u32_e32 v186, s43, v146
	ds_read_b128 v[148:151], v160
	ds_read_b128 v[152:155], v160 offset:1024
	ds_read_b128 v[156:159], v160 offset:2048
	ds_read_b128 v[160:163], v160 offset:3072
	ds_read_b128 v[164:167], v186
	ds_read_b128 v[178:181], v186 offset:1024
	ds_read_b128 v[182:185], v186 offset:2048
	ds_read_b128 v[186:189], v186 offset:3072
	s_add_u32 s18, s18, 0x40000
	s_addc_u32 s19, s19, 0
	s_mov_b32 m0, s34
	v_lshl_add_u64 v[232:233], s[18:19], 0, v[138:139]
	ds_read_b128 v[190:193], v147 offset:32768
	ds_read_b128 v[194:197], v147 offset:33792
	ds_read_b128 v[204:207], v147 offset:34816
	ds_read_b128 v[208:211], v147 offset:35840
	ds_read_b128 v[212:215], v147 offset:36864
	ds_read_b128 v[216:219], v147 offset:37888
	ds_read_b128 v[220:223], v147 offset:38912
	ds_read_b128 v[224:227], v147 offset:39936
	global_load_lds_dwordx4 v[232:233], off
	v_lshl_add_u64 v[232:233], s[18:19], 0, v[136:137]
	s_mov_b32 m0, s35
	s_nop 0
	global_load_lds_dwordx4 v[232:233], off
	s_waitcnt vmcnt(8)
	s_waitcnt lgkmcnt(0)
	s_barrier
	s_setprio 1
	s_waitcnt lgkmcnt(0)
	v_mfma_f32_16x16x32_bf16 v[130:133], v[148:151], v[190:193], v[130:133]
	v_mfma_f32_16x16x32_bf16 v[126:129], v[156:159], v[190:193], v[126:129]
	v_mfma_f32_16x16x32_bf16 v[114:117], v[148:151], v[204:207], v[114:117]
	v_mfma_f32_16x16x32_bf16 v[110:113], v[156:159], v[204:207], v[110:113]
	v_mfma_f32_16x16x32_bf16 v[94:97], v[148:151], v[212:215], v[94:97]
	v_mfma_f32_16x16x32_bf16 v[90:93], v[156:159], v[212:215], v[90:93]
	v_mfma_f32_16x16x32_bf16 v[78:81], v[148:151], v[220:223], v[78:81]
	v_mfma_f32_16x16x32_bf16 v[74:77], v[156:159], v[220:223], v[74:77]
	v_mfma_f32_16x16x32_bf16 v[130:133], v[152:155], v[194:197], v[130:133]
	v_mfma_f32_16x16x32_bf16 v[126:129], v[160:163], v[194:197], v[126:129]
	v_mfma_f32_16x16x32_bf16 v[114:117], v[152:155], v[208:211], v[114:117]
	v_mfma_f32_16x16x32_bf16 v[110:113], v[160:163], v[208:211], v[110:113]
	v_mfma_f32_16x16x32_bf16 v[94:97], v[152:155], v[216:219], v[94:97]
	v_mfma_f32_16x16x32_bf16 v[90:93], v[160:163], v[216:219], v[90:93]
	v_mfma_f32_16x16x32_bf16 v[78:81], v[152:155], v[224:227], v[78:81]
	v_mfma_f32_16x16x32_bf16 v[74:77], v[160:163], v[224:227], v[74:77]
	s_setprio 0
	s_setprio 1
	v_mfma_f32_16x16x32_bf16 v[122:125], v[164:167], v[190:193], v[122:125]
	v_mfma_f32_16x16x32_bf16 v[118:121], v[182:185], v[190:193], v[118:121]
	v_mfma_f32_16x16x32_bf16 v[106:109], v[164:167], v[204:207], v[106:109]
	v_mfma_f32_16x16x32_bf16 v[102:105], v[182:185], v[204:207], v[102:105]
	v_mfma_f32_16x16x32_bf16 v[86:89], v[164:167], v[212:215], v[86:89]
	v_mfma_f32_16x16x32_bf16 v[82:85], v[182:185], v[212:215], v[82:85]
	v_mfma_f32_16x16x32_bf16 v[70:73], v[164:167], v[220:223], v[70:73]
	v_mfma_f32_16x16x32_bf16 v[66:69], v[182:185], v[220:223], v[66:69]
	v_mfma_f32_16x16x32_bf16 v[122:125], v[178:181], v[194:197], v[122:125]
	v_mfma_f32_16x16x32_bf16 v[118:121], v[186:189], v[194:197], v[118:121]
	v_mfma_f32_16x16x32_bf16 v[106:109], v[178:181], v[208:211], v[106:109]
	v_mfma_f32_16x16x32_bf16 v[102:105], v[186:189], v[208:211], v[102:105]
	v_mfma_f32_16x16x32_bf16 v[86:89], v[178:181], v[216:219], v[86:89]
	v_mfma_f32_16x16x32_bf16 v[82:85], v[186:189], v[216:219], v[82:85]
	v_mfma_f32_16x16x32_bf16 v[70:73], v[178:181], v[224:227], v[70:73]
	v_mfma_f32_16x16x32_bf16 v[66:69], v[186:189], v[224:227], v[66:69]
	s_setprio 0
	s_barrier
	s_add_i32 s18, s42, s23
	v_lshl_add_u64 v[168:169], v[168:169], 0, s[84:85]
	s_mov_b32 m0, s18
	ds_read_b128 v[190:193], v147 offset:49152
	ds_read_b128 v[194:197], v147 offset:50176
	ds_read_b128 v[204:207], v147 offset:51200
	ds_read_b128 v[208:211], v147 offset:52224
	ds_read_b128 v[212:215], v147 offset:53248
	ds_read_b128 v[216:219], v147 offset:54272
	ds_read_b128 v[220:223], v147 offset:55296
	ds_read_b128 v[224:227], v147 offset:56320
	global_load_lds_dwordx4 v[168:169], off
	s_add_i32 m0, s18, 0x2000
	s_add_u32 s14, s14, 0x40080
	v_lshl_add_u64 v[168:169], v[198:199], 0, s[84:85]
	s_addc_u32 s15, s15, 0
	s_add_i32 s18, s43, s23
	global_load_lds_dwordx4 v[168:169], off
	v_lshl_add_u64 v[168:169], s[14:15], 0, v[172:173]
	s_mov_b32 m0, s18
	s_nop 0
	global_load_lds_dwordx4 v[168:169], off
	v_lshl_add_u64 v[168:169], s[14:15], 0, v[134:135]
	s_add_i32 m0, s18, 0x2000
	s_nop 0
	global_load_lds_dwordx4 v[168:169], off
	v_lshl_add_u64 v[168:169], v[228:229], 0, s[84:85]
	s_mov_b32 m0, s39
	s_nop 0
	global_load_lds_dwordx4 v[168:169], off
	v_lshl_add_u64 v[168:169], v[230:231], 0, s[84:85]
	s_mov_b32 m0, s40
	s_nop 0
	global_load_lds_dwordx4 v[168:169], off
	s_waitcnt vmcnt(8)
	s_waitcnt lgkmcnt(0)
	s_barrier
	s_setprio 1
	s_waitcnt lgkmcnt(0)
	v_mfma_f32_16x16x32_bf16 v[62:65], v[148:151], v[190:193], v[62:65]
	v_mfma_f32_16x16x32_bf16 v[58:61], v[156:159], v[190:193], v[58:61]
	v_mfma_f32_16x16x32_bf16 v[46:49], v[148:151], v[204:207], v[46:49]
	v_mfma_f32_16x16x32_bf16 v[42:45], v[156:159], v[204:207], v[42:45]
	v_mfma_f32_16x16x32_bf16 v[30:33], v[148:151], v[212:215], v[30:33]
	v_mfma_f32_16x16x32_bf16 v[26:29], v[156:159], v[212:215], v[26:29]
	v_mfma_f32_16x16x32_bf16 v[14:17], v[148:151], v[220:223], v[14:17]
	v_mfma_f32_16x16x32_bf16 v[10:13], v[156:159], v[220:223], v[10:13]
	v_mfma_f32_16x16x32_bf16 v[62:65], v[152:155], v[194:197], v[62:65]
	v_mfma_f32_16x16x32_bf16 v[58:61], v[160:163], v[194:197], v[58:61]
	v_mfma_f32_16x16x32_bf16 v[46:49], v[152:155], v[208:211], v[46:49]
	v_mfma_f32_16x16x32_bf16 v[42:45], v[160:163], v[208:211], v[42:45]
	v_mfma_f32_16x16x32_bf16 v[30:33], v[152:155], v[216:219], v[30:33]
	v_mfma_f32_16x16x32_bf16 v[26:29], v[160:163], v[216:219], v[26:29]
	v_mfma_f32_16x16x32_bf16 v[14:17], v[152:155], v[224:227], v[14:17]
	v_mfma_f32_16x16x32_bf16 v[10:13], v[160:163], v[224:227], v[10:13]
	s_setprio 0
	s_setprio 1
	v_mfma_f32_16x16x32_bf16 v[54:57], v[164:167], v[190:193], v[54:57]
	v_mfma_f32_16x16x32_bf16 v[50:53], v[182:185], v[190:193], v[50:53]
	v_mfma_f32_16x16x32_bf16 v[38:41], v[164:167], v[204:207], v[38:41]
	v_mfma_f32_16x16x32_bf16 v[34:37], v[182:185], v[204:207], v[34:37]
	v_mfma_f32_16x16x32_bf16 v[22:25], v[164:167], v[212:215], v[22:25]
	v_mfma_f32_16x16x32_bf16 v[18:21], v[182:185], v[212:215], v[18:21]
	v_mfma_f32_16x16x32_bf16 v[6:9], v[164:167], v[220:223], v[6:9]
	v_mfma_f32_16x16x32_bf16 v[2:5], v[182:185], v[220:223], v[2:5]
	v_mfma_f32_16x16x32_bf16 v[54:57], v[178:181], v[194:197], v[54:57]
	v_mfma_f32_16x16x32_bf16 v[50:53], v[186:189], v[194:197], v[50:53]
	v_mfma_f32_16x16x32_bf16 v[38:41], v[178:181], v[208:211], v[38:41]
	v_mfma_f32_16x16x32_bf16 v[34:37], v[186:189], v[208:211], v[34:37]
	v_mfma_f32_16x16x32_bf16 v[22:25], v[178:181], v[216:219], v[22:25]
	v_mfma_f32_16x16x32_bf16 v[18:21], v[186:189], v[216:219], v[18:21]
	v_mfma_f32_16x16x32_bf16 v[6:9], v[178:181], v[224:227], v[6:9]
	v_mfma_f32_16x16x32_bf16 v[2:5], v[186:189], v[224:227], v[2:5]
	s_add_i32 s41, s41, 2
	s_add_u32 s10, s10, 0x100
	s_addc_u32 s11, s11, 0
	s_cmp_gt_u32 s41, 13
	s_setprio 0
	s_barrier
	s_cbranch_scc0 .LBB0_893
	s_cmpk_lt_u32 s22, 0x100
	s_cbranch_scc0 .LBB0_896
	s_barrier

.LBB0_927:
	s_add_u32 s28, s22, 0xfffc0080
	s_addc_u32 s29, s23, -1
	s_add_i32 s57, 0, 0x10000
	s_cmp_eq_u32 s56, 12
	s_cselect_b32 s35, s52, s29
	s_cselect_b32 s34, s53, s28
	v_add_u32_e32 v156, s57, v159
	s_cselect_b32 s29, s54, s21
	s_cselect_b32 s28, s55, s20
	s_add_i32 s60, 0, 0x14000
	ds_read_b128 v[134:137], v156
	ds_read_b128 v[148:151], v156 offset:1024
	ds_read_b128 v[152:155], v156 offset:2048
	ds_read_b128 v[162:165], v156 offset:3072
	v_add_u32_e32 v156, s60, v159
	ds_read_b128 v[166:169], v156
	ds_read_b128 v[178:181], v156 offset:1024
	ds_read_b128 v[182:185], v156 offset:2048
	ds_read_b128 v[186:189], v156 offset:3072
	v_lshl_add_u64 v[156:157], s[22:23], 0, v[144:145]
	s_add_i32 m0, s43, 0xc000
	ds_read_b128 v[190:193], v161
	ds_read_b128 v[194:197], v161 offset:1024
	ds_read_b128 v[204:207], v161 offset:2048
	ds_read_b128 v[208:211], v161 offset:3072
	ds_read_b128 v[212:215], v161 offset:4096
	ds_read_b128 v[216:219], v161 offset:5120
	ds_read_b128 v[220:223], v161 offset:6144
	ds_read_b128 v[224:227], v161 offset:7168
	global_load_lds_dwordx4 v[156:157], off
	v_lshl_add_u64 v[156:157], s[22:23], 0, v[146:147]
	s_add_i32 m0, s43, 0xe000
	s_nop 0
	global_load_lds_dwordx4 v[156:157], off
	s_waitcnt vmcnt(8)
	s_waitcnt lgkmcnt(0)
	s_barrier
	s_setprio 1
	s_waitcnt lgkmcnt(0)
	v_mfma_f32_16x16x32_bf16 v[130:133], v[134:137], v[190:193], v[130:133]
	v_mfma_f32_16x16x32_bf16 v[126:129], v[152:155], v[190:193], v[126:129]
	v_mfma_f32_16x16x32_bf16 v[122:125], v[134:137], v[204:207], v[122:125]
	v_mfma_f32_16x16x32_bf16 v[114:117], v[152:155], v[204:207], v[114:117]
	v_mfma_f32_16x16x32_bf16 v[94:97], v[134:137], v[212:215], v[94:97]
	v_mfma_f32_16x16x32_bf16 v[90:93], v[152:155], v[212:215], v[90:93]
	v_mfma_f32_16x16x32_bf16 v[78:81], v[134:137], v[220:223], v[78:81]
	v_mfma_f32_16x16x32_bf16 v[74:77], v[152:155], v[220:223], v[74:77]
	v_mfma_f32_16x16x32_bf16 v[130:133], v[148:151], v[194:197], v[130:133]
	v_mfma_f32_16x16x32_bf16 v[126:129], v[162:165], v[194:197], v[126:129]
	v_mfma_f32_16x16x32_bf16 v[122:125], v[148:151], v[208:211], v[122:125]
	v_mfma_f32_16x16x32_bf16 v[114:117], v[162:165], v[208:211], v[114:117]
	v_mfma_f32_16x16x32_bf16 v[94:97], v[148:151], v[216:219], v[94:97]
	v_mfma_f32_16x16x32_bf16 v[90:93], v[162:165], v[216:219], v[90:93]
	v_mfma_f32_16x16x32_bf16 v[78:81], v[148:151], v[224:227], v[78:81]
	v_mfma_f32_16x16x32_bf16 v[74:77], v[162:165], v[224:227], v[74:77]
	s_setprio 0
	s_setprio 1
	v_mfma_f32_16x16x32_bf16 v[118:121], v[166:169], v[190:193], v[118:121]
	v_mfma_f32_16x16x32_bf16 v[110:113], v[182:185], v[190:193], v[110:113]
	v_mfma_f32_16x16x32_bf16 v[106:109], v[166:169], v[204:207], v[106:109]
	v_mfma_f32_16x16x32_bf16 v[102:105], v[182:185], v[204:207], v[102:105]
	v_mfma_f32_16x16x32_bf16 v[86:89], v[166:169], v[212:215], v[86:89]
	v_mfma_f32_16x16x32_bf16 v[82:85], v[182:185], v[212:215], v[82:85]
	v_mfma_f32_16x16x32_bf16 v[70:73], v[166:169], v[220:223], v[70:73]
	v_mfma_f32_16x16x32_bf16 v[66:69], v[182:185], v[220:223], v[66:69]
	v_mfma_f32_16x16x32_bf16 v[118:121], v[178:181], v[194:197], v[118:121]
	v_mfma_f32_16x16x32_bf16 v[110:113], v[186:189], v[194:197], v[110:113]
	v_mfma_f32_16x16x32_bf16 v[106:109], v[178:181], v[208:211], v[106:109]
	v_mfma_f32_16x16x32_bf16 v[102:105], v[186:189], v[208:211], v[102:105]
	v_mfma_f32_16x16x32_bf16 v[86:89], v[178:181], v[216:219], v[86:89]
	v_mfma_f32_16x16x32_bf16 v[82:85], v[186:189], v[216:219], v[82:85]
	v_mfma_f32_16x16x32_bf16 v[70:73], v[178:181], v[224:227], v[70:73]
	v_mfma_f32_16x16x32_bf16 v[66:69], v[186:189], v[224:227], v[66:69]
	s_setprio 0
	s_barrier
	s_add_i32 s57, s57, s40
	v_lshl_add_u64 v[156:157], s[28:29], 0, v[172:173]
	s_mov_b32 m0, s57
	ds_read_b128 v[190:193], v161 offset:16384
	ds_read_b128 v[194:197], v161 offset:17408
	ds_read_b128 v[204:207], v161 offset:18432
	ds_read_b128 v[208:211], v161 offset:19456
	ds_read_b128 v[212:215], v161 offset:20480
	ds_read_b128 v[216:219], v161 offset:21504
	ds_read_b128 v[220:223], v161 offset:22528
	ds_read_b128 v[224:227], v161 offset:23552
	global_load_lds_dwordx4 v[156:157], off
	s_add_i32 m0, s57, 0x2000
	s_add_u32 s58, s28, 0x40000
	v_lshl_add_u64 v[198:199], s[28:29], 0, v[138:139]
	s_addc_u32 s59, s29, 0
	s_add_i32 s57, s60, s40
	global_load_lds_dwordx4 v[198:199], off
	v_lshl_add_u64 v[228:229], s[58:59], 0, v[172:173]
	s_mov_b32 m0, s57
	v_lshl_add_u64 v[230:231], s[34:35], 0, v[140:141]
	global_load_lds_dwordx4 v[228:229], off
	v_lshl_add_u64 v[228:229], s[58:59], 0, v[138:139]
	s_add_i32 m0, s57, 0x2000
	s_nop 0
	global_load_lds_dwordx4 v[228:229], off
	v_lshl_add_u64 v[228:229], s[34:35], 0, v[142:143]
	s_mov_b32 m0, s43
	s_nop 0
	global_load_lds_dwordx4 v[228:229], off
	s_mov_b32 m0, s44
	s_nop 0
	global_load_lds_dwordx4 v[230:231], off
	s_waitcnt vmcnt(8)
	s_waitcnt lgkmcnt(0)
	s_barrier
	s_setprio 1
	s_waitcnt lgkmcnt(0)
	v_mfma_f32_16x16x32_bf16 v[62:65], v[134:137], v[190:193], v[62:65]
	v_mfma_f32_16x16x32_bf16 v[58:61], v[152:155], v[190:193], v[58:61]
	v_mfma_f32_16x16x32_bf16 v[46:49], v[134:137], v[204:207], v[46:49]
	v_mfma_f32_16x16x32_bf16 v[42:45], v[152:155], v[204:207], v[42:45]
	v_mfma_f32_16x16x32_bf16 v[30:33], v[134:137], v[212:215], v[30:33]
	v_mfma_f32_16x16x32_bf16 v[26:29], v[152:155], v[212:215], v[26:29]
	v_mfma_f32_16x16x32_bf16 v[14:17], v[134:137], v[220:223], v[14:17]
	v_mfma_f32_16x16x32_bf16 v[10:13], v[152:155], v[220:223], v[10:13]
	v_mfma_f32_16x16x32_bf16 v[62:65], v[148:151], v[194:197], v[62:65]
	v_mfma_f32_16x16x32_bf16 v[58:61], v[162:165], v[194:197], v[58:61]
	v_mfma_f32_16x16x32_bf16 v[46:49], v[148:151], v[208:211], v[46:49]
	v_mfma_f32_16x16x32_bf16 v[42:45], v[162:165], v[208:211], v[42:45]
	v_mfma_f32_16x16x32_bf16 v[30:33], v[148:151], v[216:219], v[30:33]
	v_mfma_f32_16x16x32_bf16 v[26:29], v[162:165], v[216:219], v[26:29]
	v_mfma_f32_16x16x32_bf16 v[14:17], v[148:151], v[224:227], v[14:17]
	v_mfma_f32_16x16x32_bf16 v[10:13], v[162:165], v[224:227], v[10:13]
	s_setprio 0
	s_setprio 1
	v_mfma_f32_16x16x32_bf16 v[54:57], v[166:169], v[190:193], v[54:57]
	v_mfma_f32_16x16x32_bf16 v[50:53], v[182:185], v[190:193], v[50:53]
	v_mfma_f32_16x16x32_bf16 v[38:41], v[166:169], v[204:207], v[38:41]
	v_mfma_f32_16x16x32_bf16 v[34:37], v[182:185], v[204:207], v[34:37]
	v_mfma_f32_16x16x32_bf16 v[22:25], v[166:169], v[212:215], v[22:25]
	v_mfma_f32_16x16x32_bf16 v[18:21], v[182:185], v[212:215], v[18:21]
	v_mfma_f32_16x16x32_bf16 v[6:9], v[166:169], v[220:223], v[6:9]
	v_mfma_f32_16x16x32_bf16 v[2:5], v[182:185], v[220:223], v[2:5]
	v_mfma_f32_16x16x32_bf16 v[54:57], v[178:181], v[194:197], v[54:57]
	v_mfma_f32_16x16x32_bf16 v[50:53], v[186:189], v[194:197], v[50:53]
	v_mfma_f32_16x16x32_bf16 v[38:41], v[178:181], v[208:211], v[38:41]
	v_mfma_f32_16x16x32_bf16 v[34:37], v[186:189], v[208:211], v[34:37]
	v_mfma_f32_16x16x32_bf16 v[22:25], v[178:181], v[216:219], v[22:25]
	v_mfma_f32_16x16x32_bf16 v[18:21], v[186:189], v[216:219], v[18:21]
	v_mfma_f32_16x16x32_bf16 v[6:9], v[178:181], v[224:227], v[6:9]
	v_mfma_f32_16x16x32_bf16 v[2:5], v[186:189], v[224:227], v[2:5]
	s_setprio 0
	s_barrier
	s_add_i32 s57, 0, 0x18000
	s_add_i32 s58, 0, 0x1c000
	v_add_u32_e32 v162, s57, v159
	v_add_u32_e32 v186, s58, v159
	ds_read_b128 v[134:137], v162
	ds_read_b128 v[148:151], v162 offset:1024
	ds_read_b128 v[152:155], v162 offset:2048
	ds_read_b128 v[162:165], v162 offset:3072
	ds_read_b128 v[166:169], v186
	ds_read_b128 v[178:181], v186 offset:1024
	ds_read_b128 v[182:185], v186 offset:2048
	ds_read_b128 v[186:189], v186 offset:3072
	s_add_u32 s34, s34, 0x40000
	s_addc_u32 s35, s35, 0
	s_mov_b32 m0, s45
	v_lshl_add_u64 v[232:233], s[34:35], 0, v[142:143]
	ds_read_b128 v[190:193], v161 offset:32768
	ds_read_b128 v[194:197], v161 offset:33792
	ds_read_b128 v[204:207], v161 offset:34816
	ds_read_b128 v[208:211], v161 offset:35840
	ds_read_b128 v[212:215], v161 offset:36864
	ds_read_b128 v[216:219], v161 offset:37888
	ds_read_b128 v[220:223], v161 offset:38912
	ds_read_b128 v[224:227], v161 offset:39936
	global_load_lds_dwordx4 v[232:233], off
	v_lshl_add_u64 v[232:233], s[34:35], 0, v[140:141]
	s_mov_b32 m0, s46
	s_nop 0
	global_load_lds_dwordx4 v[232:233], off
	s_waitcnt vmcnt(8)
	s_waitcnt lgkmcnt(0)
	s_barrier
	s_setprio 1
	s_waitcnt lgkmcnt(0)
	v_mfma_f32_16x16x32_bf16 v[130:133], v[134:137], v[190:193], v[130:133]
	v_mfma_f32_16x16x32_bf16 v[126:129], v[152:155], v[190:193], v[126:129]
	v_mfma_f32_16x16x32_bf16 v[122:125], v[134:137], v[204:207], v[122:125]
	v_mfma_f32_16x16x32_bf16 v[114:117], v[152:155], v[204:207], v[114:117]
	v_mfma_f32_16x16x32_bf16 v[94:97], v[134:137], v[212:215], v[94:97]
	v_mfma_f32_16x16x32_bf16 v[90:93], v[152:155], v[212:215], v[90:93]
	v_mfma_f32_16x16x32_bf16 v[78:81], v[134:137], v[220:223], v[78:81]
	v_mfma_f32_16x16x32_bf16 v[74:77], v[152:155], v[220:223], v[74:77]
	v_mfma_f32_16x16x32_bf16 v[130:133], v[148:151], v[194:197], v[130:133]
	v_mfma_f32_16x16x32_bf16 v[126:129], v[162:165], v[194:197], v[126:129]
	v_mfma_f32_16x16x32_bf16 v[122:125], v[148:151], v[208:211], v[122:125]
	v_mfma_f32_16x16x32_bf16 v[114:117], v[162:165], v[208:211], v[114:117]
	v_mfma_f32_16x16x32_bf16 v[94:97], v[148:151], v[216:219], v[94:97]
	v_mfma_f32_16x16x32_bf16 v[90:93], v[162:165], v[216:219], v[90:93]
	v_mfma_f32_16x16x32_bf16 v[78:81], v[148:151], v[224:227], v[78:81]
	v_mfma_f32_16x16x32_bf16 v[74:77], v[162:165], v[224:227], v[74:77]
	s_setprio 0
	s_setprio 1
	v_mfma_f32_16x16x32_bf16 v[118:121], v[166:169], v[190:193], v[118:121]
	v_mfma_f32_16x16x32_bf16 v[110:113], v[182:185], v[190:193], v[110:113]
	v_mfma_f32_16x16x32_bf16 v[106:109], v[166:169], v[204:207], v[106:109]
	v_mfma_f32_16x16x32_bf16 v[102:105], v[182:185], v[204:207], v[102:105]
	v_mfma_f32_16x16x32_bf16 v[86:89], v[166:169], v[212:215], v[86:89]
	v_mfma_f32_16x16x32_bf16 v[82:85], v[182:185], v[212:215], v[82:85]
	v_mfma_f32_16x16x32_bf16 v[70:73], v[166:169], v[220:223], v[70:73]
	v_mfma_f32_16x16x32_bf16 v[66:69], v[182:185], v[220:223], v[66:69]
	v_mfma_f32_16x16x32_bf16 v[118:121], v[178:181], v[194:197], v[118:121]
	v_mfma_f32_16x16x32_bf16 v[110:113], v[186:189], v[194:197], v[110:113]
	v_mfma_f32_16x16x32_bf16 v[106:109], v[178:181], v[208:211], v[106:109]
	v_mfma_f32_16x16x32_bf16 v[102:105], v[186:189], v[208:211], v[102:105]
	v_mfma_f32_16x16x32_bf16 v[86:89], v[178:181], v[216:219], v[86:89]
	v_mfma_f32_16x16x32_bf16 v[82:85], v[186:189], v[216:219], v[82:85]
	v_mfma_f32_16x16x32_bf16 v[70:73], v[178:181], v[224:227], v[70:73]
	v_mfma_f32_16x16x32_bf16 v[66:69], v[186:189], v[224:227], v[66:69]
	s_setprio 0
	s_barrier
	s_add_i32 s34, s57, s40
	v_lshl_add_u64 v[156:157], v[156:157], 0, s[84:85]
	s_mov_b32 m0, s34
	ds_read_b128 v[190:193], v161 offset:49152
	ds_read_b128 v[194:197], v161 offset:50176
	ds_read_b128 v[204:207], v161 offset:51200
	ds_read_b128 v[208:211], v161 offset:52224
	ds_read_b128 v[212:215], v161 offset:53248
	ds_read_b128 v[216:219], v161 offset:54272
	ds_read_b128 v[220:223], v161 offset:55296
	ds_read_b128 v[224:227], v161 offset:56320
	global_load_lds_dwordx4 v[156:157], off
	s_add_i32 m0, s34, 0x2000
	s_add_u32 s28, s28, 0x40080
	v_lshl_add_u64 v[156:157], v[198:199], 0, s[84:85]
	s_addc_u32 s29, s29, 0
	s_add_i32 s34, s58, s40
	global_load_lds_dwordx4 v[156:157], off
	v_lshl_add_u64 v[156:157], s[28:29], 0, v[172:173]
	s_mov_b32 m0, s34
	s_nop 0
	global_load_lds_dwordx4 v[156:157], off
	v_lshl_add_u64 v[156:157], s[28:29], 0, v[138:139]
	s_add_i32 m0, s34, 0x2000
	s_nop 0
	global_load_lds_dwordx4 v[156:157], off
	v_lshl_add_u64 v[156:157], v[228:229], 0, s[84:85]
	s_mov_b32 m0, s47
	s_nop 0
	global_load_lds_dwordx4 v[156:157], off
	v_lshl_add_u64 v[156:157], v[230:231], 0, s[84:85]
	s_mov_b32 m0, s48
	s_nop 0
	global_load_lds_dwordx4 v[156:157], off
	s_waitcnt vmcnt(8)
	s_waitcnt lgkmcnt(0)
	s_barrier
	s_setprio 1
	s_waitcnt lgkmcnt(0)
	v_mfma_f32_16x16x32_bf16 v[62:65], v[134:137], v[190:193], v[62:65]
	v_mfma_f32_16x16x32_bf16 v[58:61], v[152:155], v[190:193], v[58:61]
	v_mfma_f32_16x16x32_bf16 v[46:49], v[134:137], v[204:207], v[46:49]
	v_mfma_f32_16x16x32_bf16 v[42:45], v[152:155], v[204:207], v[42:45]
	v_mfma_f32_16x16x32_bf16 v[30:33], v[134:137], v[212:215], v[30:33]
	v_mfma_f32_16x16x32_bf16 v[26:29], v[152:155], v[212:215], v[26:29]
	v_mfma_f32_16x16x32_bf16 v[14:17], v[134:137], v[220:223], v[14:17]
	v_mfma_f32_16x16x32_bf16 v[10:13], v[152:155], v[220:223], v[10:13]
	v_mfma_f32_16x16x32_bf16 v[62:65], v[148:151], v[194:197], v[62:65]
	v_mfma_f32_16x16x32_bf16 v[58:61], v[162:165], v[194:197], v[58:61]
	v_mfma_f32_16x16x32_bf16 v[46:49], v[148:151], v[208:211], v[46:49]
	v_mfma_f32_16x16x32_bf16 v[42:45], v[162:165], v[208:211], v[42:45]
	v_mfma_f32_16x16x32_bf16 v[30:33], v[148:151], v[216:219], v[30:33]
	v_mfma_f32_16x16x32_bf16 v[26:29], v[162:165], v[216:219], v[26:29]
	v_mfma_f32_16x16x32_bf16 v[14:17], v[148:151], v[224:227], v[14:17]
	v_mfma_f32_16x16x32_bf16 v[10:13], v[162:165], v[224:227], v[10:13]
	s_setprio 0
	s_setprio 1
	v_mfma_f32_16x16x32_bf16 v[54:57], v[166:169], v[190:193], v[54:57]
	v_mfma_f32_16x16x32_bf16 v[50:53], v[182:185], v[190:193], v[50:53]
	v_mfma_f32_16x16x32_bf16 v[38:41], v[166:169], v[204:207], v[38:41]
	v_mfma_f32_16x16x32_bf16 v[34:37], v[182:185], v[204:207], v[34:37]
	v_mfma_f32_16x16x32_bf16 v[22:25], v[166:169], v[212:215], v[22:25]
	v_mfma_f32_16x16x32_bf16 v[18:21], v[182:185], v[212:215], v[18:21]
	v_mfma_f32_16x16x32_bf16 v[6:9], v[166:169], v[220:223], v[6:9]
	v_mfma_f32_16x16x32_bf16 v[2:5], v[182:185], v[220:223], v[2:5]
	v_mfma_f32_16x16x32_bf16 v[54:57], v[178:181], v[194:197], v[54:57]
	v_mfma_f32_16x16x32_bf16 v[50:53], v[186:189], v[194:197], v[50:53]
	v_mfma_f32_16x16x32_bf16 v[38:41], v[178:181], v[208:211], v[38:41]
	v_mfma_f32_16x16x32_bf16 v[34:37], v[186:189], v[208:211], v[34:37]
	v_mfma_f32_16x16x32_bf16 v[22:25], v[178:181], v[216:219], v[22:25]
	v_mfma_f32_16x16x32_bf16 v[18:21], v[186:189], v[216:219], v[18:21]
	v_mfma_f32_16x16x32_bf16 v[6:9], v[178:181], v[224:227], v[6:9]
	v_mfma_f32_16x16x32_bf16 v[2:5], v[186:189], v[224:227], v[2:5]
	s_add_i32 s56, s56, 2
	s_add_u32 s22, s22, 0x100
	s_addc_u32 s23, s23, 0
	s_add_u32 s20, s20, 0x100
	s_addc_u32 s21, s21, 0
	s_cmp_gt_u32 s56, 13
	s_setprio 0
	s_barrier
	s_cbranch_scc0 .LBB0_927
	s_and_b64 vcc, exec, s[10:11]
	s_cbranch_vccz .LBB0_930
	s_barrier

.LBB0_938:
	s_add_u32 s14, s64, s10
	s_addc_u32 s15, s65, s11
	s_add_u32 s14, s14, 0x2ce00100
	s_addc_u32 s15, s15, 0
	s_add_u32 s40, s66, s10
	s_addc_u32 s41, s62, s11
	s_add_i32 s42, 0, 0x10000
	s_cmpk_eq_i32 s10, 0x700
	s_cselect_b32 s19, s45, s15
	s_cselect_b32 s18, s44, s14
	s_cselect_b32 s15, s1, s41
	s_cselect_b32 s14, s0, s40
	s_add_i32 s43, 0, 0x14000
	v_add_u32_e32 v160, s42, v146
	v_add_u32_e32 v168, s43, v146
	ds_read_b128 v[148:151], v160
	ds_read_b128 v[152:155], v160 offset:1024
	ds_read_b128 v[156:159], v160 offset:2048
	ds_read_b128 v[160:163], v160 offset:3072
	ds_read_b128 v[164:167], v168
	ds_read_b128 v[178:181], v168 offset:1024
	ds_read_b128 v[182:185], v168 offset:2048
	ds_read_b128 v[186:189], v168 offset:3072
	v_lshl_add_u64 v[168:169], v[140:141], 0, s[10:11]
	s_add_i32 m0, s22, 0xc000
	ds_read_b128 v[190:193], v147
	ds_read_b128 v[194:197], v147 offset:1024
	ds_read_b128 v[204:207], v147 offset:2048
	ds_read_b128 v[208:211], v147 offset:3072
	ds_read_b128 v[212:215], v147 offset:4096
	ds_read_b128 v[216:219], v147 offset:5120
	ds_read_b128 v[220:223], v147 offset:6144
	ds_read_b128 v[224:227], v147 offset:7168
	global_load_lds_dwordx4 v[168:169], off
	v_lshl_add_u64 v[168:169], v[142:143], 0, s[10:11]
	s_add_i32 m0, s22, 0xe000
	s_nop 0
	global_load_lds_dwordx4 v[168:169], off
	s_waitcnt vmcnt(8)
	s_waitcnt lgkmcnt(0)
	s_barrier
	s_setprio 1
	s_waitcnt lgkmcnt(0)
	v_mfma_f32_16x16x32_bf16 v[130:133], v[148:151], v[190:193], v[130:133]
	v_mfma_f32_16x16x32_bf16 v[126:129], v[156:159], v[190:193], v[126:129]
	v_mfma_f32_16x16x32_bf16 v[114:117], v[148:151], v[204:207], v[114:117]
	v_mfma_f32_16x16x32_bf16 v[110:113], v[156:159], v[204:207], v[110:113]
	v_mfma_f32_16x16x32_bf16 v[94:97], v[148:151], v[212:215], v[94:97]
	v_mfma_f32_16x16x32_bf16 v[90:93], v[156:159], v[212:215], v[90:93]
	v_mfma_f32_16x16x32_bf16 v[78:81], v[148:151], v[220:223], v[78:81]
	v_mfma_f32_16x16x32_bf16 v[74:77], v[156:159], v[220:223], v[74:77]
	v_mfma_f32_16x16x32_bf16 v[130:133], v[152:155], v[194:197], v[130:133]
	v_mfma_f32_16x16x32_bf16 v[126:129], v[160:163], v[194:197], v[126:129]
	v_mfma_f32_16x16x32_bf16 v[114:117], v[152:155], v[208:211], v[114:117]
	v_mfma_f32_16x16x32_bf16 v[110:113], v[160:163], v[208:211], v[110:113]
	v_mfma_f32_16x16x32_bf16 v[94:97], v[152:155], v[216:219], v[94:97]
	v_mfma_f32_16x16x32_bf16 v[90:93], v[160:163], v[216:219], v[90:93]
	v_mfma_f32_16x16x32_bf16 v[78:81], v[152:155], v[224:227], v[78:81]
	v_mfma_f32_16x16x32_bf16 v[74:77], v[160:163], v[224:227], v[74:77]
	s_setprio 0
	s_setprio 1
	v_mfma_f32_16x16x32_bf16 v[122:125], v[164:167], v[190:193], v[122:125]
	v_mfma_f32_16x16x32_bf16 v[118:121], v[182:185], v[190:193], v[118:121]
	v_mfma_f32_16x16x32_bf16 v[106:109], v[164:167], v[204:207], v[106:109]
	v_mfma_f32_16x16x32_bf16 v[102:105], v[182:185], v[204:207], v[102:105]
	v_mfma_f32_16x16x32_bf16 v[86:89], v[164:167], v[212:215], v[86:89]
	v_mfma_f32_16x16x32_bf16 v[82:85], v[182:185], v[212:215], v[82:85]
	v_mfma_f32_16x16x32_bf16 v[70:73], v[164:167], v[220:223], v[70:73]
	v_mfma_f32_16x16x32_bf16 v[66:69], v[182:185], v[220:223], v[66:69]
	v_mfma_f32_16x16x32_bf16 v[122:125], v[178:181], v[194:197], v[122:125]
	v_mfma_f32_16x16x32_bf16 v[118:121], v[186:189], v[194:197], v[118:121]
	v_mfma_f32_16x16x32_bf16 v[106:109], v[178:181], v[208:211], v[106:109]
	v_mfma_f32_16x16x32_bf16 v[102:105], v[186:189], v[208:211], v[102:105]
	v_mfma_f32_16x16x32_bf16 v[86:89], v[178:181], v[216:219], v[86:89]
	v_mfma_f32_16x16x32_bf16 v[82:85], v[186:189], v[216:219], v[82:85]
	v_mfma_f32_16x16x32_bf16 v[70:73], v[178:181], v[224:227], v[70:73]
	v_mfma_f32_16x16x32_bf16 v[66:69], v[186:189], v[224:227], v[66:69]
	s_setprio 0
	s_barrier
	s_add_i32 s40, s42, s21
	v_lshl_add_u64 v[168:169], s[14:15], 0, v[172:173]
	s_mov_b32 m0, s40
	ds_read_b128 v[190:193], v147 offset:16384
	ds_read_b128 v[194:197], v147 offset:17408
	ds_read_b128 v[204:207], v147 offset:18432
	ds_read_b128 v[208:211], v147 offset:19456
	ds_read_b128 v[212:215], v147 offset:20480
	ds_read_b128 v[216:219], v147 offset:21504
	ds_read_b128 v[220:223], v147 offset:22528
	ds_read_b128 v[224:227], v147 offset:23552
	global_load_lds_dwordx4 v[168:169], off
	s_add_i32 m0, s40, 0x2000
	s_add_u32 s40, s14, 0x40000
	v_lshl_add_u64 v[198:199], s[14:15], 0, v[134:135]
	s_addc_u32 s41, s15, 0
	s_add_i32 s42, s43, s21
	global_load_lds_dwordx4 v[198:199], off
	v_lshl_add_u64 v[228:229], s[40:41], 0, v[172:173]
	s_mov_b32 m0, s42
	v_lshl_add_u64 v[230:231], s[18:19], 0, v[136:137]
	global_load_lds_dwordx4 v[228:229], off
	v_lshl_add_u64 v[228:229], s[40:41], 0, v[134:135]
	s_add_i32 m0, s42, 0x2000
	s_nop 0
	global_load_lds_dwordx4 v[228:229], off
	v_lshl_add_u64 v[228:229], s[18:19], 0, v[138:139]
	s_mov_b32 m0, s22
	s_nop 0
	global_load_lds_dwordx4 v[228:229], off
	s_mov_b32 m0, s23
	s_nop 0
	global_load_lds_dwordx4 v[230:231], off
	s_waitcnt vmcnt(8)
	s_waitcnt lgkmcnt(0)
	s_barrier
	s_setprio 1
	s_waitcnt lgkmcnt(0)
	v_mfma_f32_16x16x32_bf16 v[62:65], v[148:151], v[190:193], v[62:65]
	v_mfma_f32_16x16x32_bf16 v[58:61], v[156:159], v[190:193], v[58:61]
	v_mfma_f32_16x16x32_bf16 v[46:49], v[148:151], v[204:207], v[46:49]
	v_mfma_f32_16x16x32_bf16 v[42:45], v[156:159], v[204:207], v[42:45]
	v_mfma_f32_16x16x32_bf16 v[30:33], v[148:151], v[212:215], v[30:33]
	v_mfma_f32_16x16x32_bf16 v[26:29], v[156:159], v[212:215], v[26:29]
	v_mfma_f32_16x16x32_bf16 v[14:17], v[148:151], v[220:223], v[14:17]
	v_mfma_f32_16x16x32_bf16 v[10:13], v[156:159], v[220:223], v[10:13]
	v_mfma_f32_16x16x32_bf16 v[62:65], v[152:155], v[194:197], v[62:65]
	v_mfma_f32_16x16x32_bf16 v[58:61], v[160:163], v[194:197], v[58:61]
	v_mfma_f32_16x16x32_bf16 v[46:49], v[152:155], v[208:211], v[46:49]
	v_mfma_f32_16x16x32_bf16 v[42:45], v[160:163], v[208:211], v[42:45]
	v_mfma_f32_16x16x32_bf16 v[30:33], v[152:155], v[216:219], v[30:33]
	v_mfma_f32_16x16x32_bf16 v[26:29], v[160:163], v[216:219], v[26:29]
	v_mfma_f32_16x16x32_bf16 v[14:17], v[152:155], v[224:227], v[14:17]
	v_mfma_f32_16x16x32_bf16 v[10:13], v[160:163], v[224:227], v[10:13]
	s_setprio 0
	s_setprio 1
	v_mfma_f32_16x16x32_bf16 v[54:57], v[164:167], v[190:193], v[54:57]
	v_mfma_f32_16x16x32_bf16 v[50:53], v[182:185], v[190:193], v[50:53]
	v_mfma_f32_16x16x32_bf16 v[38:41], v[164:167], v[204:207], v[38:41]
	v_mfma_f32_16x16x32_bf16 v[34:37], v[182:185], v[204:207], v[34:37]
	v_mfma_f32_16x16x32_bf16 v[22:25], v[164:167], v[212:215], v[22:25]
	v_mfma_f32_16x16x32_bf16 v[18:21], v[182:185], v[212:215], v[18:21]
	v_mfma_f32_16x16x32_bf16 v[6:9], v[164:167], v[220:223], v[6:9]
	v_mfma_f32_16x16x32_bf16 v[2:5], v[182:185], v[220:223], v[2:5]
	v_mfma_f32_16x16x32_bf16 v[54:57], v[178:181], v[194:197], v[54:57]
	v_mfma_f32_16x16x32_bf16 v[50:53], v[186:189], v[194:197], v[50:53]
	v_mfma_f32_16x16x32_bf16 v[38:41], v[178:181], v[208:211], v[38:41]
	v_mfma_f32_16x16x32_bf16 v[34:37], v[186:189], v[208:211], v[34:37]
	v_mfma_f32_16x16x32_bf16 v[22:25], v[178:181], v[216:219], v[22:25]
	v_mfma_f32_16x16x32_bf16 v[18:21], v[186:189], v[216:219], v[18:21]
	v_mfma_f32_16x16x32_bf16 v[6:9], v[178:181], v[224:227], v[6:9]
	v_mfma_f32_16x16x32_bf16 v[2:5], v[186:189], v[224:227], v[2:5]
	s_setprio 0
	s_barrier
	s_add_i32 s40, 0, 0x18000
	s_add_i32 s41, 0, 0x1c000
	v_add_u32_e32 v160, s40, v146
	v_add_u32_e32 v186, s41, v146
	ds_read_b128 v[148:151], v160
	ds_read_b128 v[152:155], v160 offset:1024
	ds_read_b128 v[156:159], v160 offset:2048
	ds_read_b128 v[160:163], v160 offset:3072
	ds_read_b128 v[164:167], v186
	ds_read_b128 v[178:181], v186 offset:1024
	ds_read_b128 v[182:185], v186 offset:2048
	ds_read_b128 v[186:189], v186 offset:3072
	s_add_u32 s18, s18, 0x40000
	s_addc_u32 s19, s19, 0
	s_mov_b32 m0, s28
	v_lshl_add_u64 v[232:233], s[18:19], 0, v[138:139]
	ds_read_b128 v[190:193], v147 offset:32768
	ds_read_b128 v[194:197], v147 offset:33792
	ds_read_b128 v[204:207], v147 offset:34816
	ds_read_b128 v[208:211], v147 offset:35840
	ds_read_b128 v[212:215], v147 offset:36864
	ds_read_b128 v[216:219], v147 offset:37888
	ds_read_b128 v[220:223], v147 offset:38912
	ds_read_b128 v[224:227], v147 offset:39936
	global_load_lds_dwordx4 v[232:233], off
	v_lshl_add_u64 v[232:233], s[18:19], 0, v[136:137]
	s_mov_b32 m0, s29
	s_nop 0
	global_load_lds_dwordx4 v[232:233], off
	s_waitcnt vmcnt(8)
	s_waitcnt lgkmcnt(0)
	s_barrier
	s_setprio 1
	s_waitcnt lgkmcnt(0)
	v_mfma_f32_16x16x32_bf16 v[130:133], v[148:151], v[190:193], v[130:133]
	v_mfma_f32_16x16x32_bf16 v[126:129], v[156:159], v[190:193], v[126:129]
	v_mfma_f32_16x16x32_bf16 v[114:117], v[148:151], v[204:207], v[114:117]
	v_mfma_f32_16x16x32_bf16 v[110:113], v[156:159], v[204:207], v[110:113]
	v_mfma_f32_16x16x32_bf16 v[94:97], v[148:151], v[212:215], v[94:97]
	v_mfma_f32_16x16x32_bf16 v[90:93], v[156:159], v[212:215], v[90:93]
	v_mfma_f32_16x16x32_bf16 v[78:81], v[148:151], v[220:223], v[78:81]
	v_mfma_f32_16x16x32_bf16 v[74:77], v[156:159], v[220:223], v[74:77]
	v_mfma_f32_16x16x32_bf16 v[130:133], v[152:155], v[194:197], v[130:133]
	v_mfma_f32_16x16x32_bf16 v[126:129], v[160:163], v[194:197], v[126:129]
	v_mfma_f32_16x16x32_bf16 v[114:117], v[152:155], v[208:211], v[114:117]
	v_mfma_f32_16x16x32_bf16 v[110:113], v[160:163], v[208:211], v[110:113]
	v_mfma_f32_16x16x32_bf16 v[94:97], v[152:155], v[216:219], v[94:97]
	v_mfma_f32_16x16x32_bf16 v[90:93], v[160:163], v[216:219], v[90:93]
	v_mfma_f32_16x16x32_bf16 v[78:81], v[152:155], v[224:227], v[78:81]
	v_mfma_f32_16x16x32_bf16 v[74:77], v[160:163], v[224:227], v[74:77]
	s_setprio 0
	s_setprio 1
	v_mfma_f32_16x16x32_bf16 v[122:125], v[164:167], v[190:193], v[122:125]
	v_mfma_f32_16x16x32_bf16 v[118:121], v[182:185], v[190:193], v[118:121]
	v_mfma_f32_16x16x32_bf16 v[106:109], v[164:167], v[204:207], v[106:109]
	v_mfma_f32_16x16x32_bf16 v[102:105], v[182:185], v[204:207], v[102:105]
	v_mfma_f32_16x16x32_bf16 v[86:89], v[164:167], v[212:215], v[86:89]
	v_mfma_f32_16x16x32_bf16 v[82:85], v[182:185], v[212:215], v[82:85]
	v_mfma_f32_16x16x32_bf16 v[70:73], v[164:167], v[220:223], v[70:73]
	v_mfma_f32_16x16x32_bf16 v[66:69], v[182:185], v[220:223], v[66:69]
	v_mfma_f32_16x16x32_bf16 v[122:125], v[178:181], v[194:197], v[122:125]
	v_mfma_f32_16x16x32_bf16 v[118:121], v[186:189], v[194:197], v[118:121]
	v_mfma_f32_16x16x32_bf16 v[106:109], v[178:181], v[208:211], v[106:109]
	v_mfma_f32_16x16x32_bf16 v[102:105], v[186:189], v[208:211], v[102:105]
	v_mfma_f32_16x16x32_bf16 v[86:89], v[178:181], v[216:219], v[86:89]
	v_mfma_f32_16x16x32_bf16 v[82:85], v[186:189], v[216:219], v[82:85]
	v_mfma_f32_16x16x32_bf16 v[70:73], v[178:181], v[224:227], v[70:73]
	v_mfma_f32_16x16x32_bf16 v[66:69], v[186:189], v[224:227], v[66:69]
	s_setprio 0
	s_barrier
	s_add_i32 s18, s40, s21
	v_lshl_add_u64 v[168:169], v[168:169], 0, s[84:85]
	s_mov_b32 m0, s18
	ds_read_b128 v[190:193], v147 offset:49152
	ds_read_b128 v[194:197], v147 offset:50176
	ds_read_b128 v[204:207], v147 offset:51200
	ds_read_b128 v[208:211], v147 offset:52224
	ds_read_b128 v[212:215], v147 offset:53248
	ds_read_b128 v[216:219], v147 offset:54272
	ds_read_b128 v[220:223], v147 offset:55296
	ds_read_b128 v[224:227], v147 offset:56320
	global_load_lds_dwordx4 v[168:169], off
	s_add_i32 m0, s18, 0x2000
	s_add_u32 s14, s14, 0x40080
	v_lshl_add_u64 v[168:169], v[198:199], 0, s[84:85]
	s_addc_u32 s15, s15, 0
	s_add_i32 s18, s41, s21
	global_load_lds_dwordx4 v[168:169], off
	v_lshl_add_u64 v[168:169], s[14:15], 0, v[172:173]
	s_mov_b32 m0, s18
	s_nop 0
	global_load_lds_dwordx4 v[168:169], off
	v_lshl_add_u64 v[168:169], s[14:15], 0, v[134:135]
	s_add_i32 m0, s18, 0x2000
	s_nop 0
	global_load_lds_dwordx4 v[168:169], off
	v_lshl_add_u64 v[168:169], v[228:229], 0, s[84:85]
	s_mov_b32 m0, s35
	s_nop 0
	global_load_lds_dwordx4 v[168:169], off
	v_lshl_add_u64 v[168:169], v[230:231], 0, s[84:85]
	s_mov_b32 m0, s38
	s_nop 0
	global_load_lds_dwordx4 v[168:169], off
	s_waitcnt vmcnt(8)
	s_waitcnt lgkmcnt(0)
	s_barrier
	s_setprio 1
	s_waitcnt lgkmcnt(0)
	v_mfma_f32_16x16x32_bf16 v[62:65], v[148:151], v[190:193], v[62:65]
	v_mfma_f32_16x16x32_bf16 v[58:61], v[156:159], v[190:193], v[58:61]
	v_mfma_f32_16x16x32_bf16 v[46:49], v[148:151], v[204:207], v[46:49]
	v_mfma_f32_16x16x32_bf16 v[42:45], v[156:159], v[204:207], v[42:45]
	v_mfma_f32_16x16x32_bf16 v[30:33], v[148:151], v[212:215], v[30:33]
	v_mfma_f32_16x16x32_bf16 v[26:29], v[156:159], v[212:215], v[26:29]
	v_mfma_f32_16x16x32_bf16 v[14:17], v[148:151], v[220:223], v[14:17]
	v_mfma_f32_16x16x32_bf16 v[10:13], v[156:159], v[220:223], v[10:13]
	v_mfma_f32_16x16x32_bf16 v[62:65], v[152:155], v[194:197], v[62:65]
	v_mfma_f32_16x16x32_bf16 v[58:61], v[160:163], v[194:197], v[58:61]
	v_mfma_f32_16x16x32_bf16 v[46:49], v[152:155], v[208:211], v[46:49]
	v_mfma_f32_16x16x32_bf16 v[42:45], v[160:163], v[208:211], v[42:45]
	v_mfma_f32_16x16x32_bf16 v[30:33], v[152:155], v[216:219], v[30:33]
	v_mfma_f32_16x16x32_bf16 v[26:29], v[160:163], v[216:219], v[26:29]
	v_mfma_f32_16x16x32_bf16 v[14:17], v[152:155], v[224:227], v[14:17]
	v_mfma_f32_16x16x32_bf16 v[10:13], v[160:163], v[224:227], v[10:13]
	s_setprio 0
	s_setprio 1
	v_mfma_f32_16x16x32_bf16 v[54:57], v[164:167], v[190:193], v[54:57]
	v_mfma_f32_16x16x32_bf16 v[50:53], v[182:185], v[190:193], v[50:53]
	v_mfma_f32_16x16x32_bf16 v[38:41], v[164:167], v[204:207], v[38:41]
	v_mfma_f32_16x16x32_bf16 v[34:37], v[182:185], v[204:207], v[34:37]
	v_mfma_f32_16x16x32_bf16 v[22:25], v[164:167], v[212:215], v[22:25]
	v_mfma_f32_16x16x32_bf16 v[18:21], v[182:185], v[212:215], v[18:21]
	v_mfma_f32_16x16x32_bf16 v[6:9], v[164:167], v[220:223], v[6:9]
	v_mfma_f32_16x16x32_bf16 v[2:5], v[182:185], v[220:223], v[2:5]
	v_mfma_f32_16x16x32_bf16 v[54:57], v[178:181], v[194:197], v[54:57]
	v_mfma_f32_16x16x32_bf16 v[50:53], v[186:189], v[194:197], v[50:53]
	v_mfma_f32_16x16x32_bf16 v[38:41], v[178:181], v[208:211], v[38:41]
	v_mfma_f32_16x16x32_bf16 v[34:37], v[186:189], v[208:211], v[34:37]
	v_mfma_f32_16x16x32_bf16 v[22:25], v[178:181], v[216:219], v[22:25]
	v_mfma_f32_16x16x32_bf16 v[18:21], v[186:189], v[216:219], v[18:21]
	v_mfma_f32_16x16x32_bf16 v[6:9], v[178:181], v[224:227], v[6:9]
	v_mfma_f32_16x16x32_bf16 v[2:5], v[186:189], v[224:227], v[2:5]
	s_add_i32 s39, s39, 2
	s_add_u32 s10, s10, 0x100
	s_addc_u32 s11, s11, 0
	s_cmp_gt_u32 s39, 13
	s_setprio 0
	s_barrier
	s_cbranch_scc0 .LBB0_938
	s_cmpk_lt_u32 s20, 0x100
	s_cbranch_scc0 .LBB0_941
	s_barrier

.LBB0_1004:
	s_add_u32 s14, s46, s10
	s_addc_u32 s15, s47, s11
	s_add_u32 s14, s14, 0x2ce00100
	s_addc_u32 s15, s15, 0
	s_add_u32 s40, s48, s10
	s_addc_u32 s41, s49, s11
	s_add_i32 s42, 0, 0x10000
	s_cmpk_eq_i32 s10, 0x700
	s_cselect_b32 s19, s45, s15
	s_cselect_b32 s18, s44, s14
	s_cselect_b32 s15, s1, s41
	s_cselect_b32 s14, s0, s40
	s_add_i32 s43, 0, 0x14000
	v_add_u32_e32 v160, s42, v146
	v_add_u32_e32 v168, s43, v146
	ds_read_b128 v[148:151], v160
	ds_read_b128 v[152:155], v160 offset:1024
	ds_read_b128 v[156:159], v160 offset:2048
	ds_read_b128 v[160:163], v160 offset:3072
	ds_read_b128 v[164:167], v168
	ds_read_b128 v[178:181], v168 offset:1024
	ds_read_b128 v[182:185], v168 offset:2048
	ds_read_b128 v[186:189], v168 offset:3072
	v_lshl_add_u64 v[168:169], v[140:141], 0, s[10:11]
	s_add_i32 m0, s22, 0xc000
	ds_read_b128 v[190:193], v147
	ds_read_b128 v[194:197], v147 offset:1024
	ds_read_b128 v[204:207], v147 offset:2048
	ds_read_b128 v[208:211], v147 offset:3072
	ds_read_b128 v[212:215], v147 offset:4096
	ds_read_b128 v[216:219], v147 offset:5120
	ds_read_b128 v[220:223], v147 offset:6144
	ds_read_b128 v[224:227], v147 offset:7168
	global_load_lds_dwordx4 v[168:169], off
	v_lshl_add_u64 v[168:169], v[142:143], 0, s[10:11]
	s_add_i32 m0, s22, 0xe000
	s_nop 0
	global_load_lds_dwordx4 v[168:169], off
	s_waitcnt vmcnt(8)
	s_waitcnt lgkmcnt(0)
	s_barrier
	s_setprio 1
	s_waitcnt lgkmcnt(0)
	v_mfma_f32_16x16x32_bf16 v[130:133], v[148:151], v[190:193], v[130:133]
	v_mfma_f32_16x16x32_bf16 v[126:129], v[156:159], v[190:193], v[126:129]
	v_mfma_f32_16x16x32_bf16 v[122:125], v[148:151], v[204:207], v[122:125]
	v_mfma_f32_16x16x32_bf16 v[114:117], v[156:159], v[204:207], v[114:117]
	v_mfma_f32_16x16x32_bf16 v[94:97], v[148:151], v[212:215], v[94:97]
	v_mfma_f32_16x16x32_bf16 v[90:93], v[156:159], v[212:215], v[90:93]
	v_mfma_f32_16x16x32_bf16 v[78:81], v[148:151], v[220:223], v[78:81]
	v_mfma_f32_16x16x32_bf16 v[74:77], v[156:159], v[220:223], v[74:77]
	v_mfma_f32_16x16x32_bf16 v[130:133], v[152:155], v[194:197], v[130:133]
	v_mfma_f32_16x16x32_bf16 v[126:129], v[160:163], v[194:197], v[126:129]
	v_mfma_f32_16x16x32_bf16 v[122:125], v[152:155], v[208:211], v[122:125]
	v_mfma_f32_16x16x32_bf16 v[114:117], v[160:163], v[208:211], v[114:117]
	v_mfma_f32_16x16x32_bf16 v[94:97], v[152:155], v[216:219], v[94:97]
	v_mfma_f32_16x16x32_bf16 v[90:93], v[160:163], v[216:219], v[90:93]
	v_mfma_f32_16x16x32_bf16 v[78:81], v[152:155], v[224:227], v[78:81]
	v_mfma_f32_16x16x32_bf16 v[74:77], v[160:163], v[224:227], v[74:77]
	s_setprio 0
	s_setprio 1
	v_mfma_f32_16x16x32_bf16 v[118:121], v[164:167], v[190:193], v[118:121]
	v_mfma_f32_16x16x32_bf16 v[110:113], v[182:185], v[190:193], v[110:113]
	v_mfma_f32_16x16x32_bf16 v[106:109], v[164:167], v[204:207], v[106:109]
	v_mfma_f32_16x16x32_bf16 v[102:105], v[182:185], v[204:207], v[102:105]
	v_mfma_f32_16x16x32_bf16 v[86:89], v[164:167], v[212:215], v[86:89]
	v_mfma_f32_16x16x32_bf16 v[82:85], v[182:185], v[212:215], v[82:85]
	v_mfma_f32_16x16x32_bf16 v[70:73], v[164:167], v[220:223], v[70:73]
	v_mfma_f32_16x16x32_bf16 v[66:69], v[182:185], v[220:223], v[66:69]
	v_mfma_f32_16x16x32_bf16 v[118:121], v[178:181], v[194:197], v[118:121]
	v_mfma_f32_16x16x32_bf16 v[110:113], v[186:189], v[194:197], v[110:113]
	v_mfma_f32_16x16x32_bf16 v[106:109], v[178:181], v[208:211], v[106:109]
	v_mfma_f32_16x16x32_bf16 v[102:105], v[186:189], v[208:211], v[102:105]
	v_mfma_f32_16x16x32_bf16 v[86:89], v[178:181], v[216:219], v[86:89]
	v_mfma_f32_16x16x32_bf16 v[82:85], v[186:189], v[216:219], v[82:85]
	v_mfma_f32_16x16x32_bf16 v[70:73], v[178:181], v[224:227], v[70:73]
	v_mfma_f32_16x16x32_bf16 v[66:69], v[186:189], v[224:227], v[66:69]
	s_setprio 0
	s_barrier
	s_add_i32 s40, s42, s21
	v_lshl_add_u64 v[168:169], s[14:15], 0, v[172:173]
	s_mov_b32 m0, s40
	ds_read_b128 v[190:193], v147 offset:16384
	ds_read_b128 v[194:197], v147 offset:17408
	ds_read_b128 v[204:207], v147 offset:18432
	ds_read_b128 v[208:211], v147 offset:19456
	ds_read_b128 v[212:215], v147 offset:20480
	ds_read_b128 v[216:219], v147 offset:21504
	ds_read_b128 v[220:223], v147 offset:22528
	ds_read_b128 v[224:227], v147 offset:23552
	global_load_lds_dwordx4 v[168:169], off
	s_add_i32 m0, s40, 0x2000
	s_add_u32 s40, s14, 0x40000
	v_lshl_add_u64 v[198:199], s[14:15], 0, v[134:135]
	s_addc_u32 s41, s15, 0
	s_add_i32 s42, s43, s21
	global_load_lds_dwordx4 v[198:199], off
	v_lshl_add_u64 v[228:229], s[40:41], 0, v[172:173]
	s_mov_b32 m0, s42
	v_lshl_add_u64 v[230:231], s[18:19], 0, v[136:137]
	global_load_lds_dwordx4 v[228:229], off
	v_lshl_add_u64 v[228:229], s[40:41], 0, v[134:135]
	s_add_i32 m0, s42, 0x2000
	s_nop 0
	global_load_lds_dwordx4 v[228:229], off
	v_lshl_add_u64 v[228:229], s[18:19], 0, v[138:139]
	s_mov_b32 m0, s22
	s_nop 0
	global_load_lds_dwordx4 v[228:229], off
	s_mov_b32 m0, s23
	s_nop 0
	global_load_lds_dwordx4 v[230:231], off
	s_waitcnt vmcnt(8)
	s_waitcnt lgkmcnt(0)
	s_barrier
	s_setprio 1
	s_waitcnt lgkmcnt(0)
	v_mfma_f32_16x16x32_bf16 v[62:65], v[148:151], v[190:193], v[62:65]
	v_mfma_f32_16x16x32_bf16 v[58:61], v[156:159], v[190:193], v[58:61]
	v_mfma_f32_16x16x32_bf16 v[46:49], v[148:151], v[204:207], v[46:49]
	v_mfma_f32_16x16x32_bf16 v[42:45], v[156:159], v[204:207], v[42:45]
	v_mfma_f32_16x16x32_bf16 v[30:33], v[148:151], v[212:215], v[30:33]
	v_mfma_f32_16x16x32_bf16 v[26:29], v[156:159], v[212:215], v[26:29]
	v_mfma_f32_16x16x32_bf16 v[14:17], v[148:151], v[220:223], v[14:17]
	v_mfma_f32_16x16x32_bf16 v[10:13], v[156:159], v[220:223], v[10:13]
	v_mfma_f32_16x16x32_bf16 v[62:65], v[152:155], v[194:197], v[62:65]
	v_mfma_f32_16x16x32_bf16 v[58:61], v[160:163], v[194:197], v[58:61]
	v_mfma_f32_16x16x32_bf16 v[46:49], v[152:155], v[208:211], v[46:49]
	v_mfma_f32_16x16x32_bf16 v[42:45], v[160:163], v[208:211], v[42:45]
	v_mfma_f32_16x16x32_bf16 v[30:33], v[152:155], v[216:219], v[30:33]
	v_mfma_f32_16x16x32_bf16 v[26:29], v[160:163], v[216:219], v[26:29]
	v_mfma_f32_16x16x32_bf16 v[14:17], v[152:155], v[224:227], v[14:17]
	v_mfma_f32_16x16x32_bf16 v[10:13], v[160:163], v[224:227], v[10:13]
	s_setprio 0
	s_setprio 1
	v_mfma_f32_16x16x32_bf16 v[54:57], v[164:167], v[190:193], v[54:57]
	v_mfma_f32_16x16x32_bf16 v[50:53], v[182:185], v[190:193], v[50:53]
	v_mfma_f32_16x16x32_bf16 v[38:41], v[164:167], v[204:207], v[38:41]
	v_mfma_f32_16x16x32_bf16 v[34:37], v[182:185], v[204:207], v[34:37]
	v_mfma_f32_16x16x32_bf16 v[22:25], v[164:167], v[212:215], v[22:25]
	v_mfma_f32_16x16x32_bf16 v[18:21], v[182:185], v[212:215], v[18:21]
	v_mfma_f32_16x16x32_bf16 v[6:9], v[164:167], v[220:223], v[6:9]
	v_mfma_f32_16x16x32_bf16 v[2:5], v[182:185], v[220:223], v[2:5]
	v_mfma_f32_16x16x32_bf16 v[54:57], v[178:181], v[194:197], v[54:57]
	v_mfma_f32_16x16x32_bf16 v[50:53], v[186:189], v[194:197], v[50:53]
	v_mfma_f32_16x16x32_bf16 v[38:41], v[178:181], v[208:211], v[38:41]
	v_mfma_f32_16x16x32_bf16 v[34:37], v[186:189], v[208:211], v[34:37]
	v_mfma_f32_16x16x32_bf16 v[22:25], v[178:181], v[216:219], v[22:25]
	v_mfma_f32_16x16x32_bf16 v[18:21], v[186:189], v[216:219], v[18:21]
	v_mfma_f32_16x16x32_bf16 v[6:9], v[178:181], v[224:227], v[6:9]
	v_mfma_f32_16x16x32_bf16 v[2:5], v[186:189], v[224:227], v[2:5]
	s_setprio 0
	s_barrier
	s_add_i32 s40, 0, 0x18000
	s_add_i32 s41, 0, 0x1c000
	v_add_u32_e32 v160, s40, v146
	v_add_u32_e32 v186, s41, v146
	ds_read_b128 v[148:151], v160
	ds_read_b128 v[152:155], v160 offset:1024
	ds_read_b128 v[156:159], v160 offset:2048
	ds_read_b128 v[160:163], v160 offset:3072
	ds_read_b128 v[164:167], v186
	ds_read_b128 v[178:181], v186 offset:1024
	ds_read_b128 v[182:185], v186 offset:2048
	ds_read_b128 v[186:189], v186 offset:3072
	s_add_u32 s18, s18, 0x40000
	s_addc_u32 s19, s19, 0
	s_mov_b32 m0, s28
	v_lshl_add_u64 v[232:233], s[18:19], 0, v[138:139]
	ds_read_b128 v[190:193], v147 offset:32768
	ds_read_b128 v[194:197], v147 offset:33792
	ds_read_b128 v[204:207], v147 offset:34816
	ds_read_b128 v[208:211], v147 offset:35840
	ds_read_b128 v[212:215], v147 offset:36864
	ds_read_b128 v[216:219], v147 offset:37888
	ds_read_b128 v[220:223], v147 offset:38912
	ds_read_b128 v[224:227], v147 offset:39936
	global_load_lds_dwordx4 v[232:233], off
	v_lshl_add_u64 v[232:233], s[18:19], 0, v[136:137]
	s_mov_b32 m0, s29
	s_nop 0
	global_load_lds_dwordx4 v[232:233], off
	s_waitcnt vmcnt(8)
	s_waitcnt lgkmcnt(0)
	s_barrier
	s_setprio 1
	s_waitcnt lgkmcnt(0)
	v_mfma_f32_16x16x32_bf16 v[130:133], v[148:151], v[190:193], v[130:133]
	v_mfma_f32_16x16x32_bf16 v[126:129], v[156:159], v[190:193], v[126:129]
	v_mfma_f32_16x16x32_bf16 v[122:125], v[148:151], v[204:207], v[122:125]
	v_mfma_f32_16x16x32_bf16 v[114:117], v[156:159], v[204:207], v[114:117]
	v_mfma_f32_16x16x32_bf16 v[94:97], v[148:151], v[212:215], v[94:97]
	v_mfma_f32_16x16x32_bf16 v[90:93], v[156:159], v[212:215], v[90:93]
	v_mfma_f32_16x16x32_bf16 v[78:81], v[148:151], v[220:223], v[78:81]
	v_mfma_f32_16x16x32_bf16 v[74:77], v[156:159], v[220:223], v[74:77]
	v_mfma_f32_16x16x32_bf16 v[130:133], v[152:155], v[194:197], v[130:133]
	v_mfma_f32_16x16x32_bf16 v[126:129], v[160:163], v[194:197], v[126:129]
	v_mfma_f32_16x16x32_bf16 v[122:125], v[152:155], v[208:211], v[122:125]
	v_mfma_f32_16x16x32_bf16 v[114:117], v[160:163], v[208:211], v[114:117]
	v_mfma_f32_16x16x32_bf16 v[94:97], v[152:155], v[216:219], v[94:97]
	v_mfma_f32_16x16x32_bf16 v[90:93], v[160:163], v[216:219], v[90:93]
	v_mfma_f32_16x16x32_bf16 v[78:81], v[152:155], v[224:227], v[78:81]
	v_mfma_f32_16x16x32_bf16 v[74:77], v[160:163], v[224:227], v[74:77]
	s_setprio 0
	s_setprio 1
	v_mfma_f32_16x16x32_bf16 v[118:121], v[164:167], v[190:193], v[118:121]
	v_mfma_f32_16x16x32_bf16 v[110:113], v[182:185], v[190:193], v[110:113]
	v_mfma_f32_16x16x32_bf16 v[106:109], v[164:167], v[204:207], v[106:109]
	v_mfma_f32_16x16x32_bf16 v[102:105], v[182:185], v[204:207], v[102:105]
	v_mfma_f32_16x16x32_bf16 v[86:89], v[164:167], v[212:215], v[86:89]
	v_mfma_f32_16x16x32_bf16 v[82:85], v[182:185], v[212:215], v[82:85]
	v_mfma_f32_16x16x32_bf16 v[70:73], v[164:167], v[220:223], v[70:73]
	v_mfma_f32_16x16x32_bf16 v[66:69], v[182:185], v[220:223], v[66:69]
	v_mfma_f32_16x16x32_bf16 v[118:121], v[178:181], v[194:197], v[118:121]
	v_mfma_f32_16x16x32_bf16 v[110:113], v[186:189], v[194:197], v[110:113]
	v_mfma_f32_16x16x32_bf16 v[106:109], v[178:181], v[208:211], v[106:109]
	v_mfma_f32_16x16x32_bf16 v[102:105], v[186:189], v[208:211], v[102:105]
	v_mfma_f32_16x16x32_bf16 v[86:89], v[178:181], v[216:219], v[86:89]
	v_mfma_f32_16x16x32_bf16 v[82:85], v[186:189], v[216:219], v[82:85]
	v_mfma_f32_16x16x32_bf16 v[70:73], v[178:181], v[224:227], v[70:73]
	v_mfma_f32_16x16x32_bf16 v[66:69], v[186:189], v[224:227], v[66:69]
	s_setprio 0
	s_barrier
	s_add_i32 s18, s40, s21
	v_lshl_add_u64 v[168:169], v[168:169], 0, s[84:85]
	s_mov_b32 m0, s18
	ds_read_b128 v[190:193], v147 offset:49152
	ds_read_b128 v[194:197], v147 offset:50176
	ds_read_b128 v[204:207], v147 offset:51200
	ds_read_b128 v[208:211], v147 offset:52224
	ds_read_b128 v[212:215], v147 offset:53248
	ds_read_b128 v[216:219], v147 offset:54272
	ds_read_b128 v[220:223], v147 offset:55296
	ds_read_b128 v[224:227], v147 offset:56320
	global_load_lds_dwordx4 v[168:169], off
	s_add_i32 m0, s18, 0x2000
	s_add_u32 s14, s14, 0x40080
	v_lshl_add_u64 v[168:169], v[198:199], 0, s[84:85]
	s_addc_u32 s15, s15, 0
	s_add_i32 s18, s41, s21
	global_load_lds_dwordx4 v[168:169], off
	v_lshl_add_u64 v[168:169], s[14:15], 0, v[172:173]
	s_mov_b32 m0, s18
	s_nop 0
	global_load_lds_dwordx4 v[168:169], off
	v_lshl_add_u64 v[168:169], s[14:15], 0, v[134:135]
	s_add_i32 m0, s18, 0x2000
	s_nop 0
	global_load_lds_dwordx4 v[168:169], off
	v_lshl_add_u64 v[168:169], v[228:229], 0, s[84:85]
	s_mov_b32 m0, s35
	s_nop 0
	global_load_lds_dwordx4 v[168:169], off
	v_lshl_add_u64 v[168:169], v[230:231], 0, s[84:85]
	s_mov_b32 m0, s38
	s_nop 0
	global_load_lds_dwordx4 v[168:169], off
	s_waitcnt vmcnt(8)
	s_waitcnt lgkmcnt(0)
	s_barrier
	s_setprio 1
	s_waitcnt lgkmcnt(0)
	v_mfma_f32_16x16x32_bf16 v[62:65], v[148:151], v[190:193], v[62:65]
	v_mfma_f32_16x16x32_bf16 v[58:61], v[156:159], v[190:193], v[58:61]
	v_mfma_f32_16x16x32_bf16 v[46:49], v[148:151], v[204:207], v[46:49]
	v_mfma_f32_16x16x32_bf16 v[42:45], v[156:159], v[204:207], v[42:45]
	v_mfma_f32_16x16x32_bf16 v[30:33], v[148:151], v[212:215], v[30:33]
	v_mfma_f32_16x16x32_bf16 v[26:29], v[156:159], v[212:215], v[26:29]
	v_mfma_f32_16x16x32_bf16 v[14:17], v[148:151], v[220:223], v[14:17]
	v_mfma_f32_16x16x32_bf16 v[10:13], v[156:159], v[220:223], v[10:13]
	v_mfma_f32_16x16x32_bf16 v[62:65], v[152:155], v[194:197], v[62:65]
	v_mfma_f32_16x16x32_bf16 v[58:61], v[160:163], v[194:197], v[58:61]
	v_mfma_f32_16x16x32_bf16 v[46:49], v[152:155], v[208:211], v[46:49]
	v_mfma_f32_16x16x32_bf16 v[42:45], v[160:163], v[208:211], v[42:45]
	v_mfma_f32_16x16x32_bf16 v[30:33], v[152:155], v[216:219], v[30:33]
	v_mfma_f32_16x16x32_bf16 v[26:29], v[160:163], v[216:219], v[26:29]
	v_mfma_f32_16x16x32_bf16 v[14:17], v[152:155], v[224:227], v[14:17]
	v_mfma_f32_16x16x32_bf16 v[10:13], v[160:163], v[224:227], v[10:13]
	s_setprio 0
	s_setprio 1
	v_mfma_f32_16x16x32_bf16 v[54:57], v[164:167], v[190:193], v[54:57]
	v_mfma_f32_16x16x32_bf16 v[50:53], v[182:185], v[190:193], v[50:53]
	v_mfma_f32_16x16x32_bf16 v[38:41], v[164:167], v[204:207], v[38:41]
	v_mfma_f32_16x16x32_bf16 v[34:37], v[182:185], v[204:207], v[34:37]
	v_mfma_f32_16x16x32_bf16 v[22:25], v[164:167], v[212:215], v[22:25]
	v_mfma_f32_16x16x32_bf16 v[18:21], v[182:185], v[212:215], v[18:21]
	v_mfma_f32_16x16x32_bf16 v[6:9], v[164:167], v[220:223], v[6:9]
	v_mfma_f32_16x16x32_bf16 v[2:5], v[182:185], v[220:223], v[2:5]
	v_mfma_f32_16x16x32_bf16 v[54:57], v[178:181], v[194:197], v[54:57]
	v_mfma_f32_16x16x32_bf16 v[50:53], v[186:189], v[194:197], v[50:53]
	v_mfma_f32_16x16x32_bf16 v[38:41], v[178:181], v[208:211], v[38:41]
	v_mfma_f32_16x16x32_bf16 v[34:37], v[186:189], v[208:211], v[34:37]
	v_mfma_f32_16x16x32_bf16 v[22:25], v[178:181], v[216:219], v[22:25]
	v_mfma_f32_16x16x32_bf16 v[18:21], v[186:189], v[216:219], v[18:21]
	v_mfma_f32_16x16x32_bf16 v[6:9], v[178:181], v[224:227], v[6:9]
	v_mfma_f32_16x16x32_bf16 v[2:5], v[186:189], v[224:227], v[2:5]
	s_add_i32 s39, s39, 2
	s_add_u32 s10, s10, 0x100
	s_addc_u32 s11, s11, 0
	s_cmp_gt_u32 s39, 13
	s_setprio 0
	s_barrier
	s_cbranch_scc0 .LBB0_1004
	s_cmpk_lt_u32 s20, 0x100
	s_cbranch_scc0 .LBB0_1007
	s_barrier

.LBB0_1015:
	s_add_u32 s28, s18, 0xfffc0080
	s_addc_u32 s29, s19, -1
	s_add_i32 s56, 0, 0x10000
	s_cmp_eq_u32 s55, 12
	s_cselect_b32 s35, s51, s29
	s_cselect_b32 s34, s52, s28
	s_cselect_b32 s29, s20, s54
	s_cselect_b32 s28, s21, s53
	s_add_i32 s58, 0, 0x14000
	v_add_u32_e32 v146, s56, v205
	v_add_u32_e32 v162, s58, v205
	ds_read_b128 v[134:137], v146
	ds_read_b128 v[138:141], v146 offset:1024
	ds_read_b128 v[142:145], v146 offset:2048
	ds_read_b128 v[146:149], v146 offset:3072
	ds_read_b128 v[150:153], v162
	ds_read_b128 v[154:157], v162 offset:1024
	ds_read_b128 v[158:161], v162 offset:2048
	ds_read_b128 v[162:165], v162 offset:3072
	v_lshl_add_u64 v[224:225], s[18:19], 0, v[184:185]
	s_add_i32 m0, s43, 0xc000
	ds_read_b128 v[166:169], v207
	ds_read_b128 v[188:191], v207 offset:1024
	ds_read_b128 v[192:195], v207 offset:2048
	ds_read_b128 v[196:199], v207 offset:3072
	ds_read_b128 v[208:211], v207 offset:4096
	ds_read_b128 v[212:215], v207 offset:5120
	ds_read_b128 v[216:219], v207 offset:6144
	ds_read_b128 v[220:223], v207 offset:7168
	global_load_lds_dwordx4 v[224:225], off
	v_lshl_add_u64 v[224:225], s[18:19], 0, v[186:187]
	s_add_i32 m0, s43, 0xe000
	s_nop 0
	global_load_lds_dwordx4 v[224:225], off
	s_waitcnt vmcnt(8)
	s_waitcnt lgkmcnt(0)
	s_barrier
	s_setprio 1
	s_waitcnt lgkmcnt(0)
	v_mfma_f32_16x16x32_bf16 v[130:133], v[134:137], v[166:169], v[130:133]
	v_mfma_f32_16x16x32_bf16 v[126:129], v[142:145], v[166:169], v[126:129]
	v_mfma_f32_16x16x32_bf16 v[114:117], v[134:137], v[192:195], v[114:117]
	v_mfma_f32_16x16x32_bf16 v[110:113], v[142:145], v[192:195], v[110:113]
	v_mfma_f32_16x16x32_bf16 v[94:97], v[134:137], v[208:211], v[94:97]
	v_mfma_f32_16x16x32_bf16 v[90:93], v[142:145], v[208:211], v[90:93]
	v_mfma_f32_16x16x32_bf16 v[78:81], v[134:137], v[216:219], v[78:81]
	v_mfma_f32_16x16x32_bf16 v[74:77], v[142:145], v[216:219], v[74:77]
	v_mfma_f32_16x16x32_bf16 v[130:133], v[138:141], v[188:191], v[130:133]
	v_mfma_f32_16x16x32_bf16 v[126:129], v[146:149], v[188:191], v[126:129]
	v_mfma_f32_16x16x32_bf16 v[114:117], v[138:141], v[196:199], v[114:117]
	v_mfma_f32_16x16x32_bf16 v[110:113], v[146:149], v[196:199], v[110:113]
	v_mfma_f32_16x16x32_bf16 v[94:97], v[138:141], v[212:215], v[94:97]
	v_mfma_f32_16x16x32_bf16 v[90:93], v[146:149], v[212:215], v[90:93]
	v_mfma_f32_16x16x32_bf16 v[78:81], v[138:141], v[220:223], v[78:81]
	v_mfma_f32_16x16x32_bf16 v[74:77], v[146:149], v[220:223], v[74:77]
	s_setprio 0
	s_setprio 1
	v_mfma_f32_16x16x32_bf16 v[122:125], v[150:153], v[166:169], v[122:125]
	v_mfma_f32_16x16x32_bf16 v[118:121], v[158:161], v[166:169], v[118:121]
	v_mfma_f32_16x16x32_bf16 v[106:109], v[150:153], v[192:195], v[106:109]
	v_mfma_f32_16x16x32_bf16 v[102:105], v[158:161], v[192:195], v[102:105]
	v_mfma_f32_16x16x32_bf16 v[86:89], v[150:153], v[208:211], v[86:89]
	v_mfma_f32_16x16x32_bf16 v[82:85], v[158:161], v[208:211], v[82:85]
	v_mfma_f32_16x16x32_bf16 v[70:73], v[150:153], v[216:219], v[70:73]
	v_mfma_f32_16x16x32_bf16 v[66:69], v[158:161], v[216:219], v[66:69]
	v_mfma_f32_16x16x32_bf16 v[122:125], v[154:157], v[188:191], v[122:125]
	v_mfma_f32_16x16x32_bf16 v[118:121], v[162:165], v[188:191], v[118:121]
	v_mfma_f32_16x16x32_bf16 v[106:109], v[154:157], v[196:199], v[106:109]
	v_mfma_f32_16x16x32_bf16 v[102:105], v[162:165], v[196:199], v[102:105]
	v_mfma_f32_16x16x32_bf16 v[86:89], v[154:157], v[212:215], v[86:89]
	v_mfma_f32_16x16x32_bf16 v[82:85], v[162:165], v[212:215], v[82:85]
	v_mfma_f32_16x16x32_bf16 v[70:73], v[154:157], v[220:223], v[70:73]
	v_mfma_f32_16x16x32_bf16 v[66:69], v[162:165], v[220:223], v[66:69]
	s_setprio 0
	s_barrier
	s_add_i32 s56, s56, s40
	v_lshl_add_u64 v[224:225], s[28:29], 0, v[172:173]
	s_mov_b32 m0, s56
	ds_read_b128 v[166:169], v207 offset:16384
	ds_read_b128 v[188:191], v207 offset:17408
	ds_read_b128 v[192:195], v207 offset:18432
	ds_read_b128 v[196:199], v207 offset:19456
	ds_read_b128 v[208:211], v207 offset:20480
	ds_read_b128 v[212:215], v207 offset:21504
	ds_read_b128 v[216:219], v207 offset:22528
	ds_read_b128 v[220:223], v207 offset:23552
	global_load_lds_dwordx4 v[224:225], off
	s_add_i32 m0, s56, 0x2000
	s_add_u32 s56, s28, 0x40000
	v_lshl_add_u64 v[226:227], s[28:29], 0, v[178:179]
	s_addc_u32 s57, s29, 0
	s_add_i32 s58, s58, s40
	global_load_lds_dwordx4 v[226:227], off
	v_lshl_add_u64 v[228:229], s[56:57], 0, v[172:173]
	s_mov_b32 m0, s58
	v_lshl_add_u64 v[230:231], s[34:35], 0, v[180:181]
	global_load_lds_dwordx4 v[228:229], off
	v_lshl_add_u64 v[228:229], s[56:57], 0, v[178:179]
	s_add_i32 m0, s58, 0x2000
	s_nop 0
	global_load_lds_dwordx4 v[228:229], off
	v_lshl_add_u64 v[228:229], s[34:35], 0, v[182:183]
	s_mov_b32 m0, s43
	s_nop 0
	global_load_lds_dwordx4 v[228:229], off
	s_mov_b32 m0, s44
	s_nop 0
	global_load_lds_dwordx4 v[230:231], off
	s_waitcnt vmcnt(8)
	s_waitcnt lgkmcnt(0)
	s_barrier
	s_setprio 1
	s_waitcnt lgkmcnt(0)
	v_mfma_f32_16x16x32_bf16 v[62:65], v[134:137], v[166:169], v[62:65]
	v_mfma_f32_16x16x32_bf16 v[58:61], v[142:145], v[166:169], v[58:61]
	v_mfma_f32_16x16x32_bf16 v[46:49], v[134:137], v[192:195], v[46:49]
	v_mfma_f32_16x16x32_bf16 v[42:45], v[142:145], v[192:195], v[42:45]
	v_mfma_f32_16x16x32_bf16 v[30:33], v[134:137], v[208:211], v[30:33]
	v_mfma_f32_16x16x32_bf16 v[26:29], v[142:145], v[208:211], v[26:29]
	v_mfma_f32_16x16x32_bf16 v[14:17], v[134:137], v[216:219], v[14:17]
	v_mfma_f32_16x16x32_bf16 v[10:13], v[142:145], v[216:219], v[10:13]
	v_mfma_f32_16x16x32_bf16 v[62:65], v[138:141], v[188:191], v[62:65]
	v_mfma_f32_16x16x32_bf16 v[58:61], v[146:149], v[188:191], v[58:61]
	v_mfma_f32_16x16x32_bf16 v[46:49], v[138:141], v[196:199], v[46:49]
	v_mfma_f32_16x16x32_bf16 v[42:45], v[146:149], v[196:199], v[42:45]
	v_mfma_f32_16x16x32_bf16 v[30:33], v[138:141], v[212:215], v[30:33]
	v_mfma_f32_16x16x32_bf16 v[26:29], v[146:149], v[212:215], v[26:29]
	v_mfma_f32_16x16x32_bf16 v[14:17], v[138:141], v[220:223], v[14:17]
	v_mfma_f32_16x16x32_bf16 v[10:13], v[146:149], v[220:223], v[10:13]
	s_setprio 0
	s_setprio 1
	v_mfma_f32_16x16x32_bf16 v[54:57], v[150:153], v[166:169], v[54:57]
	v_mfma_f32_16x16x32_bf16 v[50:53], v[158:161], v[166:169], v[50:53]
	v_mfma_f32_16x16x32_bf16 v[38:41], v[150:153], v[192:195], v[38:41]
	v_mfma_f32_16x16x32_bf16 v[34:37], v[158:161], v[192:195], v[34:37]
	v_mfma_f32_16x16x32_bf16 v[22:25], v[150:153], v[208:211], v[22:25]
	v_mfma_f32_16x16x32_bf16 v[18:21], v[158:161], v[208:211], v[18:21]
	v_mfma_f32_16x16x32_bf16 v[6:9], v[150:153], v[216:219], v[6:9]
	v_mfma_f32_16x16x32_bf16 v[2:5], v[158:161], v[216:219], v[2:5]
	v_mfma_f32_16x16x32_bf16 v[54:57], v[154:157], v[188:191], v[54:57]
	v_mfma_f32_16x16x32_bf16 v[50:53], v[162:165], v[188:191], v[50:53]
	v_mfma_f32_16x16x32_bf16 v[38:41], v[154:157], v[196:199], v[38:41]
	v_mfma_f32_16x16x32_bf16 v[34:37], v[162:165], v[196:199], v[34:37]
	v_mfma_f32_16x16x32_bf16 v[22:25], v[154:157], v[212:215], v[22:25]
	v_mfma_f32_16x16x32_bf16 v[18:21], v[162:165], v[212:215], v[18:21]
	v_mfma_f32_16x16x32_bf16 v[6:9], v[154:157], v[220:223], v[6:9]
	v_mfma_f32_16x16x32_bf16 v[2:5], v[162:165], v[220:223], v[2:5]
	s_setprio 0
	s_barrier
	s_add_i32 s56, 0, 0x18000
	s_add_i32 s57, 0, 0x1c000
	v_add_u32_e32 v146, s56, v205
	v_add_u32_e32 v162, s57, v205
	ds_read_b128 v[134:137], v146
	ds_read_b128 v[138:141], v146 offset:1024
	ds_read_b128 v[142:145], v146 offset:2048
	ds_read_b128 v[146:149], v146 offset:3072
	ds_read_b128 v[150:153], v162
	ds_read_b128 v[154:157], v162 offset:1024
	ds_read_b128 v[158:161], v162 offset:2048
	ds_read_b128 v[162:165], v162 offset:3072
	s_add_u32 s34, s34, 0x40000
	s_addc_u32 s35, s35, 0
	s_mov_b32 m0, s45
	v_lshl_add_u64 v[232:233], s[34:35], 0, v[182:183]
	ds_read_b128 v[166:169], v207 offset:32768
	ds_read_b128 v[188:191], v207 offset:33792
	ds_read_b128 v[192:195], v207 offset:34816
	ds_read_b128 v[196:199], v207 offset:35840
	ds_read_b128 v[208:211], v207 offset:36864
	ds_read_b128 v[212:215], v207 offset:37888
	ds_read_b128 v[216:219], v207 offset:38912
	ds_read_b128 v[220:223], v207 offset:39936
	global_load_lds_dwordx4 v[232:233], off
	v_lshl_add_u64 v[232:233], s[34:35], 0, v[180:181]
	s_mov_b32 m0, s46
	s_nop 0
	global_load_lds_dwordx4 v[232:233], off
	s_waitcnt vmcnt(8)
	s_waitcnt lgkmcnt(0)
	s_barrier
	s_setprio 1
	s_waitcnt lgkmcnt(0)
	v_mfma_f32_16x16x32_bf16 v[130:133], v[134:137], v[166:169], v[130:133]
	v_mfma_f32_16x16x32_bf16 v[126:129], v[142:145], v[166:169], v[126:129]
	v_mfma_f32_16x16x32_bf16 v[114:117], v[134:137], v[192:195], v[114:117]
	v_mfma_f32_16x16x32_bf16 v[110:113], v[142:145], v[192:195], v[110:113]
	v_mfma_f32_16x16x32_bf16 v[94:97], v[134:137], v[208:211], v[94:97]
	v_mfma_f32_16x16x32_bf16 v[90:93], v[142:145], v[208:211], v[90:93]
	v_mfma_f32_16x16x32_bf16 v[78:81], v[134:137], v[216:219], v[78:81]
	v_mfma_f32_16x16x32_bf16 v[74:77], v[142:145], v[216:219], v[74:77]
	v_mfma_f32_16x16x32_bf16 v[130:133], v[138:141], v[188:191], v[130:133]
	v_mfma_f32_16x16x32_bf16 v[126:129], v[146:149], v[188:191], v[126:129]
	v_mfma_f32_16x16x32_bf16 v[114:117], v[138:141], v[196:199], v[114:117]
	v_mfma_f32_16x16x32_bf16 v[110:113], v[146:149], v[196:199], v[110:113]
	v_mfma_f32_16x16x32_bf16 v[94:97], v[138:141], v[212:215], v[94:97]
	v_mfma_f32_16x16x32_bf16 v[90:93], v[146:149], v[212:215], v[90:93]
	v_mfma_f32_16x16x32_bf16 v[78:81], v[138:141], v[220:223], v[78:81]
	v_mfma_f32_16x16x32_bf16 v[74:77], v[146:149], v[220:223], v[74:77]
	s_setprio 0
	s_setprio 1
	v_mfma_f32_16x16x32_bf16 v[122:125], v[150:153], v[166:169], v[122:125]
	v_mfma_f32_16x16x32_bf16 v[118:121], v[158:161], v[166:169], v[118:121]
	v_mfma_f32_16x16x32_bf16 v[106:109], v[150:153], v[192:195], v[106:109]
	v_mfma_f32_16x16x32_bf16 v[102:105], v[158:161], v[192:195], v[102:105]
	v_mfma_f32_16x16x32_bf16 v[86:89], v[150:153], v[208:211], v[86:89]
	v_mfma_f32_16x16x32_bf16 v[82:85], v[158:161], v[208:211], v[82:85]
	v_mfma_f32_16x16x32_bf16 v[70:73], v[150:153], v[216:219], v[70:73]
	v_mfma_f32_16x16x32_bf16 v[66:69], v[158:161], v[216:219], v[66:69]
	v_mfma_f32_16x16x32_bf16 v[122:125], v[154:157], v[188:191], v[122:125]
	v_mfma_f32_16x16x32_bf16 v[118:121], v[162:165], v[188:191], v[118:121]
	v_mfma_f32_16x16x32_bf16 v[106:109], v[154:157], v[196:199], v[106:109]
	v_mfma_f32_16x16x32_bf16 v[102:105], v[162:165], v[196:199], v[102:105]
	v_mfma_f32_16x16x32_bf16 v[86:89], v[154:157], v[212:215], v[86:89]
	v_mfma_f32_16x16x32_bf16 v[82:85], v[162:165], v[212:215], v[82:85]
	v_mfma_f32_16x16x32_bf16 v[70:73], v[154:157], v[220:223], v[70:73]
	v_mfma_f32_16x16x32_bf16 v[66:69], v[162:165], v[220:223], v[66:69]
	s_setprio 0
	s_barrier
	s_add_i32 s34, s56, s40
	v_lshl_add_u64 v[224:225], v[224:225], 0, s[84:85]
	s_mov_b32 m0, s34
	ds_read_b128 v[166:169], v207 offset:49152
	ds_read_b128 v[188:191], v207 offset:50176
	ds_read_b128 v[192:195], v207 offset:51200
	ds_read_b128 v[196:199], v207 offset:52224
	ds_read_b128 v[208:211], v207 offset:53248
	ds_read_b128 v[212:215], v207 offset:54272
	ds_read_b128 v[216:219], v207 offset:55296
	ds_read_b128 v[220:223], v207 offset:56320
	global_load_lds_dwordx4 v[224:225], off
	s_add_i32 m0, s34, 0x2000
	s_add_u32 s28, s28, 0x40080
	v_lshl_add_u64 v[224:225], v[226:227], 0, s[84:85]
	s_addc_u32 s29, s29, 0
	s_add_i32 s34, s57, s40
	global_load_lds_dwordx4 v[224:225], off
	v_lshl_add_u64 v[224:225], s[28:29], 0, v[172:173]
	s_mov_b32 m0, s34
	s_nop 0
	global_load_lds_dwordx4 v[224:225], off
	v_lshl_add_u64 v[224:225], s[28:29], 0, v[178:179]
	s_add_i32 m0, s34, 0x2000
	s_nop 0
	global_load_lds_dwordx4 v[224:225], off
	v_lshl_add_u64 v[224:225], v[228:229], 0, s[84:85]
	s_mov_b32 m0, s47
	s_nop 0
	global_load_lds_dwordx4 v[224:225], off
	v_lshl_add_u64 v[224:225], v[230:231], 0, s[84:85]
	s_mov_b32 m0, s48
	s_nop 0
	global_load_lds_dwordx4 v[224:225], off
	s_waitcnt vmcnt(8)
	s_waitcnt lgkmcnt(0)
	s_barrier
	s_setprio 1
	s_waitcnt lgkmcnt(0)
	v_mfma_f32_16x16x32_bf16 v[62:65], v[134:137], v[166:169], v[62:65]
	v_mfma_f32_16x16x32_bf16 v[58:61], v[142:145], v[166:169], v[58:61]
	v_mfma_f32_16x16x32_bf16 v[46:49], v[134:137], v[192:195], v[46:49]
	v_mfma_f32_16x16x32_bf16 v[42:45], v[142:145], v[192:195], v[42:45]
	v_mfma_f32_16x16x32_bf16 v[30:33], v[134:137], v[208:211], v[30:33]
	v_mfma_f32_16x16x32_bf16 v[26:29], v[142:145], v[208:211], v[26:29]
	v_mfma_f32_16x16x32_bf16 v[14:17], v[134:137], v[216:219], v[14:17]
	v_mfma_f32_16x16x32_bf16 v[10:13], v[142:145], v[216:219], v[10:13]
	v_mfma_f32_16x16x32_bf16 v[62:65], v[138:141], v[188:191], v[62:65]
	v_mfma_f32_16x16x32_bf16 v[58:61], v[146:149], v[188:191], v[58:61]
	v_mfma_f32_16x16x32_bf16 v[46:49], v[138:141], v[196:199], v[46:49]
	v_mfma_f32_16x16x32_bf16 v[42:45], v[146:149], v[196:199], v[42:45]
	v_mfma_f32_16x16x32_bf16 v[30:33], v[138:141], v[212:215], v[30:33]
	v_mfma_f32_16x16x32_bf16 v[26:29], v[146:149], v[212:215], v[26:29]
	v_mfma_f32_16x16x32_bf16 v[14:17], v[138:141], v[220:223], v[14:17]
	v_mfma_f32_16x16x32_bf16 v[10:13], v[146:149], v[220:223], v[10:13]
	s_setprio 0
	s_setprio 1
	v_mfma_f32_16x16x32_bf16 v[54:57], v[150:153], v[166:169], v[54:57]
	v_mfma_f32_16x16x32_bf16 v[50:53], v[158:161], v[166:169], v[50:53]
	v_mfma_f32_16x16x32_bf16 v[38:41], v[150:153], v[192:195], v[38:41]
	v_mfma_f32_16x16x32_bf16 v[34:37], v[158:161], v[192:195], v[34:37]
	v_mfma_f32_16x16x32_bf16 v[22:25], v[150:153], v[208:211], v[22:25]
	v_mfma_f32_16x16x32_bf16 v[18:21], v[158:161], v[208:211], v[18:21]
	v_mfma_f32_16x16x32_bf16 v[6:9], v[150:153], v[216:219], v[6:9]
	v_mfma_f32_16x16x32_bf16 v[2:5], v[158:161], v[216:219], v[2:5]
	v_mfma_f32_16x16x32_bf16 v[54:57], v[154:157], v[188:191], v[54:57]
	v_mfma_f32_16x16x32_bf16 v[50:53], v[162:165], v[188:191], v[50:53]
	v_mfma_f32_16x16x32_bf16 v[38:41], v[154:157], v[196:199], v[38:41]
	v_mfma_f32_16x16x32_bf16 v[34:37], v[162:165], v[196:199], v[34:37]
	v_mfma_f32_16x16x32_bf16 v[22:25], v[154:157], v[212:215], v[22:25]
	v_mfma_f32_16x16x32_bf16 v[18:21], v[162:165], v[212:215], v[18:21]
	v_mfma_f32_16x16x32_bf16 v[6:9], v[154:157], v[220:223], v[6:9]
	v_mfma_f32_16x16x32_bf16 v[2:5], v[162:165], v[220:223], v[2:5]
	s_add_i32 s55, s55, 2
	s_add_u32 s18, s18, 0x100
	s_addc_u32 s19, s19, 0
	s_add_u32 s53, s53, 0x100
	s_addc_u32 s54, s54, 0
	s_cmp_gt_u32 s55, 13
	s_setprio 0
	s_barrier
	s_cbranch_scc0 .LBB0_1015
	s_and_b64 vcc, exec, s[10:11]
	s_cbranch_vccz .LBB0_1018
	s_barrier

.LBB0_1095:
	s_add_u32 s22, s42, s18
	s_addc_u32 s23, s43, s19
	s_add_u32 s22, s22, 0x32800100
	s_addc_u32 s23, s23, 0
	s_add_u32 s47, s44, s18
	s_addc_u32 s48, s45, s19
	s_add_i32 s49, 0, 0x10000
	s_cmpk_eq_i32 s18, 0xf00
	s_cselect_b32 s29, s15, s23
	s_cselect_b32 s28, s14, s22
	s_cselect_b32 s23, s11, s48
	s_cselect_b32 s22, s10, s47
	s_add_i32 s47, 0, 0x14000
	v_add_u32_e32 v160, s49, v146
	v_add_u32_e32 v168, s47, v146
	ds_read_b128 v[148:151], v160
	ds_read_b128 v[152:155], v160 offset:1024
	ds_read_b128 v[156:159], v160 offset:2048
	ds_read_b128 v[160:163], v160 offset:3072
	ds_read_b128 v[164:167], v168
	ds_read_b128 v[178:181], v168 offset:1024
	ds_read_b128 v[182:185], v168 offset:2048
	ds_read_b128 v[186:189], v168 offset:3072
	v_lshl_add_u64 v[168:169], v[140:141], 0, s[18:19]
	s_add_i32 m0, s1, 0xc000
	ds_read_b128 v[190:193], v147
	ds_read_b128 v[194:197], v147 offset:1024
	ds_read_b128 v[204:207], v147 offset:2048
	ds_read_b128 v[208:211], v147 offset:3072
	ds_read_b128 v[212:215], v147 offset:4096
	ds_read_b128 v[216:219], v147 offset:5120
	ds_read_b128 v[220:223], v147 offset:6144
	ds_read_b128 v[224:227], v147 offset:7168
	global_load_lds_dwordx4 v[168:169], off
	v_lshl_add_u64 v[168:169], v[142:143], 0, s[18:19]
	s_add_i32 m0, s1, 0xe000
	s_nop 0
	global_load_lds_dwordx4 v[168:169], off
	s_waitcnt vmcnt(8)
	s_waitcnt lgkmcnt(0)
	s_barrier
	s_setprio 1
	s_waitcnt lgkmcnt(0)
	v_mfma_f32_16x16x32_bf16 v[130:133], v[148:151], v[190:193], v[130:133]
	v_mfma_f32_16x16x32_bf16 v[126:129], v[156:159], v[190:193], v[126:129]
	v_mfma_f32_16x16x32_bf16 v[122:125], v[148:151], v[204:207], v[122:125]
	v_mfma_f32_16x16x32_bf16 v[118:121], v[156:159], v[204:207], v[118:121]
	v_mfma_f32_16x16x32_bf16 v[94:97], v[148:151], v[212:215], v[94:97]
	v_mfma_f32_16x16x32_bf16 v[90:93], v[156:159], v[212:215], v[90:93]
	v_mfma_f32_16x16x32_bf16 v[78:81], v[148:151], v[220:223], v[78:81]
	v_mfma_f32_16x16x32_bf16 v[74:77], v[156:159], v[220:223], v[74:77]
	v_mfma_f32_16x16x32_bf16 v[130:133], v[152:155], v[194:197], v[130:133]
	v_mfma_f32_16x16x32_bf16 v[126:129], v[160:163], v[194:197], v[126:129]
	v_mfma_f32_16x16x32_bf16 v[122:125], v[152:155], v[208:211], v[122:125]
	v_mfma_f32_16x16x32_bf16 v[118:121], v[160:163], v[208:211], v[118:121]
	v_mfma_f32_16x16x32_bf16 v[94:97], v[152:155], v[216:219], v[94:97]
	v_mfma_f32_16x16x32_bf16 v[90:93], v[160:163], v[216:219], v[90:93]
	v_mfma_f32_16x16x32_bf16 v[78:81], v[152:155], v[224:227], v[78:81]
	v_mfma_f32_16x16x32_bf16 v[74:77], v[160:163], v[224:227], v[74:77]
	s_setprio 0
	s_setprio 1
	v_mfma_f32_16x16x32_bf16 v[114:117], v[164:167], v[190:193], v[114:117]
	v_mfma_f32_16x16x32_bf16 v[110:113], v[182:185], v[190:193], v[110:113]
	v_mfma_f32_16x16x32_bf16 v[106:109], v[164:167], v[204:207], v[106:109]
	v_mfma_f32_16x16x32_bf16 v[102:105], v[182:185], v[204:207], v[102:105]
	v_mfma_f32_16x16x32_bf16 v[86:89], v[164:167], v[212:215], v[86:89]
	v_mfma_f32_16x16x32_bf16 v[82:85], v[182:185], v[212:215], v[82:85]
	v_mfma_f32_16x16x32_bf16 v[70:73], v[164:167], v[220:223], v[70:73]
	v_mfma_f32_16x16x32_bf16 v[66:69], v[182:185], v[220:223], v[66:69]
	v_mfma_f32_16x16x32_bf16 v[114:117], v[178:181], v[194:197], v[114:117]
	v_mfma_f32_16x16x32_bf16 v[110:113], v[186:189], v[194:197], v[110:113]
	v_mfma_f32_16x16x32_bf16 v[106:109], v[178:181], v[208:211], v[106:109]
	v_mfma_f32_16x16x32_bf16 v[102:105], v[186:189], v[208:211], v[102:105]
	v_mfma_f32_16x16x32_bf16 v[86:89], v[178:181], v[216:219], v[86:89]
	v_mfma_f32_16x16x32_bf16 v[82:85], v[186:189], v[216:219], v[82:85]
	v_mfma_f32_16x16x32_bf16 v[70:73], v[178:181], v[224:227], v[70:73]
	v_mfma_f32_16x16x32_bf16 v[66:69], v[186:189], v[224:227], v[66:69]
	s_setprio 0
	s_barrier
	s_add_i32 s48, s49, s21
	v_lshl_add_u64 v[168:169], s[22:23], 0, v[172:173]
	s_mov_b32 m0, s48
	ds_read_b128 v[190:193], v147 offset:16384
	ds_read_b128 v[194:197], v147 offset:17408
	ds_read_b128 v[204:207], v147 offset:18432
	ds_read_b128 v[208:211], v147 offset:19456
	ds_read_b128 v[212:215], v147 offset:20480
	ds_read_b128 v[216:219], v147 offset:21504
	ds_read_b128 v[220:223], v147 offset:22528
	ds_read_b128 v[224:227], v147 offset:23552
	global_load_lds_dwordx4 v[168:169], off
	s_add_i32 m0, s48, 0x2000
	s_add_u32 s48, s22, 0x80000
	v_lshl_add_u64 v[198:199], s[22:23], 0, v[138:139]
	s_addc_u32 s49, s23, 0
	s_add_i32 s47, s47, s21
	global_load_lds_dwordx4 v[198:199], off
	v_lshl_add_u64 v[228:229], s[48:49], 0, v[172:173]
	s_mov_b32 m0, s47
	v_lshl_add_u64 v[230:231], s[28:29], 0, v[136:137]
	global_load_lds_dwordx4 v[228:229], off
	v_lshl_add_u64 v[228:229], s[48:49], 0, v[138:139]
	s_add_i32 m0, s47, 0x2000
	s_nop 0
	global_load_lds_dwordx4 v[228:229], off
	v_lshl_add_u64 v[228:229], s[28:29], 0, v[134:135]
	s_mov_b32 m0, s1
	s_nop 0
	global_load_lds_dwordx4 v[228:229], off
	s_mov_b32 m0, s34
	s_nop 0
	global_load_lds_dwordx4 v[230:231], off
	s_waitcnt vmcnt(8)
	s_waitcnt lgkmcnt(0)
	s_barrier
	s_setprio 1
	s_waitcnt lgkmcnt(0)
	v_mfma_f32_16x16x32_bf16 v[62:65], v[148:151], v[190:193], v[62:65]
	v_mfma_f32_16x16x32_bf16 v[58:61], v[156:159], v[190:193], v[58:61]
	v_mfma_f32_16x16x32_bf16 v[46:49], v[148:151], v[204:207], v[46:49]
	v_mfma_f32_16x16x32_bf16 v[42:45], v[156:159], v[204:207], v[42:45]
	v_mfma_f32_16x16x32_bf16 v[30:33], v[148:151], v[212:215], v[30:33]
	v_mfma_f32_16x16x32_bf16 v[26:29], v[156:159], v[212:215], v[26:29]
	v_mfma_f32_16x16x32_bf16 v[14:17], v[148:151], v[220:223], v[14:17]
	v_mfma_f32_16x16x32_bf16 v[10:13], v[156:159], v[220:223], v[10:13]
	v_mfma_f32_16x16x32_bf16 v[62:65], v[152:155], v[194:197], v[62:65]
	v_mfma_f32_16x16x32_bf16 v[58:61], v[160:163], v[194:197], v[58:61]
	v_mfma_f32_16x16x32_bf16 v[46:49], v[152:155], v[208:211], v[46:49]
	v_mfma_f32_16x16x32_bf16 v[42:45], v[160:163], v[208:211], v[42:45]
	v_mfma_f32_16x16x32_bf16 v[30:33], v[152:155], v[216:219], v[30:33]
	v_mfma_f32_16x16x32_bf16 v[26:29], v[160:163], v[216:219], v[26:29]
	v_mfma_f32_16x16x32_bf16 v[14:17], v[152:155], v[224:227], v[14:17]
	v_mfma_f32_16x16x32_bf16 v[10:13], v[160:163], v[224:227], v[10:13]
	s_setprio 0
	s_setprio 1
	v_mfma_f32_16x16x32_bf16 v[54:57], v[164:167], v[190:193], v[54:57]
	v_mfma_f32_16x16x32_bf16 v[50:53], v[182:185], v[190:193], v[50:53]
	v_mfma_f32_16x16x32_bf16 v[38:41], v[164:167], v[204:207], v[38:41]
	v_mfma_f32_16x16x32_bf16 v[34:37], v[182:185], v[204:207], v[34:37]
	v_mfma_f32_16x16x32_bf16 v[22:25], v[164:167], v[212:215], v[22:25]
	v_mfma_f32_16x16x32_bf16 v[18:21], v[182:185], v[212:215], v[18:21]
	v_mfma_f32_16x16x32_bf16 v[6:9], v[164:167], v[220:223], v[6:9]
	v_mfma_f32_16x16x32_bf16 v[2:5], v[182:185], v[220:223], v[2:5]
	v_mfma_f32_16x16x32_bf16 v[54:57], v[178:181], v[194:197], v[54:57]
	v_mfma_f32_16x16x32_bf16 v[50:53], v[186:189], v[194:197], v[50:53]
	v_mfma_f32_16x16x32_bf16 v[38:41], v[178:181], v[208:211], v[38:41]
	v_mfma_f32_16x16x32_bf16 v[34:37], v[186:189], v[208:211], v[34:37]
	v_mfma_f32_16x16x32_bf16 v[22:25], v[178:181], v[216:219], v[22:25]
	v_mfma_f32_16x16x32_bf16 v[18:21], v[186:189], v[216:219], v[18:21]
	v_mfma_f32_16x16x32_bf16 v[6:9], v[178:181], v[224:227], v[6:9]
	v_mfma_f32_16x16x32_bf16 v[2:5], v[186:189], v[224:227], v[2:5]
	s_setprio 0
	s_barrier
	s_add_i32 s47, 0, 0x18000
	s_add_i32 s48, 0, 0x1c000
	v_add_u32_e32 v160, s47, v146
	v_add_u32_e32 v186, s48, v146
	ds_read_b128 v[148:151], v160
	ds_read_b128 v[152:155], v160 offset:1024
	ds_read_b128 v[156:159], v160 offset:2048
	ds_read_b128 v[160:163], v160 offset:3072
	ds_read_b128 v[164:167], v186
	ds_read_b128 v[178:181], v186 offset:1024
	ds_read_b128 v[182:185], v186 offset:2048
	ds_read_b128 v[186:189], v186 offset:3072
	s_add_u32 s28, s28, 0x80000
	s_addc_u32 s29, s29, 0
	s_mov_b32 m0, s35
	v_lshl_add_u64 v[232:233], s[28:29], 0, v[134:135]
	ds_read_b128 v[190:193], v147 offset:32768
	ds_read_b128 v[194:197], v147 offset:33792
	ds_read_b128 v[204:207], v147 offset:34816
	ds_read_b128 v[208:211], v147 offset:35840
	ds_read_b128 v[212:215], v147 offset:36864
	ds_read_b128 v[216:219], v147 offset:37888
	ds_read_b128 v[220:223], v147 offset:38912
	ds_read_b128 v[224:227], v147 offset:39936
	global_load_lds_dwordx4 v[232:233], off
	v_lshl_add_u64 v[232:233], s[28:29], 0, v[136:137]
	s_mov_b32 m0, s38
	s_nop 0
	global_load_lds_dwordx4 v[232:233], off
	s_waitcnt vmcnt(8)
	s_waitcnt lgkmcnt(0)
	s_barrier
	s_setprio 1
	s_waitcnt lgkmcnt(0)
	v_mfma_f32_16x16x32_bf16 v[130:133], v[148:151], v[190:193], v[130:133]
	v_mfma_f32_16x16x32_bf16 v[126:129], v[156:159], v[190:193], v[126:129]
	v_mfma_f32_16x16x32_bf16 v[122:125], v[148:151], v[204:207], v[122:125]
	v_mfma_f32_16x16x32_bf16 v[118:121], v[156:159], v[204:207], v[118:121]
	v_mfma_f32_16x16x32_bf16 v[94:97], v[148:151], v[212:215], v[94:97]
	v_mfma_f32_16x16x32_bf16 v[90:93], v[156:159], v[212:215], v[90:93]
	v_mfma_f32_16x16x32_bf16 v[78:81], v[148:151], v[220:223], v[78:81]
	v_mfma_f32_16x16x32_bf16 v[74:77], v[156:159], v[220:223], v[74:77]
	v_mfma_f32_16x16x32_bf16 v[130:133], v[152:155], v[194:197], v[130:133]
	v_mfma_f32_16x16x32_bf16 v[126:129], v[160:163], v[194:197], v[126:129]
	v_mfma_f32_16x16x32_bf16 v[122:125], v[152:155], v[208:211], v[122:125]
	v_mfma_f32_16x16x32_bf16 v[118:121], v[160:163], v[208:211], v[118:121]
	v_mfma_f32_16x16x32_bf16 v[94:97], v[152:155], v[216:219], v[94:97]
	v_mfma_f32_16x16x32_bf16 v[90:93], v[160:163], v[216:219], v[90:93]
	v_mfma_f32_16x16x32_bf16 v[78:81], v[152:155], v[224:227], v[78:81]
	v_mfma_f32_16x16x32_bf16 v[74:77], v[160:163], v[224:227], v[74:77]
	s_setprio 0
	s_setprio 1
	v_mfma_f32_16x16x32_bf16 v[114:117], v[164:167], v[190:193], v[114:117]
	v_mfma_f32_16x16x32_bf16 v[110:113], v[182:185], v[190:193], v[110:113]
	v_mfma_f32_16x16x32_bf16 v[106:109], v[164:167], v[204:207], v[106:109]
	v_mfma_f32_16x16x32_bf16 v[102:105], v[182:185], v[204:207], v[102:105]
	v_mfma_f32_16x16x32_bf16 v[86:89], v[164:167], v[212:215], v[86:89]
	v_mfma_f32_16x16x32_bf16 v[82:85], v[182:185], v[212:215], v[82:85]
	v_mfma_f32_16x16x32_bf16 v[70:73], v[164:167], v[220:223], v[70:73]
	v_mfma_f32_16x16x32_bf16 v[66:69], v[182:185], v[220:223], v[66:69]
	v_mfma_f32_16x16x32_bf16 v[114:117], v[178:181], v[194:197], v[114:117]
	v_mfma_f32_16x16x32_bf16 v[110:113], v[186:189], v[194:197], v[110:113]
	v_mfma_f32_16x16x32_bf16 v[106:109], v[178:181], v[208:211], v[106:109]
	v_mfma_f32_16x16x32_bf16 v[102:105], v[186:189], v[208:211], v[102:105]
	v_mfma_f32_16x16x32_bf16 v[86:89], v[178:181], v[216:219], v[86:89]
	v_mfma_f32_16x16x32_bf16 v[82:85], v[186:189], v[216:219], v[82:85]
	v_mfma_f32_16x16x32_bf16 v[70:73], v[178:181], v[224:227], v[70:73]
	v_mfma_f32_16x16x32_bf16 v[66:69], v[186:189], v[224:227], v[66:69]
	s_setprio 0
	s_barrier
	s_add_i32 s28, s47, s21
	v_lshl_add_u64 v[168:169], v[168:169], 0, s[84:85]
	s_mov_b32 m0, s28
	ds_read_b128 v[190:193], v147 offset:49152
	ds_read_b128 v[194:197], v147 offset:50176
	ds_read_b128 v[204:207], v147 offset:51200
	ds_read_b128 v[208:211], v147 offset:52224
	ds_read_b128 v[212:215], v147 offset:53248
	ds_read_b128 v[216:219], v147 offset:54272
	ds_read_b128 v[220:223], v147 offset:55296
	ds_read_b128 v[224:227], v147 offset:56320
	global_load_lds_dwordx4 v[168:169], off
	s_add_i32 m0, s28, 0x2000
	s_add_u32 s22, s22, 0x80080
	v_lshl_add_u64 v[168:169], v[198:199], 0, s[84:85]
	s_addc_u32 s23, s23, 0
	s_add_i32 s28, s48, s21
	global_load_lds_dwordx4 v[168:169], off
	v_lshl_add_u64 v[168:169], s[22:23], 0, v[172:173]
	s_mov_b32 m0, s28
	s_nop 0
	global_load_lds_dwordx4 v[168:169], off
	v_lshl_add_u64 v[168:169], s[22:23], 0, v[138:139]
	s_add_i32 m0, s28, 0x2000
	s_nop 0
	global_load_lds_dwordx4 v[168:169], off
	v_lshl_add_u64 v[168:169], v[228:229], 0, s[84:85]
	s_mov_b32 m0, s40
	s_nop 0
	global_load_lds_dwordx4 v[168:169], off
	v_lshl_add_u64 v[168:169], v[230:231], 0, s[84:85]
	s_mov_b32 m0, s41
	s_nop 0
	global_load_lds_dwordx4 v[168:169], off
	s_waitcnt vmcnt(8)
	s_waitcnt lgkmcnt(0)
	s_barrier
	s_setprio 1
	s_waitcnt lgkmcnt(0)
	v_mfma_f32_16x16x32_bf16 v[62:65], v[148:151], v[190:193], v[62:65]
	v_mfma_f32_16x16x32_bf16 v[58:61], v[156:159], v[190:193], v[58:61]
	v_mfma_f32_16x16x32_bf16 v[46:49], v[148:151], v[204:207], v[46:49]
	v_mfma_f32_16x16x32_bf16 v[42:45], v[156:159], v[204:207], v[42:45]
	v_mfma_f32_16x16x32_bf16 v[30:33], v[148:151], v[212:215], v[30:33]
	v_mfma_f32_16x16x32_bf16 v[26:29], v[156:159], v[212:215], v[26:29]
	v_mfma_f32_16x16x32_bf16 v[14:17], v[148:151], v[220:223], v[14:17]
	v_mfma_f32_16x16x32_bf16 v[10:13], v[156:159], v[220:223], v[10:13]
	v_mfma_f32_16x16x32_bf16 v[62:65], v[152:155], v[194:197], v[62:65]
	v_mfma_f32_16x16x32_bf16 v[58:61], v[160:163], v[194:197], v[58:61]
	v_mfma_f32_16x16x32_bf16 v[46:49], v[152:155], v[208:211], v[46:49]
	v_mfma_f32_16x16x32_bf16 v[42:45], v[160:163], v[208:211], v[42:45]
	v_mfma_f32_16x16x32_bf16 v[30:33], v[152:155], v[216:219], v[30:33]
	v_mfma_f32_16x16x32_bf16 v[26:29], v[160:163], v[216:219], v[26:29]
	v_mfma_f32_16x16x32_bf16 v[14:17], v[152:155], v[224:227], v[14:17]
	v_mfma_f32_16x16x32_bf16 v[10:13], v[160:163], v[224:227], v[10:13]
	s_setprio 0
	s_setprio 1
	v_mfma_f32_16x16x32_bf16 v[54:57], v[164:167], v[190:193], v[54:57]
	v_mfma_f32_16x16x32_bf16 v[50:53], v[182:185], v[190:193], v[50:53]
	v_mfma_f32_16x16x32_bf16 v[38:41], v[164:167], v[204:207], v[38:41]
	v_mfma_f32_16x16x32_bf16 v[34:37], v[182:185], v[204:207], v[34:37]
	v_mfma_f32_16x16x32_bf16 v[22:25], v[164:167], v[212:215], v[22:25]
	v_mfma_f32_16x16x32_bf16 v[18:21], v[182:185], v[212:215], v[18:21]
	v_mfma_f32_16x16x32_bf16 v[6:9], v[164:167], v[220:223], v[6:9]
	v_mfma_f32_16x16x32_bf16 v[2:5], v[182:185], v[220:223], v[2:5]
	v_mfma_f32_16x16x32_bf16 v[54:57], v[178:181], v[194:197], v[54:57]
	v_mfma_f32_16x16x32_bf16 v[50:53], v[186:189], v[194:197], v[50:53]
	v_mfma_f32_16x16x32_bf16 v[38:41], v[178:181], v[208:211], v[38:41]
	v_mfma_f32_16x16x32_bf16 v[34:37], v[186:189], v[208:211], v[34:37]
	v_mfma_f32_16x16x32_bf16 v[22:25], v[178:181], v[216:219], v[22:25]
	v_mfma_f32_16x16x32_bf16 v[18:21], v[186:189], v[216:219], v[18:21]
	v_mfma_f32_16x16x32_bf16 v[6:9], v[178:181], v[224:227], v[6:9]
	v_mfma_f32_16x16x32_bf16 v[2:5], v[186:189], v[224:227], v[2:5]
	s_add_i32 s46, s46, 2
	s_add_u32 s18, s18, 0x100
	s_addc_u32 s19, s19, 0
	s_cmp_gt_u32 s46, 29
	s_setprio 0
	s_barrier
	s_cbranch_scc0 .LBB0_1095
	s_cmpk_lt_u32 s20, 0x100
	s_cbranch_scc0 .LBB0_1098
	s_barrier

.LBB0_1160:
	s_add_u32 s14, s46, s10
	s_addc_u32 s15, s47, s11
	s_add_u32 s14, s14, 0x32800100
	s_addc_u32 s15, s15, 0
	s_add_u32 s40, s48, s10
	s_addc_u32 s41, s49, s11
	s_add_i32 s42, 0, 0x10000
	s_cmpk_eq_i32 s10, 0xf00
	s_cselect_b32 s19, s45, s15
	s_cselect_b32 s18, s44, s14
	s_cselect_b32 s15, s1, s41
	s_cselect_b32 s14, s0, s40
	s_add_i32 s43, 0, 0x14000
	v_add_u32_e32 v160, s42, v146
	v_add_u32_e32 v168, s43, v146
	ds_read_b128 v[148:151], v160
	ds_read_b128 v[152:155], v160 offset:1024
	ds_read_b128 v[156:159], v160 offset:2048
	ds_read_b128 v[160:163], v160 offset:3072
	ds_read_b128 v[164:167], v168
	ds_read_b128 v[178:181], v168 offset:1024
	ds_read_b128 v[182:185], v168 offset:2048
	ds_read_b128 v[186:189], v168 offset:3072
	v_lshl_add_u64 v[168:169], v[140:141], 0, s[10:11]
	s_add_i32 m0, s22, 0xc000
	ds_read_b128 v[190:193], v147
	ds_read_b128 v[194:197], v147 offset:1024
	ds_read_b128 v[204:207], v147 offset:2048
	ds_read_b128 v[208:211], v147 offset:3072
	ds_read_b128 v[212:215], v147 offset:4096
	ds_read_b128 v[216:219], v147 offset:5120
	ds_read_b128 v[220:223], v147 offset:6144
	ds_read_b128 v[224:227], v147 offset:7168
	global_load_lds_dwordx4 v[168:169], off
	v_lshl_add_u64 v[168:169], v[142:143], 0, s[10:11]
	s_add_i32 m0, s22, 0xe000
	s_nop 0
	global_load_lds_dwordx4 v[168:169], off
	s_waitcnt vmcnt(8)
	s_waitcnt lgkmcnt(0)
	s_barrier
	s_setprio 1
	s_waitcnt lgkmcnt(0)
	v_mfma_f32_16x16x32_bf16 v[130:133], v[148:151], v[190:193], v[130:133]
	v_mfma_f32_16x16x32_bf16 v[126:129], v[156:159], v[190:193], v[126:129]
	v_mfma_f32_16x16x32_bf16 v[122:125], v[148:151], v[204:207], v[122:125]
	v_mfma_f32_16x16x32_bf16 v[118:121], v[156:159], v[204:207], v[118:121]
	v_mfma_f32_16x16x32_bf16 v[94:97], v[148:151], v[212:215], v[94:97]
	v_mfma_f32_16x16x32_bf16 v[90:93], v[156:159], v[212:215], v[90:93]
	v_mfma_f32_16x16x32_bf16 v[78:81], v[148:151], v[220:223], v[78:81]
	v_mfma_f32_16x16x32_bf16 v[74:77], v[156:159], v[220:223], v[74:77]
	v_mfma_f32_16x16x32_bf16 v[130:133], v[152:155], v[194:197], v[130:133]
	v_mfma_f32_16x16x32_bf16 v[126:129], v[160:163], v[194:197], v[126:129]
	v_mfma_f32_16x16x32_bf16 v[122:125], v[152:155], v[208:211], v[122:125]
	v_mfma_f32_16x16x32_bf16 v[118:121], v[160:163], v[208:211], v[118:121]
	v_mfma_f32_16x16x32_bf16 v[94:97], v[152:155], v[216:219], v[94:97]
	v_mfma_f32_16x16x32_bf16 v[90:93], v[160:163], v[216:219], v[90:93]
	v_mfma_f32_16x16x32_bf16 v[78:81], v[152:155], v[224:227], v[78:81]
	v_mfma_f32_16x16x32_bf16 v[74:77], v[160:163], v[224:227], v[74:77]
	s_setprio 0
	s_setprio 1
	v_mfma_f32_16x16x32_bf16 v[114:117], v[164:167], v[190:193], v[114:117]
	v_mfma_f32_16x16x32_bf16 v[110:113], v[182:185], v[190:193], v[110:113]
	v_mfma_f32_16x16x32_bf16 v[106:109], v[164:167], v[204:207], v[106:109]
	v_mfma_f32_16x16x32_bf16 v[102:105], v[182:185], v[204:207], v[102:105]
	v_mfma_f32_16x16x32_bf16 v[86:89], v[164:167], v[212:215], v[86:89]
	v_mfma_f32_16x16x32_bf16 v[82:85], v[182:185], v[212:215], v[82:85]
	v_mfma_f32_16x16x32_bf16 v[70:73], v[164:167], v[220:223], v[70:73]
	v_mfma_f32_16x16x32_bf16 v[66:69], v[182:185], v[220:223], v[66:69]
	v_mfma_f32_16x16x32_bf16 v[114:117], v[178:181], v[194:197], v[114:117]
	v_mfma_f32_16x16x32_bf16 v[110:113], v[186:189], v[194:197], v[110:113]
	v_mfma_f32_16x16x32_bf16 v[106:109], v[178:181], v[208:211], v[106:109]
	v_mfma_f32_16x16x32_bf16 v[102:105], v[186:189], v[208:211], v[102:105]
	v_mfma_f32_16x16x32_bf16 v[86:89], v[178:181], v[216:219], v[86:89]
	v_mfma_f32_16x16x32_bf16 v[82:85], v[186:189], v[216:219], v[82:85]
	v_mfma_f32_16x16x32_bf16 v[70:73], v[178:181], v[224:227], v[70:73]
	v_mfma_f32_16x16x32_bf16 v[66:69], v[186:189], v[224:227], v[66:69]
	s_setprio 0
	s_barrier
	s_add_i32 s40, s42, s21
	v_lshl_add_u64 v[168:169], s[14:15], 0, v[172:173]
	s_mov_b32 m0, s40
	ds_read_b128 v[190:193], v147 offset:16384
	ds_read_b128 v[194:197], v147 offset:17408
	ds_read_b128 v[204:207], v147 offset:18432
	ds_read_b128 v[208:211], v147 offset:19456
	ds_read_b128 v[212:215], v147 offset:20480
	ds_read_b128 v[216:219], v147 offset:21504
	ds_read_b128 v[220:223], v147 offset:22528
	ds_read_b128 v[224:227], v147 offset:23552
	global_load_lds_dwordx4 v[168:169], off
	s_add_i32 m0, s40, 0x2000
	s_add_u32 s40, s14, 0x80000
	v_lshl_add_u64 v[198:199], s[14:15], 0, v[138:139]
	s_addc_u32 s41, s15, 0
	s_add_i32 s42, s43, s21
	global_load_lds_dwordx4 v[198:199], off
	v_lshl_add_u64 v[228:229], s[40:41], 0, v[172:173]
	s_mov_b32 m0, s42
	v_lshl_add_u64 v[230:231], s[18:19], 0, v[136:137]
	global_load_lds_dwordx4 v[228:229], off
	v_lshl_add_u64 v[228:229], s[40:41], 0, v[138:139]
	s_add_i32 m0, s42, 0x2000
	s_nop 0
	global_load_lds_dwordx4 v[228:229], off
	v_lshl_add_u64 v[228:229], s[18:19], 0, v[134:135]
	s_mov_b32 m0, s22
	s_nop 0
	global_load_lds_dwordx4 v[228:229], off
	s_mov_b32 m0, s23
	s_nop 0
	global_load_lds_dwordx4 v[230:231], off
	s_waitcnt vmcnt(8)
	s_waitcnt lgkmcnt(0)
	s_barrier
	s_setprio 1
	s_waitcnt lgkmcnt(0)
	v_mfma_f32_16x16x32_bf16 v[62:65], v[148:151], v[190:193], v[62:65]
	v_mfma_f32_16x16x32_bf16 v[58:61], v[156:159], v[190:193], v[58:61]
	v_mfma_f32_16x16x32_bf16 v[46:49], v[148:151], v[204:207], v[46:49]
	v_mfma_f32_16x16x32_bf16 v[42:45], v[156:159], v[204:207], v[42:45]
	v_mfma_f32_16x16x32_bf16 v[30:33], v[148:151], v[212:215], v[30:33]
	v_mfma_f32_16x16x32_bf16 v[26:29], v[156:159], v[212:215], v[26:29]
	v_mfma_f32_16x16x32_bf16 v[14:17], v[148:151], v[220:223], v[14:17]
	v_mfma_f32_16x16x32_bf16 v[10:13], v[156:159], v[220:223], v[10:13]
	v_mfma_f32_16x16x32_bf16 v[62:65], v[152:155], v[194:197], v[62:65]
	v_mfma_f32_16x16x32_bf16 v[58:61], v[160:163], v[194:197], v[58:61]
	v_mfma_f32_16x16x32_bf16 v[46:49], v[152:155], v[208:211], v[46:49]
	v_mfma_f32_16x16x32_bf16 v[42:45], v[160:163], v[208:211], v[42:45]
	v_mfma_f32_16x16x32_bf16 v[30:33], v[152:155], v[216:219], v[30:33]
	v_mfma_f32_16x16x32_bf16 v[26:29], v[160:163], v[216:219], v[26:29]
	v_mfma_f32_16x16x32_bf16 v[14:17], v[152:155], v[224:227], v[14:17]
	v_mfma_f32_16x16x32_bf16 v[10:13], v[160:163], v[224:227], v[10:13]
	s_setprio 0
	s_setprio 1
	v_mfma_f32_16x16x32_bf16 v[54:57], v[164:167], v[190:193], v[54:57]
	v_mfma_f32_16x16x32_bf16 v[50:53], v[182:185], v[190:193], v[50:53]
	v_mfma_f32_16x16x32_bf16 v[38:41], v[164:167], v[204:207], v[38:41]
	v_mfma_f32_16x16x32_bf16 v[34:37], v[182:185], v[204:207], v[34:37]
	v_mfma_f32_16x16x32_bf16 v[22:25], v[164:167], v[212:215], v[22:25]
	v_mfma_f32_16x16x32_bf16 v[18:21], v[182:185], v[212:215], v[18:21]
	v_mfma_f32_16x16x32_bf16 v[6:9], v[164:167], v[220:223], v[6:9]
	v_mfma_f32_16x16x32_bf16 v[2:5], v[182:185], v[220:223], v[2:5]
	v_mfma_f32_16x16x32_bf16 v[54:57], v[178:181], v[194:197], v[54:57]
	v_mfma_f32_16x16x32_bf16 v[50:53], v[186:189], v[194:197], v[50:53]
	v_mfma_f32_16x16x32_bf16 v[38:41], v[178:181], v[208:211], v[38:41]
	v_mfma_f32_16x16x32_bf16 v[34:37], v[186:189], v[208:211], v[34:37]
	v_mfma_f32_16x16x32_bf16 v[22:25], v[178:181], v[216:219], v[22:25]
	v_mfma_f32_16x16x32_bf16 v[18:21], v[186:189], v[216:219], v[18:21]
	v_mfma_f32_16x16x32_bf16 v[6:9], v[178:181], v[224:227], v[6:9]
	v_mfma_f32_16x16x32_bf16 v[2:5], v[186:189], v[224:227], v[2:5]
	s_setprio 0
	s_barrier
	s_add_i32 s40, 0, 0x18000
	s_add_i32 s41, 0, 0x1c000
	v_add_u32_e32 v160, s40, v146
	v_add_u32_e32 v186, s41, v146
	ds_read_b128 v[148:151], v160
	ds_read_b128 v[152:155], v160 offset:1024
	ds_read_b128 v[156:159], v160 offset:2048
	ds_read_b128 v[160:163], v160 offset:3072
	ds_read_b128 v[164:167], v186
	ds_read_b128 v[178:181], v186 offset:1024
	ds_read_b128 v[182:185], v186 offset:2048
	ds_read_b128 v[186:189], v186 offset:3072
	s_add_u32 s18, s18, 0x80000
	s_addc_u32 s19, s19, 0
	s_mov_b32 m0, s28
	v_lshl_add_u64 v[232:233], s[18:19], 0, v[134:135]
	ds_read_b128 v[190:193], v147 offset:32768
	ds_read_b128 v[194:197], v147 offset:33792
	ds_read_b128 v[204:207], v147 offset:34816
	ds_read_b128 v[208:211], v147 offset:35840
	ds_read_b128 v[212:215], v147 offset:36864
	ds_read_b128 v[216:219], v147 offset:37888
	ds_read_b128 v[220:223], v147 offset:38912
	ds_read_b128 v[224:227], v147 offset:39936
	global_load_lds_dwordx4 v[232:233], off
	v_lshl_add_u64 v[232:233], s[18:19], 0, v[136:137]
	s_mov_b32 m0, s29
	s_nop 0
	global_load_lds_dwordx4 v[232:233], off
	s_waitcnt vmcnt(8)
	s_waitcnt lgkmcnt(0)
	s_barrier
	s_setprio 1
	s_waitcnt lgkmcnt(0)
	v_mfma_f32_16x16x32_bf16 v[130:133], v[148:151], v[190:193], v[130:133]
	v_mfma_f32_16x16x32_bf16 v[126:129], v[156:159], v[190:193], v[126:129]
	v_mfma_f32_16x16x32_bf16 v[122:125], v[148:151], v[204:207], v[122:125]
	v_mfma_f32_16x16x32_bf16 v[118:121], v[156:159], v[204:207], v[118:121]
	v_mfma_f32_16x16x32_bf16 v[94:97], v[148:151], v[212:215], v[94:97]
	v_mfma_f32_16x16x32_bf16 v[90:93], v[156:159], v[212:215], v[90:93]
	v_mfma_f32_16x16x32_bf16 v[78:81], v[148:151], v[220:223], v[78:81]
	v_mfma_f32_16x16x32_bf16 v[74:77], v[156:159], v[220:223], v[74:77]
	v_mfma_f32_16x16x32_bf16 v[130:133], v[152:155], v[194:197], v[130:133]
	v_mfma_f32_16x16x32_bf16 v[126:129], v[160:163], v[194:197], v[126:129]
	v_mfma_f32_16x16x32_bf16 v[122:125], v[152:155], v[208:211], v[122:125]
	v_mfma_f32_16x16x32_bf16 v[118:121], v[160:163], v[208:211], v[118:121]
	v_mfma_f32_16x16x32_bf16 v[94:97], v[152:155], v[216:219], v[94:97]
	v_mfma_f32_16x16x32_bf16 v[90:93], v[160:163], v[216:219], v[90:93]
	v_mfma_f32_16x16x32_bf16 v[78:81], v[152:155], v[224:227], v[78:81]
	v_mfma_f32_16x16x32_bf16 v[74:77], v[160:163], v[224:227], v[74:77]
	s_setprio 0
	s_setprio 1
	v_mfma_f32_16x16x32_bf16 v[114:117], v[164:167], v[190:193], v[114:117]
	v_mfma_f32_16x16x32_bf16 v[110:113], v[182:185], v[190:193], v[110:113]
	v_mfma_f32_16x16x32_bf16 v[106:109], v[164:167], v[204:207], v[106:109]
	v_mfma_f32_16x16x32_bf16 v[102:105], v[182:185], v[204:207], v[102:105]
	v_mfma_f32_16x16x32_bf16 v[86:89], v[164:167], v[212:215], v[86:89]
	v_mfma_f32_16x16x32_bf16 v[82:85], v[182:185], v[212:215], v[82:85]
	v_mfma_f32_16x16x32_bf16 v[70:73], v[164:167], v[220:223], v[70:73]
	v_mfma_f32_16x16x32_bf16 v[66:69], v[182:185], v[220:223], v[66:69]
	v_mfma_f32_16x16x32_bf16 v[114:117], v[178:181], v[194:197], v[114:117]
	v_mfma_f32_16x16x32_bf16 v[110:113], v[186:189], v[194:197], v[110:113]
	v_mfma_f32_16x16x32_bf16 v[106:109], v[178:181], v[208:211], v[106:109]
	v_mfma_f32_16x16x32_bf16 v[102:105], v[186:189], v[208:211], v[102:105]
	v_mfma_f32_16x16x32_bf16 v[86:89], v[178:181], v[216:219], v[86:89]
	v_mfma_f32_16x16x32_bf16 v[82:85], v[186:189], v[216:219], v[82:85]
	v_mfma_f32_16x16x32_bf16 v[70:73], v[178:181], v[224:227], v[70:73]
	v_mfma_f32_16x16x32_bf16 v[66:69], v[186:189], v[224:227], v[66:69]
	s_setprio 0
	s_barrier
	s_add_i32 s18, s40, s21
	v_lshl_add_u64 v[168:169], v[168:169], 0, s[84:85]
	s_mov_b32 m0, s18
	ds_read_b128 v[190:193], v147 offset:49152
	ds_read_b128 v[194:197], v147 offset:50176
	ds_read_b128 v[204:207], v147 offset:51200
	ds_read_b128 v[208:211], v147 offset:52224
	ds_read_b128 v[212:215], v147 offset:53248
	ds_read_b128 v[216:219], v147 offset:54272
	ds_read_b128 v[220:223], v147 offset:55296
	ds_read_b128 v[224:227], v147 offset:56320
	global_load_lds_dwordx4 v[168:169], off
	s_add_i32 m0, s18, 0x2000
	s_add_u32 s14, s14, 0x80080
	v_lshl_add_u64 v[168:169], v[198:199], 0, s[84:85]
	s_addc_u32 s15, s15, 0
	s_add_i32 s18, s41, s21
	global_load_lds_dwordx4 v[168:169], off
	v_lshl_add_u64 v[168:169], s[14:15], 0, v[172:173]
	s_mov_b32 m0, s18
	s_nop 0
	global_load_lds_dwordx4 v[168:169], off
	v_lshl_add_u64 v[168:169], s[14:15], 0, v[138:139]
	s_add_i32 m0, s18, 0x2000
	s_nop 0
	global_load_lds_dwordx4 v[168:169], off
	v_lshl_add_u64 v[168:169], v[228:229], 0, s[84:85]
	s_mov_b32 m0, s35
	s_nop 0
	global_load_lds_dwordx4 v[168:169], off
	v_lshl_add_u64 v[168:169], v[230:231], 0, s[84:85]
	s_mov_b32 m0, s38
	s_nop 0
	global_load_lds_dwordx4 v[168:169], off
	s_waitcnt vmcnt(8)
	s_waitcnt lgkmcnt(0)
	s_barrier
	s_setprio 1
	s_waitcnt lgkmcnt(0)
	v_mfma_f32_16x16x32_bf16 v[62:65], v[148:151], v[190:193], v[62:65]
	v_mfma_f32_16x16x32_bf16 v[58:61], v[156:159], v[190:193], v[58:61]
	v_mfma_f32_16x16x32_bf16 v[46:49], v[148:151], v[204:207], v[46:49]
	v_mfma_f32_16x16x32_bf16 v[42:45], v[156:159], v[204:207], v[42:45]
	v_mfma_f32_16x16x32_bf16 v[30:33], v[148:151], v[212:215], v[30:33]
	v_mfma_f32_16x16x32_bf16 v[26:29], v[156:159], v[212:215], v[26:29]
	v_mfma_f32_16x16x32_bf16 v[14:17], v[148:151], v[220:223], v[14:17]
	v_mfma_f32_16x16x32_bf16 v[10:13], v[156:159], v[220:223], v[10:13]
	v_mfma_f32_16x16x32_bf16 v[62:65], v[152:155], v[194:197], v[62:65]
	v_mfma_f32_16x16x32_bf16 v[58:61], v[160:163], v[194:197], v[58:61]
	v_mfma_f32_16x16x32_bf16 v[46:49], v[152:155], v[208:211], v[46:49]
	v_mfma_f32_16x16x32_bf16 v[42:45], v[160:163], v[208:211], v[42:45]
	v_mfma_f32_16x16x32_bf16 v[30:33], v[152:155], v[216:219], v[30:33]
	v_mfma_f32_16x16x32_bf16 v[26:29], v[160:163], v[216:219], v[26:29]
	v_mfma_f32_16x16x32_bf16 v[14:17], v[152:155], v[224:227], v[14:17]
	v_mfma_f32_16x16x32_bf16 v[10:13], v[160:163], v[224:227], v[10:13]
	s_setprio 0
	s_setprio 1
	v_mfma_f32_16x16x32_bf16 v[54:57], v[164:167], v[190:193], v[54:57]
	v_mfma_f32_16x16x32_bf16 v[50:53], v[182:185], v[190:193], v[50:53]
	v_mfma_f32_16x16x32_bf16 v[38:41], v[164:167], v[204:207], v[38:41]
	v_mfma_f32_16x16x32_bf16 v[34:37], v[182:185], v[204:207], v[34:37]
	v_mfma_f32_16x16x32_bf16 v[22:25], v[164:167], v[212:215], v[22:25]
	v_mfma_f32_16x16x32_bf16 v[18:21], v[182:185], v[212:215], v[18:21]
	v_mfma_f32_16x16x32_bf16 v[6:9], v[164:167], v[220:223], v[6:9]
	v_mfma_f32_16x16x32_bf16 v[2:5], v[182:185], v[220:223], v[2:5]
	v_mfma_f32_16x16x32_bf16 v[54:57], v[178:181], v[194:197], v[54:57]
	v_mfma_f32_16x16x32_bf16 v[50:53], v[186:189], v[194:197], v[50:53]
	v_mfma_f32_16x16x32_bf16 v[38:41], v[178:181], v[208:211], v[38:41]
	v_mfma_f32_16x16x32_bf16 v[34:37], v[186:189], v[208:211], v[34:37]
	v_mfma_f32_16x16x32_bf16 v[22:25], v[178:181], v[216:219], v[22:25]
	v_mfma_f32_16x16x32_bf16 v[18:21], v[186:189], v[216:219], v[18:21]
	v_mfma_f32_16x16x32_bf16 v[6:9], v[178:181], v[224:227], v[6:9]
	v_mfma_f32_16x16x32_bf16 v[2:5], v[186:189], v[224:227], v[2:5]
	s_add_i32 s39, s39, 2
	s_add_u32 s10, s10, 0x100
	s_addc_u32 s11, s11, 0
	s_cmp_gt_u32 s39, 29
	s_setprio 0
	s_barrier
	s_cbranch_scc0 .LBB0_1160
	s_cmpk_lt_u32 s20, 0x100
	s_cbranch_scc0 .LBB0_1163
	s_barrier

.LBB0_1169:
	s_add_u32 s14, s46, s10
	s_addc_u32 s15, s47, s11
	s_add_u32 s14, s14, 0x39400100
	s_addc_u32 s15, s15, 0
	s_add_u32 s40, s48, s10
	s_addc_u32 s41, s49, s11
	s_add_i32 s42, 0, 0x10000
	s_cmpk_eq_i32 s10, 0xf00
	s_cselect_b32 s19, s45, s15
	s_cselect_b32 s18, s44, s14
	s_cselect_b32 s15, s1, s41
	s_cselect_b32 s14, s0, s40
	s_add_i32 s43, 0, 0x14000
	v_add_u32_e32 v160, s42, v146
	v_add_u32_e32 v168, s43, v146
	ds_read_b128 v[148:151], v160
	ds_read_b128 v[152:155], v160 offset:1024
	ds_read_b128 v[156:159], v160 offset:2048
	ds_read_b128 v[160:163], v160 offset:3072
	ds_read_b128 v[164:167], v168
	ds_read_b128 v[178:181], v168 offset:1024
	ds_read_b128 v[182:185], v168 offset:2048
	ds_read_b128 v[186:189], v168 offset:3072
	v_lshl_add_u64 v[168:169], v[136:137], 0, s[10:11]
	s_add_i32 m0, s22, 0xc000
	ds_read_b128 v[190:193], v147
	ds_read_b128 v[194:197], v147 offset:1024
	ds_read_b128 v[204:207], v147 offset:2048
	ds_read_b128 v[208:211], v147 offset:3072
	ds_read_b128 v[212:215], v147 offset:4096
	ds_read_b128 v[216:219], v147 offset:5120
	ds_read_b128 v[220:223], v147 offset:6144
	ds_read_b128 v[224:227], v147 offset:7168
	global_load_lds_dwordx4 v[168:169], off
	v_lshl_add_u64 v[168:169], v[142:143], 0, s[10:11]
	s_add_i32 m0, s22, 0xe000
	s_nop 0
	global_load_lds_dwordx4 v[168:169], off
	s_waitcnt vmcnt(8)
	s_waitcnt lgkmcnt(0)
	s_barrier
	s_setprio 1
	s_waitcnt lgkmcnt(0)
	v_mfma_f32_16x16x32_bf16 v[138:141], v[148:151], v[190:193], v[138:141]
	v_mfma_f32_16x16x32_bf16 v[126:129], v[156:159], v[190:193], v[126:129]
	v_mfma_f32_16x16x32_bf16 v[114:117], v[148:151], v[204:207], v[114:117]
	v_mfma_f32_16x16x32_bf16 v[110:113], v[156:159], v[204:207], v[110:113]
	v_mfma_f32_16x16x32_bf16 v[94:97], v[148:151], v[212:215], v[94:97]
	v_mfma_f32_16x16x32_bf16 v[90:93], v[156:159], v[212:215], v[90:93]
	v_mfma_f32_16x16x32_bf16 v[78:81], v[148:151], v[220:223], v[78:81]
	v_mfma_f32_16x16x32_bf16 v[74:77], v[156:159], v[220:223], v[74:77]
	v_mfma_f32_16x16x32_bf16 v[138:141], v[152:155], v[194:197], v[138:141]
	v_mfma_f32_16x16x32_bf16 v[126:129], v[160:163], v[194:197], v[126:129]
	v_mfma_f32_16x16x32_bf16 v[114:117], v[152:155], v[208:211], v[114:117]
	v_mfma_f32_16x16x32_bf16 v[110:113], v[160:163], v[208:211], v[110:113]
	v_mfma_f32_16x16x32_bf16 v[94:97], v[152:155], v[216:219], v[94:97]
	v_mfma_f32_16x16x32_bf16 v[90:93], v[160:163], v[216:219], v[90:93]
	v_mfma_f32_16x16x32_bf16 v[78:81], v[152:155], v[224:227], v[78:81]
	v_mfma_f32_16x16x32_bf16 v[74:77], v[160:163], v[224:227], v[74:77]
	s_setprio 0
	s_setprio 1
	v_mfma_f32_16x16x32_bf16 v[122:125], v[164:167], v[190:193], v[122:125]
	v_mfma_f32_16x16x32_bf16 v[118:121], v[182:185], v[190:193], v[118:121]
	v_mfma_f32_16x16x32_bf16 v[106:109], v[164:167], v[204:207], v[106:109]
	v_mfma_f32_16x16x32_bf16 v[102:105], v[182:185], v[204:207], v[102:105]
	v_mfma_f32_16x16x32_bf16 v[86:89], v[164:167], v[212:215], v[86:89]
	v_mfma_f32_16x16x32_bf16 v[82:85], v[182:185], v[212:215], v[82:85]
	v_mfma_f32_16x16x32_bf16 v[70:73], v[164:167], v[220:223], v[70:73]
	v_mfma_f32_16x16x32_bf16 v[66:69], v[182:185], v[220:223], v[66:69]
	v_mfma_f32_16x16x32_bf16 v[122:125], v[178:181], v[194:197], v[122:125]
	v_mfma_f32_16x16x32_bf16 v[118:121], v[186:189], v[194:197], v[118:121]
	v_mfma_f32_16x16x32_bf16 v[106:109], v[178:181], v[208:211], v[106:109]
	v_mfma_f32_16x16x32_bf16 v[102:105], v[186:189], v[208:211], v[102:105]
	v_mfma_f32_16x16x32_bf16 v[86:89], v[178:181], v[216:219], v[86:89]
	v_mfma_f32_16x16x32_bf16 v[82:85], v[186:189], v[216:219], v[82:85]
	v_mfma_f32_16x16x32_bf16 v[70:73], v[178:181], v[224:227], v[70:73]
	v_mfma_f32_16x16x32_bf16 v[66:69], v[186:189], v[224:227], v[66:69]
	s_setprio 0
	s_barrier
	s_add_i32 s40, s42, s21
	v_lshl_add_u64 v[168:169], s[14:15], 0, v[172:173]
	s_mov_b32 m0, s40
	ds_read_b128 v[190:193], v147 offset:16384
	ds_read_b128 v[194:197], v147 offset:17408
	ds_read_b128 v[204:207], v147 offset:18432
	ds_read_b128 v[208:211], v147 offset:19456
	ds_read_b128 v[212:215], v147 offset:20480
	ds_read_b128 v[216:219], v147 offset:21504
	ds_read_b128 v[220:223], v147 offset:22528
	ds_read_b128 v[224:227], v147 offset:23552
	global_load_lds_dwordx4 v[168:169], off
	s_add_i32 m0, s40, 0x2000
	s_add_u32 s40, s14, 0x80000
	v_lshl_add_u64 v[198:199], s[14:15], 0, v[130:131]
	s_addc_u32 s41, s15, 0
	s_add_i32 s42, s43, s21
	global_load_lds_dwordx4 v[198:199], off
	v_lshl_add_u64 v[228:229], s[40:41], 0, v[172:173]
	s_mov_b32 m0, s42
	v_lshl_add_u64 v[230:231], s[18:19], 0, v[132:133]
	global_load_lds_dwordx4 v[228:229], off
	v_lshl_add_u64 v[228:229], s[40:41], 0, v[130:131]
	s_add_i32 m0, s42, 0x2000
	s_nop 0
	global_load_lds_dwordx4 v[228:229], off
	v_lshl_add_u64 v[228:229], s[18:19], 0, v[134:135]
	s_mov_b32 m0, s22
	s_nop 0
	global_load_lds_dwordx4 v[228:229], off
	s_mov_b32 m0, s23
	s_nop 0
	global_load_lds_dwordx4 v[230:231], off
	s_waitcnt vmcnt(8)
	s_waitcnt lgkmcnt(0)
	s_barrier
	s_setprio 1
	s_waitcnt lgkmcnt(0)
	v_mfma_f32_16x16x32_bf16 v[62:65], v[148:151], v[190:193], v[62:65]
	v_mfma_f32_16x16x32_bf16 v[58:61], v[156:159], v[190:193], v[58:61]
	v_mfma_f32_16x16x32_bf16 v[46:49], v[148:151], v[204:207], v[46:49]
	v_mfma_f32_16x16x32_bf16 v[42:45], v[156:159], v[204:207], v[42:45]
	v_mfma_f32_16x16x32_bf16 v[30:33], v[148:151], v[212:215], v[30:33]
	v_mfma_f32_16x16x32_bf16 v[26:29], v[156:159], v[212:215], v[26:29]
	v_mfma_f32_16x16x32_bf16 v[14:17], v[148:151], v[220:223], v[14:17]
	v_mfma_f32_16x16x32_bf16 v[10:13], v[156:159], v[220:223], v[10:13]
	v_mfma_f32_16x16x32_bf16 v[62:65], v[152:155], v[194:197], v[62:65]
	v_mfma_f32_16x16x32_bf16 v[58:61], v[160:163], v[194:197], v[58:61]
	v_mfma_f32_16x16x32_bf16 v[46:49], v[152:155], v[208:211], v[46:49]
	v_mfma_f32_16x16x32_bf16 v[42:45], v[160:163], v[208:211], v[42:45]
	v_mfma_f32_16x16x32_bf16 v[30:33], v[152:155], v[216:219], v[30:33]
	v_mfma_f32_16x16x32_bf16 v[26:29], v[160:163], v[216:219], v[26:29]
	v_mfma_f32_16x16x32_bf16 v[14:17], v[152:155], v[224:227], v[14:17]
	v_mfma_f32_16x16x32_bf16 v[10:13], v[160:163], v[224:227], v[10:13]
	s_setprio 0
	s_setprio 1
	v_mfma_f32_16x16x32_bf16 v[54:57], v[164:167], v[190:193], v[54:57]
	v_mfma_f32_16x16x32_bf16 v[50:53], v[182:185], v[190:193], v[50:53]
	v_mfma_f32_16x16x32_bf16 v[38:41], v[164:167], v[204:207], v[38:41]
	v_mfma_f32_16x16x32_bf16 v[34:37], v[182:185], v[204:207], v[34:37]
	v_mfma_f32_16x16x32_bf16 v[22:25], v[164:167], v[212:215], v[22:25]
	v_mfma_f32_16x16x32_bf16 v[18:21], v[182:185], v[212:215], v[18:21]
	v_mfma_f32_16x16x32_bf16 v[6:9], v[164:167], v[220:223], v[6:9]
	v_mfma_f32_16x16x32_bf16 v[2:5], v[182:185], v[220:223], v[2:5]
	v_mfma_f32_16x16x32_bf16 v[54:57], v[178:181], v[194:197], v[54:57]
	v_mfma_f32_16x16x32_bf16 v[50:53], v[186:189], v[194:197], v[50:53]
	v_mfma_f32_16x16x32_bf16 v[38:41], v[178:181], v[208:211], v[38:41]
	v_mfma_f32_16x16x32_bf16 v[34:37], v[186:189], v[208:211], v[34:37]
	v_mfma_f32_16x16x32_bf16 v[22:25], v[178:181], v[216:219], v[22:25]
	v_mfma_f32_16x16x32_bf16 v[18:21], v[186:189], v[216:219], v[18:21]
	v_mfma_f32_16x16x32_bf16 v[6:9], v[178:181], v[224:227], v[6:9]
	v_mfma_f32_16x16x32_bf16 v[2:5], v[186:189], v[224:227], v[2:5]
	s_setprio 0
	s_barrier
	s_add_i32 s40, 0, 0x18000
	s_add_i32 s41, 0, 0x1c000
	v_add_u32_e32 v160, s40, v146
	v_add_u32_e32 v186, s41, v146
	ds_read_b128 v[148:151], v160
	ds_read_b128 v[152:155], v160 offset:1024
	ds_read_b128 v[156:159], v160 offset:2048
	ds_read_b128 v[160:163], v160 offset:3072
	ds_read_b128 v[164:167], v186
	ds_read_b128 v[178:181], v186 offset:1024
	ds_read_b128 v[182:185], v186 offset:2048
	ds_read_b128 v[186:189], v186 offset:3072
	s_add_u32 s18, s18, 0x80000
	s_addc_u32 s19, s19, 0
	s_mov_b32 m0, s28
	v_lshl_add_u64 v[232:233], s[18:19], 0, v[134:135]
	ds_read_b128 v[190:193], v147 offset:32768
	ds_read_b128 v[194:197], v147 offset:33792
	ds_read_b128 v[204:207], v147 offset:34816
	ds_read_b128 v[208:211], v147 offset:35840
	ds_read_b128 v[212:215], v147 offset:36864
	ds_read_b128 v[216:219], v147 offset:37888
	ds_read_b128 v[220:223], v147 offset:38912
	ds_read_b128 v[224:227], v147 offset:39936
	global_load_lds_dwordx4 v[232:233], off
	v_lshl_add_u64 v[232:233], s[18:19], 0, v[132:133]
	s_mov_b32 m0, s29
	s_nop 0
	global_load_lds_dwordx4 v[232:233], off
	s_waitcnt vmcnt(8)
	s_waitcnt lgkmcnt(0)
	s_barrier
	s_setprio 1
	s_waitcnt lgkmcnt(0)
	v_mfma_f32_16x16x32_bf16 v[138:141], v[148:151], v[190:193], v[138:141]
	v_mfma_f32_16x16x32_bf16 v[126:129], v[156:159], v[190:193], v[126:129]
	v_mfma_f32_16x16x32_bf16 v[114:117], v[148:151], v[204:207], v[114:117]
	v_mfma_f32_16x16x32_bf16 v[110:113], v[156:159], v[204:207], v[110:113]
	v_mfma_f32_16x16x32_bf16 v[94:97], v[148:151], v[212:215], v[94:97]
	v_mfma_f32_16x16x32_bf16 v[90:93], v[156:159], v[212:215], v[90:93]
	v_mfma_f32_16x16x32_bf16 v[78:81], v[148:151], v[220:223], v[78:81]
	v_mfma_f32_16x16x32_bf16 v[74:77], v[156:159], v[220:223], v[74:77]
	v_mfma_f32_16x16x32_bf16 v[138:141], v[152:155], v[194:197], v[138:141]
	v_mfma_f32_16x16x32_bf16 v[126:129], v[160:163], v[194:197], v[126:129]
	v_mfma_f32_16x16x32_bf16 v[114:117], v[152:155], v[208:211], v[114:117]
	v_mfma_f32_16x16x32_bf16 v[110:113], v[160:163], v[208:211], v[110:113]
	v_mfma_f32_16x16x32_bf16 v[94:97], v[152:155], v[216:219], v[94:97]
	v_mfma_f32_16x16x32_bf16 v[90:93], v[160:163], v[216:219], v[90:93]
	v_mfma_f32_16x16x32_bf16 v[78:81], v[152:155], v[224:227], v[78:81]
	v_mfma_f32_16x16x32_bf16 v[74:77], v[160:163], v[224:227], v[74:77]
	s_setprio 0
	s_setprio 1
	v_mfma_f32_16x16x32_bf16 v[122:125], v[164:167], v[190:193], v[122:125]
	v_mfma_f32_16x16x32_bf16 v[118:121], v[182:185], v[190:193], v[118:121]
	v_mfma_f32_16x16x32_bf16 v[106:109], v[164:167], v[204:207], v[106:109]
	v_mfma_f32_16x16x32_bf16 v[102:105], v[182:185], v[204:207], v[102:105]
	v_mfma_f32_16x16x32_bf16 v[86:89], v[164:167], v[212:215], v[86:89]
	v_mfma_f32_16x16x32_bf16 v[82:85], v[182:185], v[212:215], v[82:85]
	v_mfma_f32_16x16x32_bf16 v[70:73], v[164:167], v[220:223], v[70:73]
	v_mfma_f32_16x16x32_bf16 v[66:69], v[182:185], v[220:223], v[66:69]
	v_mfma_f32_16x16x32_bf16 v[122:125], v[178:181], v[194:197], v[122:125]
	v_mfma_f32_16x16x32_bf16 v[118:121], v[186:189], v[194:197], v[118:121]
	v_mfma_f32_16x16x32_bf16 v[106:109], v[178:181], v[208:211], v[106:109]
	v_mfma_f32_16x16x32_bf16 v[102:105], v[186:189], v[208:211], v[102:105]
	v_mfma_f32_16x16x32_bf16 v[86:89], v[178:181], v[216:219], v[86:89]
	v_mfma_f32_16x16x32_bf16 v[82:85], v[186:189], v[216:219], v[82:85]
	v_mfma_f32_16x16x32_bf16 v[70:73], v[178:181], v[224:227], v[70:73]
	v_mfma_f32_16x16x32_bf16 v[66:69], v[186:189], v[224:227], v[66:69]
	s_setprio 0
	s_barrier
	s_add_i32 s18, s40, s21
	v_lshl_add_u64 v[168:169], v[168:169], 0, s[84:85]
	s_mov_b32 m0, s18
	ds_read_b128 v[190:193], v147 offset:49152
	ds_read_b128 v[194:197], v147 offset:50176
	ds_read_b128 v[204:207], v147 offset:51200
	ds_read_b128 v[208:211], v147 offset:52224
	ds_read_b128 v[212:215], v147 offset:53248
	ds_read_b128 v[216:219], v147 offset:54272
	ds_read_b128 v[220:223], v147 offset:55296
	ds_read_b128 v[224:227], v147 offset:56320
	global_load_lds_dwordx4 v[168:169], off
	s_add_i32 m0, s18, 0x2000
	s_add_u32 s14, s14, 0x80080
	v_lshl_add_u64 v[168:169], v[198:199], 0, s[84:85]
	s_addc_u32 s15, s15, 0
	s_add_i32 s18, s41, s21
	global_load_lds_dwordx4 v[168:169], off
	v_lshl_add_u64 v[168:169], s[14:15], 0, v[172:173]
	s_mov_b32 m0, s18
	s_nop 0
	global_load_lds_dwordx4 v[168:169], off
	v_lshl_add_u64 v[168:169], s[14:15], 0, v[130:131]
	s_add_i32 m0, s18, 0x2000
	s_nop 0
	global_load_lds_dwordx4 v[168:169], off
	v_lshl_add_u64 v[168:169], v[228:229], 0, s[84:85]
	s_mov_b32 m0, s35
	s_nop 0
	global_load_lds_dwordx4 v[168:169], off
	v_lshl_add_u64 v[168:169], v[230:231], 0, s[84:85]
	s_mov_b32 m0, s38
	s_nop 0
	global_load_lds_dwordx4 v[168:169], off
	s_waitcnt vmcnt(8)
	s_waitcnt lgkmcnt(0)
	s_barrier
	s_setprio 1
	s_waitcnt lgkmcnt(0)
	v_mfma_f32_16x16x32_bf16 v[62:65], v[148:151], v[190:193], v[62:65]
	v_mfma_f32_16x16x32_bf16 v[58:61], v[156:159], v[190:193], v[58:61]
	v_mfma_f32_16x16x32_bf16 v[46:49], v[148:151], v[204:207], v[46:49]
	v_mfma_f32_16x16x32_bf16 v[42:45], v[156:159], v[204:207], v[42:45]
	v_mfma_f32_16x16x32_bf16 v[30:33], v[148:151], v[212:215], v[30:33]
	v_mfma_f32_16x16x32_bf16 v[26:29], v[156:159], v[212:215], v[26:29]
	v_mfma_f32_16x16x32_bf16 v[14:17], v[148:151], v[220:223], v[14:17]
	v_mfma_f32_16x16x32_bf16 v[10:13], v[156:159], v[220:223], v[10:13]
	v_mfma_f32_16x16x32_bf16 v[62:65], v[152:155], v[194:197], v[62:65]
	v_mfma_f32_16x16x32_bf16 v[58:61], v[160:163], v[194:197], v[58:61]
	v_mfma_f32_16x16x32_bf16 v[46:49], v[152:155], v[208:211], v[46:49]
	v_mfma_f32_16x16x32_bf16 v[42:45], v[160:163], v[208:211], v[42:45]
	v_mfma_f32_16x16x32_bf16 v[30:33], v[152:155], v[216:219], v[30:33]
	v_mfma_f32_16x16x32_bf16 v[26:29], v[160:163], v[216:219], v[26:29]
	v_mfma_f32_16x16x32_bf16 v[14:17], v[152:155], v[224:227], v[14:17]
	v_mfma_f32_16x16x32_bf16 v[10:13], v[160:163], v[224:227], v[10:13]
	s_setprio 0
	s_setprio 1
	v_mfma_f32_16x16x32_bf16 v[54:57], v[164:167], v[190:193], v[54:57]
	v_mfma_f32_16x16x32_bf16 v[50:53], v[182:185], v[190:193], v[50:53]
	v_mfma_f32_16x16x32_bf16 v[38:41], v[164:167], v[204:207], v[38:41]
	v_mfma_f32_16x16x32_bf16 v[34:37], v[182:185], v[204:207], v[34:37]
	v_mfma_f32_16x16x32_bf16 v[22:25], v[164:167], v[212:215], v[22:25]
	v_mfma_f32_16x16x32_bf16 v[18:21], v[182:185], v[212:215], v[18:21]
	v_mfma_f32_16x16x32_bf16 v[6:9], v[164:167], v[220:223], v[6:9]
	v_mfma_f32_16x16x32_bf16 v[2:5], v[182:185], v[220:223], v[2:5]
	v_mfma_f32_16x16x32_bf16 v[54:57], v[178:181], v[194:197], v[54:57]
	v_mfma_f32_16x16x32_bf16 v[50:53], v[186:189], v[194:197], v[50:53]
	v_mfma_f32_16x16x32_bf16 v[38:41], v[178:181], v[208:211], v[38:41]
	v_mfma_f32_16x16x32_bf16 v[34:37], v[186:189], v[208:211], v[34:37]
	v_mfma_f32_16x16x32_bf16 v[22:25], v[178:181], v[216:219], v[22:25]
	v_mfma_f32_16x16x32_bf16 v[18:21], v[186:189], v[216:219], v[18:21]
	v_mfma_f32_16x16x32_bf16 v[6:9], v[178:181], v[224:227], v[6:9]
	v_mfma_f32_16x16x32_bf16 v[2:5], v[186:189], v[224:227], v[2:5]
	s_add_i32 s39, s39, 2
	s_add_u32 s10, s10, 0x100
	s_addc_u32 s11, s11, 0
	s_cmp_gt_u32 s39, 29
	s_setprio 0
	s_barrier
	s_cbranch_scc0 .LBB0_1169
	s_cmpk_lt_u32 s20, 0x100
	s_cbranch_scc0 .LBB0_1172
	s_barrier

.LBB0_1349:
	s_add_u32 s14, s46, s10
	s_addc_u32 s15, s47, s11
	s_add_u32 s14, s14, 0x39400100
	s_addc_u32 s15, s15, 0
	s_add_u32 s40, s48, s10
	s_addc_u32 s41, s49, s11
	s_add_i32 s42, 0, 0x10000
	s_cmpk_eq_i32 s10, 0xf00
	s_cselect_b32 s19, s45, s15
	s_cselect_b32 s18, s44, s14
	s_cselect_b32 s15, s1, s41
	s_cselect_b32 s14, s0, s40
	s_add_i32 s43, 0, 0x14000
	v_add_u32_e32 v160, s42, v146
	v_add_u32_e32 v168, s43, v146
	ds_read_b128 v[148:151], v160
	ds_read_b128 v[152:155], v160 offset:1024
	ds_read_b128 v[156:159], v160 offset:2048
	ds_read_b128 v[160:163], v160 offset:3072
	ds_read_b128 v[164:167], v168
	ds_read_b128 v[178:181], v168 offset:1024
	ds_read_b128 v[182:185], v168 offset:2048
	ds_read_b128 v[186:189], v168 offset:3072
	v_lshl_add_u64 v[168:169], v[136:137], 0, s[10:11]
	s_add_i32 m0, s22, 0xc000
	ds_read_b128 v[190:193], v147
	ds_read_b128 v[194:197], v147 offset:1024
	ds_read_b128 v[204:207], v147 offset:2048
	ds_read_b128 v[208:211], v147 offset:3072
	ds_read_b128 v[212:215], v147 offset:4096
	ds_read_b128 v[216:219], v147 offset:5120
	ds_read_b128 v[220:223], v147 offset:6144
	ds_read_b128 v[224:227], v147 offset:7168
	global_load_lds_dwordx4 v[168:169], off
	v_lshl_add_u64 v[168:169], v[142:143], 0, s[10:11]
	s_add_i32 m0, s22, 0xe000
	s_nop 0
	global_load_lds_dwordx4 v[168:169], off
	s_waitcnt vmcnt(8)
	s_waitcnt lgkmcnt(0)
	s_barrier
	s_setprio 1
	s_waitcnt lgkmcnt(0)
	v_mfma_f32_16x16x32_bf16 v[138:141], v[148:151], v[190:193], v[138:141]
	v_mfma_f32_16x16x32_bf16 v[126:129], v[156:159], v[190:193], v[126:129]
	v_mfma_f32_16x16x32_bf16 v[114:117], v[148:151], v[204:207], v[114:117]
	v_mfma_f32_16x16x32_bf16 v[110:113], v[156:159], v[204:207], v[110:113]
	v_mfma_f32_16x16x32_bf16 v[94:97], v[148:151], v[212:215], v[94:97]
	v_mfma_f32_16x16x32_bf16 v[90:93], v[156:159], v[212:215], v[90:93]
	v_mfma_f32_16x16x32_bf16 v[78:81], v[148:151], v[220:223], v[78:81]
	v_mfma_f32_16x16x32_bf16 v[74:77], v[156:159], v[220:223], v[74:77]
	v_mfma_f32_16x16x32_bf16 v[138:141], v[152:155], v[194:197], v[138:141]
	v_mfma_f32_16x16x32_bf16 v[126:129], v[160:163], v[194:197], v[126:129]
	v_mfma_f32_16x16x32_bf16 v[114:117], v[152:155], v[208:211], v[114:117]
	v_mfma_f32_16x16x32_bf16 v[110:113], v[160:163], v[208:211], v[110:113]
	v_mfma_f32_16x16x32_bf16 v[94:97], v[152:155], v[216:219], v[94:97]
	v_mfma_f32_16x16x32_bf16 v[90:93], v[160:163], v[216:219], v[90:93]
	v_mfma_f32_16x16x32_bf16 v[78:81], v[152:155], v[224:227], v[78:81]
	v_mfma_f32_16x16x32_bf16 v[74:77], v[160:163], v[224:227], v[74:77]
	s_setprio 0
	s_setprio 1
	v_mfma_f32_16x16x32_bf16 v[122:125], v[164:167], v[190:193], v[122:125]
	v_mfma_f32_16x16x32_bf16 v[118:121], v[182:185], v[190:193], v[118:121]
	v_mfma_f32_16x16x32_bf16 v[106:109], v[164:167], v[204:207], v[106:109]
	v_mfma_f32_16x16x32_bf16 v[102:105], v[182:185], v[204:207], v[102:105]
	v_mfma_f32_16x16x32_bf16 v[86:89], v[164:167], v[212:215], v[86:89]
	v_mfma_f32_16x16x32_bf16 v[82:85], v[182:185], v[212:215], v[82:85]
	v_mfma_f32_16x16x32_bf16 v[70:73], v[164:167], v[220:223], v[70:73]
	v_mfma_f32_16x16x32_bf16 v[66:69], v[182:185], v[220:223], v[66:69]
	v_mfma_f32_16x16x32_bf16 v[122:125], v[178:181], v[194:197], v[122:125]
	v_mfma_f32_16x16x32_bf16 v[118:121], v[186:189], v[194:197], v[118:121]
	v_mfma_f32_16x16x32_bf16 v[106:109], v[178:181], v[208:211], v[106:109]
	v_mfma_f32_16x16x32_bf16 v[102:105], v[186:189], v[208:211], v[102:105]
	v_mfma_f32_16x16x32_bf16 v[86:89], v[178:181], v[216:219], v[86:89]
	v_mfma_f32_16x16x32_bf16 v[82:85], v[186:189], v[216:219], v[82:85]
	v_mfma_f32_16x16x32_bf16 v[70:73], v[178:181], v[224:227], v[70:73]
	v_mfma_f32_16x16x32_bf16 v[66:69], v[186:189], v[224:227], v[66:69]
	s_setprio 0
	s_barrier
	s_add_i32 s40, s42, s21
	v_lshl_add_u64 v[168:169], s[14:15], 0, v[172:173]
	s_mov_b32 m0, s40
	ds_read_b128 v[190:193], v147 offset:16384
	ds_read_b128 v[194:197], v147 offset:17408
	ds_read_b128 v[204:207], v147 offset:18432
	ds_read_b128 v[208:211], v147 offset:19456
	ds_read_b128 v[212:215], v147 offset:20480
	ds_read_b128 v[216:219], v147 offset:21504
	ds_read_b128 v[220:223], v147 offset:22528
	ds_read_b128 v[224:227], v147 offset:23552
	global_load_lds_dwordx4 v[168:169], off
	s_add_i32 m0, s40, 0x2000
	s_add_u32 s40, s14, 0x80000
	v_lshl_add_u64 v[198:199], s[14:15], 0, v[134:135]
	s_addc_u32 s41, s15, 0
	s_add_i32 s42, s43, s21
	global_load_lds_dwordx4 v[198:199], off
	v_lshl_add_u64 v[228:229], s[40:41], 0, v[172:173]
	s_mov_b32 m0, s42
	v_lshl_add_u64 v[230:231], s[18:19], 0, v[132:133]
	global_load_lds_dwordx4 v[228:229], off
	v_lshl_add_u64 v[228:229], s[40:41], 0, v[134:135]
	s_add_i32 m0, s42, 0x2000
	s_nop 0
	global_load_lds_dwordx4 v[228:229], off
	v_lshl_add_u64 v[228:229], s[18:19], 0, v[130:131]
	s_mov_b32 m0, s22
	s_nop 0
	global_load_lds_dwordx4 v[228:229], off
	s_mov_b32 m0, s23
	s_nop 0
	global_load_lds_dwordx4 v[230:231], off
	s_waitcnt vmcnt(8)
	s_waitcnt lgkmcnt(0)
	s_barrier
	s_setprio 1
	s_waitcnt lgkmcnt(0)
	v_mfma_f32_16x16x32_bf16 v[62:65], v[148:151], v[190:193], v[62:65]
	v_mfma_f32_16x16x32_bf16 v[58:61], v[156:159], v[190:193], v[58:61]
	v_mfma_f32_16x16x32_bf16 v[46:49], v[148:151], v[204:207], v[46:49]
	v_mfma_f32_16x16x32_bf16 v[42:45], v[156:159], v[204:207], v[42:45]
	v_mfma_f32_16x16x32_bf16 v[30:33], v[148:151], v[212:215], v[30:33]
	v_mfma_f32_16x16x32_bf16 v[26:29], v[156:159], v[212:215], v[26:29]
	v_mfma_f32_16x16x32_bf16 v[14:17], v[148:151], v[220:223], v[14:17]
	v_mfma_f32_16x16x32_bf16 v[10:13], v[156:159], v[220:223], v[10:13]
	v_mfma_f32_16x16x32_bf16 v[62:65], v[152:155], v[194:197], v[62:65]
	v_mfma_f32_16x16x32_bf16 v[58:61], v[160:163], v[194:197], v[58:61]
	v_mfma_f32_16x16x32_bf16 v[46:49], v[152:155], v[208:211], v[46:49]
	v_mfma_f32_16x16x32_bf16 v[42:45], v[160:163], v[208:211], v[42:45]
	v_mfma_f32_16x16x32_bf16 v[30:33], v[152:155], v[216:219], v[30:33]
	v_mfma_f32_16x16x32_bf16 v[26:29], v[160:163], v[216:219], v[26:29]
	v_mfma_f32_16x16x32_bf16 v[14:17], v[152:155], v[224:227], v[14:17]
	v_mfma_f32_16x16x32_bf16 v[10:13], v[160:163], v[224:227], v[10:13]
	s_setprio 0
	s_setprio 1
	v_mfma_f32_16x16x32_bf16 v[54:57], v[164:167], v[190:193], v[54:57]
	v_mfma_f32_16x16x32_bf16 v[50:53], v[182:185], v[190:193], v[50:53]
	v_mfma_f32_16x16x32_bf16 v[38:41], v[164:167], v[204:207], v[38:41]
	v_mfma_f32_16x16x32_bf16 v[34:37], v[182:185], v[204:207], v[34:37]
	v_mfma_f32_16x16x32_bf16 v[22:25], v[164:167], v[212:215], v[22:25]
	v_mfma_f32_16x16x32_bf16 v[18:21], v[182:185], v[212:215], v[18:21]
	v_mfma_f32_16x16x32_bf16 v[6:9], v[164:167], v[220:223], v[6:9]
	v_mfma_f32_16x16x32_bf16 v[2:5], v[182:185], v[220:223], v[2:5]
	v_mfma_f32_16x16x32_bf16 v[54:57], v[178:181], v[194:197], v[54:57]
	v_mfma_f32_16x16x32_bf16 v[50:53], v[186:189], v[194:197], v[50:53]
	v_mfma_f32_16x16x32_bf16 v[38:41], v[178:181], v[208:211], v[38:41]
	v_mfma_f32_16x16x32_bf16 v[34:37], v[186:189], v[208:211], v[34:37]
	v_mfma_f32_16x16x32_bf16 v[22:25], v[178:181], v[216:219], v[22:25]
	v_mfma_f32_16x16x32_bf16 v[18:21], v[186:189], v[216:219], v[18:21]
	v_mfma_f32_16x16x32_bf16 v[6:9], v[178:181], v[224:227], v[6:9]
	v_mfma_f32_16x16x32_bf16 v[2:5], v[186:189], v[224:227], v[2:5]
	s_setprio 0
	s_barrier
	s_add_i32 s40, 0, 0x18000
	s_add_i32 s41, 0, 0x1c000
	v_add_u32_e32 v160, s40, v146
	v_add_u32_e32 v186, s41, v146
	ds_read_b128 v[148:151], v160
	ds_read_b128 v[152:155], v160 offset:1024
	ds_read_b128 v[156:159], v160 offset:2048
	ds_read_b128 v[160:163], v160 offset:3072
	ds_read_b128 v[164:167], v186
	ds_read_b128 v[178:181], v186 offset:1024
	ds_read_b128 v[182:185], v186 offset:2048
	ds_read_b128 v[186:189], v186 offset:3072
	s_add_u32 s18, s18, 0x80000
	s_addc_u32 s19, s19, 0
	s_mov_b32 m0, s28
	v_lshl_add_u64 v[232:233], s[18:19], 0, v[130:131]
	ds_read_b128 v[190:193], v147 offset:32768
	ds_read_b128 v[194:197], v147 offset:33792
	ds_read_b128 v[204:207], v147 offset:34816
	ds_read_b128 v[208:211], v147 offset:35840
	ds_read_b128 v[212:215], v147 offset:36864
	ds_read_b128 v[216:219], v147 offset:37888
	ds_read_b128 v[220:223], v147 offset:38912
	ds_read_b128 v[224:227], v147 offset:39936
	global_load_lds_dwordx4 v[232:233], off
	v_lshl_add_u64 v[232:233], s[18:19], 0, v[132:133]
	s_mov_b32 m0, s29
	s_nop 0
	global_load_lds_dwordx4 v[232:233], off
	s_waitcnt vmcnt(8)
	s_waitcnt lgkmcnt(0)
	s_barrier
	s_setprio 1
	s_waitcnt lgkmcnt(0)
	v_mfma_f32_16x16x32_bf16 v[138:141], v[148:151], v[190:193], v[138:141]
	v_mfma_f32_16x16x32_bf16 v[126:129], v[156:159], v[190:193], v[126:129]
	v_mfma_f32_16x16x32_bf16 v[114:117], v[148:151], v[204:207], v[114:117]
	v_mfma_f32_16x16x32_bf16 v[110:113], v[156:159], v[204:207], v[110:113]
	v_mfma_f32_16x16x32_bf16 v[94:97], v[148:151], v[212:215], v[94:97]
	v_mfma_f32_16x16x32_bf16 v[90:93], v[156:159], v[212:215], v[90:93]
	v_mfma_f32_16x16x32_bf16 v[78:81], v[148:151], v[220:223], v[78:81]
	v_mfma_f32_16x16x32_bf16 v[74:77], v[156:159], v[220:223], v[74:77]
	v_mfma_f32_16x16x32_bf16 v[138:141], v[152:155], v[194:197], v[138:141]
	v_mfma_f32_16x16x32_bf16 v[126:129], v[160:163], v[194:197], v[126:129]
	v_mfma_f32_16x16x32_bf16 v[114:117], v[152:155], v[208:211], v[114:117]
	v_mfma_f32_16x16x32_bf16 v[110:113], v[160:163], v[208:211], v[110:113]
	v_mfma_f32_16x16x32_bf16 v[94:97], v[152:155], v[216:219], v[94:97]
	v_mfma_f32_16x16x32_bf16 v[90:93], v[160:163], v[216:219], v[90:93]
	v_mfma_f32_16x16x32_bf16 v[78:81], v[152:155], v[224:227], v[78:81]
	v_mfma_f32_16x16x32_bf16 v[74:77], v[160:163], v[224:227], v[74:77]
	s_setprio 0
	s_setprio 1
	v_mfma_f32_16x16x32_bf16 v[122:125], v[164:167], v[190:193], v[122:125]
	v_mfma_f32_16x16x32_bf16 v[118:121], v[182:185], v[190:193], v[118:121]
	v_mfma_f32_16x16x32_bf16 v[106:109], v[164:167], v[204:207], v[106:109]
	v_mfma_f32_16x16x32_bf16 v[102:105], v[182:185], v[204:207], v[102:105]
	v_mfma_f32_16x16x32_bf16 v[86:89], v[164:167], v[212:215], v[86:89]
	v_mfma_f32_16x16x32_bf16 v[82:85], v[182:185], v[212:215], v[82:85]
	v_mfma_f32_16x16x32_bf16 v[70:73], v[164:167], v[220:223], v[70:73]
	v_mfma_f32_16x16x32_bf16 v[66:69], v[182:185], v[220:223], v[66:69]
	v_mfma_f32_16x16x32_bf16 v[122:125], v[178:181], v[194:197], v[122:125]
	v_mfma_f32_16x16x32_bf16 v[118:121], v[186:189], v[194:197], v[118:121]
	v_mfma_f32_16x16x32_bf16 v[106:109], v[178:181], v[208:211], v[106:109]
	v_mfma_f32_16x16x32_bf16 v[102:105], v[186:189], v[208:211], v[102:105]
	v_mfma_f32_16x16x32_bf16 v[86:89], v[178:181], v[216:219], v[86:89]
	v_mfma_f32_16x16x32_bf16 v[82:85], v[186:189], v[216:219], v[82:85]
	v_mfma_f32_16x16x32_bf16 v[70:73], v[178:181], v[224:227], v[70:73]
	v_mfma_f32_16x16x32_bf16 v[66:69], v[186:189], v[224:227], v[66:69]
	s_setprio 0
	s_barrier
	s_add_i32 s18, s40, s21
	v_lshl_add_u64 v[168:169], v[168:169], 0, s[84:85]
	s_mov_b32 m0, s18
	ds_read_b128 v[190:193], v147 offset:49152
	ds_read_b128 v[194:197], v147 offset:50176
	ds_read_b128 v[204:207], v147 offset:51200
	ds_read_b128 v[208:211], v147 offset:52224
	ds_read_b128 v[212:215], v147 offset:53248
	ds_read_b128 v[216:219], v147 offset:54272
	ds_read_b128 v[220:223], v147 offset:55296
	ds_read_b128 v[224:227], v147 offset:56320
	global_load_lds_dwordx4 v[168:169], off
	s_add_i32 m0, s18, 0x2000
	s_add_u32 s14, s14, 0x80080
	v_lshl_add_u64 v[168:169], v[198:199], 0, s[84:85]
	s_addc_u32 s15, s15, 0
	s_add_i32 s18, s41, s21
	global_load_lds_dwordx4 v[168:169], off
	v_lshl_add_u64 v[168:169], s[14:15], 0, v[172:173]
	s_mov_b32 m0, s18
	s_nop 0
	global_load_lds_dwordx4 v[168:169], off
	v_lshl_add_u64 v[168:169], s[14:15], 0, v[134:135]
	s_add_i32 m0, s18, 0x2000
	s_nop 0
	global_load_lds_dwordx4 v[168:169], off
	v_lshl_add_u64 v[168:169], v[228:229], 0, s[84:85]
	s_mov_b32 m0, s35
	s_nop 0
	global_load_lds_dwordx4 v[168:169], off
	v_lshl_add_u64 v[168:169], v[230:231], 0, s[84:85]
	s_mov_b32 m0, s38
	s_nop 0
	global_load_lds_dwordx4 v[168:169], off
	s_waitcnt vmcnt(8)
	s_waitcnt lgkmcnt(0)
	s_barrier
	s_setprio 1
	s_waitcnt lgkmcnt(0)
	v_mfma_f32_16x16x32_bf16 v[62:65], v[148:151], v[190:193], v[62:65]
	v_mfma_f32_16x16x32_bf16 v[58:61], v[156:159], v[190:193], v[58:61]
	v_mfma_f32_16x16x32_bf16 v[46:49], v[148:151], v[204:207], v[46:49]
	v_mfma_f32_16x16x32_bf16 v[42:45], v[156:159], v[204:207], v[42:45]
	v_mfma_f32_16x16x32_bf16 v[30:33], v[148:151], v[212:215], v[30:33]
	v_mfma_f32_16x16x32_bf16 v[26:29], v[156:159], v[212:215], v[26:29]
	v_mfma_f32_16x16x32_bf16 v[14:17], v[148:151], v[220:223], v[14:17]
	v_mfma_f32_16x16x32_bf16 v[10:13], v[156:159], v[220:223], v[10:13]
	v_mfma_f32_16x16x32_bf16 v[62:65], v[152:155], v[194:197], v[62:65]
	v_mfma_f32_16x16x32_bf16 v[58:61], v[160:163], v[194:197], v[58:61]
	v_mfma_f32_16x16x32_bf16 v[46:49], v[152:155], v[208:211], v[46:49]
	v_mfma_f32_16x16x32_bf16 v[42:45], v[160:163], v[208:211], v[42:45]
	v_mfma_f32_16x16x32_bf16 v[30:33], v[152:155], v[216:219], v[30:33]
	v_mfma_f32_16x16x32_bf16 v[26:29], v[160:163], v[216:219], v[26:29]
	v_mfma_f32_16x16x32_bf16 v[14:17], v[152:155], v[224:227], v[14:17]
	v_mfma_f32_16x16x32_bf16 v[10:13], v[160:163], v[224:227], v[10:13]
	s_setprio 0
	s_setprio 1
	v_mfma_f32_16x16x32_bf16 v[54:57], v[164:167], v[190:193], v[54:57]
	v_mfma_f32_16x16x32_bf16 v[50:53], v[182:185], v[190:193], v[50:53]
	v_mfma_f32_16x16x32_bf16 v[38:41], v[164:167], v[204:207], v[38:41]
	v_mfma_f32_16x16x32_bf16 v[34:37], v[182:185], v[204:207], v[34:37]
	v_mfma_f32_16x16x32_bf16 v[22:25], v[164:167], v[212:215], v[22:25]
	v_mfma_f32_16x16x32_bf16 v[18:21], v[182:185], v[212:215], v[18:21]
	v_mfma_f32_16x16x32_bf16 v[6:9], v[164:167], v[220:223], v[6:9]
	v_mfma_f32_16x16x32_bf16 v[2:5], v[182:185], v[220:223], v[2:5]
	v_mfma_f32_16x16x32_bf16 v[54:57], v[178:181], v[194:197], v[54:57]
	v_mfma_f32_16x16x32_bf16 v[50:53], v[186:189], v[194:197], v[50:53]
	v_mfma_f32_16x16x32_bf16 v[38:41], v[178:181], v[208:211], v[38:41]
	v_mfma_f32_16x16x32_bf16 v[34:37], v[186:189], v[208:211], v[34:37]
	v_mfma_f32_16x16x32_bf16 v[22:25], v[178:181], v[216:219], v[22:25]
	v_mfma_f32_16x16x32_bf16 v[18:21], v[186:189], v[216:219], v[18:21]
	v_mfma_f32_16x16x32_bf16 v[6:9], v[178:181], v[224:227], v[6:9]
	v_mfma_f32_16x16x32_bf16 v[2:5], v[186:189], v[224:227], v[2:5]
	s_add_i32 s39, s39, 2
	s_add_u32 s10, s10, 0x100
	s_addc_u32 s11, s11, 0
	s_cmp_gt_u32 s39, 29
	s_setprio 0
	s_barrier
	s_cbranch_scc0 .LBB0_1349
	s_cmpk_lt_u32 s20, 0x100
	s_cbranch_scc0 .LBB0_1352
	s_barrier
